# off-diagonal stick-breaking body + first K-loop iteration peeled in 8 GEMM phases (first MFMA per accumulator takes C=0; the 128 v_mov accumulator clears per unit removed)
# baseline (speedup 1.0000x reference)
;     __device__ __forceinline__ bool next(int i, Unit& u) const { if (!S.next(i, u)) return false; if (u.pn >= 4) u.pn += 2; return true; }
; #define PG8_STAGE(bufoff, gbase, voff) do { _Pragma("unroll") for (int _i = 0; _i < 2; ++_i) \
;         __builtin_amdgcn_global_load_lds((const unsigned*)((const char*)(gbase) + (voff)[_i]), (PG8_LAS unsigned*)(lds + (bufoff) + ldsw + _i * 8192), 16, 0, 0); } while (0)
; #define PG8_LDA(dst, b, h) do { _Pragma("unroll") for (int m = 0; m < 4; ++m) _Pragma("unroll") for (int k = 0; k < 2; ++k) dst[m][k] = *(const PG8_LAS bf16x8*)(lds + PG8_SA(b, h) + aoff + m * 2048 + k * 1024); } while (0)
; #define PG8_LDB(dst, b, h) do { _Pragma("unroll") for (int n = 0; n < 2; ++n) _Pragma("unroll") for (int k = 0; k < 2; ++k) dst[n][k] = *(const PG8_LAS bf16x8*)(lds + PG8_SB(b, h) + boff + n * 2048 + k * 1024); } while (0)
; template <class Epi, class Sched, bool ALIGN_EPI = false, bool SP2 = false>
; __device__ __forceinline__ void gemm_phase(PG8_LAS unsigned char* lds, const Gemm g, const Sched& S, const Epi& E) {
;     ...
;         const bool has_next = S.next(ui + 1, nxt);
;         if constexpr (Epi::LDS_PF) { if (has_next) E.prefetch(nxt, lds + STAGE_BYTES + ((ui + 1) % 3) * 4096, wid, lane); }
;         const char* nA = has_next ? (const char*)g.A + (size_t)nxt.pm * tstepA : cA; const char* nB = has_next ? (const char*)g.Bt + (size_t)nxt.pn * tstepB : cB;
;         for (int t = 0; t < nt; t += 2) {
;             const bool last = (t == nt - 2);
;             const char* a1 = cA + (size_t)(t + 1) * kstep;
;             const char* a2 = last ? nA : cA + (size_t)(t + 2) * kstep; const char* b2 = last ? nB : cB + (size_t)(t + 2) * kstep;
;             const char* a3 = a2 + kstep; const char* b3 = b2 + kstep;
;             if (last && has_next) S.a_ready(nxt);
;             if constexpr (SP2) {
;             PG8_LDB(B0, 0, 0); PG8_LDB(B1, 0, 1); PG8_SCHED; PG8_LDA(At, 0, 0); PG8_STAGE(PG8_SA(1, 1), a1 + hstepA, voffA);
;             PG8_WAIT_V(8); PG8_WAIT_L(0); PG8_BAR; PG8_MMA(0, 0, At, B0); PG8_MMA(0, 1, At, B1); PG8_BAR; PG8_SCHED;
;             PG8_LDA(At, 0, 1); PG8_STAGE(PG8_SB(0, 0), b2, voffB); PG8_STAGE(PG8_SB(0, 1), b2 + hstepB, voffB); PG8_STAGE(PG8_SA(0, 0), a2, voffA);
;             PG8_WAIT_V(8); PG8_WAIT_L(0); PG8_BAR; PG8_MMA(1, 0, At, B0); PG8_MMA(1, 1, At, B1); PG8_BAR; PG8_SCHED;
.LBB0_144:
	s_ashr_i32 s21, s20, 31
	s_lshl_b64 s[0:1], s[20:21], 19
	v_readlane_b32 s22, v253, 23
	v_readlane_b32 s23, v253, 24
	s_add_u32 s22, s22, s0
	s_addc_u32 s23, s23, s1
	s_and_b64 s[0:1], s[6:7], exec
	s_cselect_b32 s5, s23, s29
	s_cselect_b32 s21, s22, s28
	s_ashr_i32 s19, s18, 31
	s_lshl_b64 s[0:1], s[18:19], 19
	s_add_u32 s24, s8, s0
	s_addc_u32 s25, s9, s1
	s_and_b64 s[0:1], s[6:7], exec
	s_cselect_b32 s19, s25, s31
	s_cselect_b32 s48, s24, s30
	s_add_u32 s28, s28, 0x40080
	s_addc_u32 s29, s29, 0
	s_add_u32 s49, s30, 0x100
	s_addc_u32 s50, s31, 0
	s_mov_b32 s51, -2
	ds_read_b128 v[146:149], v151
	ds_read_b128 v[156:159], v151 offset:1024
	ds_read_b128 v[160:163], v151 offset:2048
	ds_read_b128 v[164:167], v151 offset:3072
	ds_read_b128 v[168:171], v152
	ds_read_b128 v[172:175], v152 offset:1024
	ds_read_b128 v[176:179], v152 offset:2048
	ds_read_b128 v[180:183], v152 offset:3072
	s_add_u32 s0, s28, 0xfffc0080
	s_addc_u32 s1, s29, -1
	s_cmp_eq_u32 s51, 12
	s_cselect_b32 s35, s5, s1
	s_cselect_b32 s34, s21, s0
	s_cselect_b32 s31, s19, s50
	s_cselect_b32 s30, s48, s49
	v_lshl_add_u64 v[216:217], s[28:29], 0, v[138:139]
	s_add_i32 m0, s27, 0xc000
	ds_read_b128 v[184:187], v153
	ds_read_b128 v[188:191], v153 offset:1024
	ds_read_b128 v[192:195], v153 offset:2048
	ds_read_b128 v[196:199], v153 offset:3072
	ds_read_b128 v[200:203], v153 offset:4096
	ds_read_b128 v[204:207], v153 offset:5120
	ds_read_b128 v[208:211], v153 offset:6144
	ds_read_b128 v[212:215], v153 offset:7168
	global_load_lds_dwordx4 v[216:217], off
	v_lshl_add_u64 v[216:217], s[28:29], 0, v[140:141]
	s_add_i32 m0, s27, 0xe000
	s_nop 0
	global_load_lds_dwordx4 v[216:217], off
	s_waitcnt vmcnt(8)
	s_waitcnt lgkmcnt(0)
	s_barrier
	s_setprio 1
	s_waitcnt lgkmcnt(0)
	v_mfma_f32_16x16x32_bf16 v[126:129], v[146:149], v[184:187], 0
	v_mfma_f32_16x16x32_bf16 v[122:125], v[160:163], v[184:187], 0
	v_mfma_f32_16x16x32_bf16 v[118:121], v[146:149], v[192:195], 0
	v_mfma_f32_16x16x32_bf16 v[110:113], v[160:163], v[192:195], 0
	v_mfma_f32_16x16x32_bf16 v[102:105], v[146:149], v[200:203], 0
	v_mfma_f32_16x16x32_bf16 v[94:97], v[160:163], v[200:203], 0
	v_mfma_f32_16x16x32_bf16 v[86:89], v[146:149], v[208:211], 0
	v_mfma_f32_16x16x32_bf16 v[78:81], v[160:163], v[208:211], 0
	v_mfma_f32_16x16x32_bf16 v[126:129], v[156:159], v[188:191], v[126:129]
	v_mfma_f32_16x16x32_bf16 v[122:125], v[164:167], v[188:191], v[122:125]
	v_mfma_f32_16x16x32_bf16 v[118:121], v[156:159], v[196:199], v[118:121]
	v_mfma_f32_16x16x32_bf16 v[110:113], v[164:167], v[196:199], v[110:113]
	v_mfma_f32_16x16x32_bf16 v[102:105], v[156:159], v[204:207], v[102:105]
	v_mfma_f32_16x16x32_bf16 v[94:97], v[164:167], v[204:207], v[94:97]
	v_mfma_f32_16x16x32_bf16 v[86:89], v[156:159], v[212:215], v[86:89]
	v_mfma_f32_16x16x32_bf16 v[78:81], v[164:167], v[212:215], v[78:81]
	s_setprio 0
	s_setprio 1
	v_mfma_f32_16x16x32_bf16 v[114:117], v[168:171], v[184:187], 0
	v_mfma_f32_16x16x32_bf16 v[106:109], v[176:179], v[184:187], 0
	v_mfma_f32_16x16x32_bf16 v[98:101], v[168:171], v[192:195], 0
	v_mfma_f32_16x16x32_bf16 v[90:93], v[176:179], v[192:195], 0
	v_mfma_f32_16x16x32_bf16 v[82:85], v[168:171], v[200:203], 0
	v_mfma_f32_16x16x32_bf16 v[74:77], v[176:179], v[200:203], 0
	v_mfma_f32_16x16x32_bf16 v[70:73], v[168:171], v[208:211], 0
	v_mfma_f32_16x16x32_bf16 v[66:69], v[176:179], v[208:211], 0
	v_mfma_f32_16x16x32_bf16 v[114:117], v[172:175], v[188:191], v[114:117]
	v_mfma_f32_16x16x32_bf16 v[106:109], v[180:183], v[188:191], v[106:109]
	v_mfma_f32_16x16x32_bf16 v[98:101], v[172:175], v[196:199], v[98:101]
	v_mfma_f32_16x16x32_bf16 v[90:93], v[180:183], v[196:199], v[90:93]
	v_mfma_f32_16x16x32_bf16 v[82:85], v[172:175], v[204:207], v[82:85]
	v_mfma_f32_16x16x32_bf16 v[74:77], v[180:183], v[204:207], v[74:77]
	v_mfma_f32_16x16x32_bf16 v[70:73], v[172:175], v[212:215], v[70:73]
	v_mfma_f32_16x16x32_bf16 v[66:69], v[180:183], v[212:215], v[66:69]
	s_setprio 0
	s_barrier
	s_add_i32 s0, s43, s3
	v_lshl_add_u64 v[216:217], s[30:31], 0, v[134:135]
	s_mov_b32 m0, s0
	ds_read_b128 v[184:187], v153 offset:16384
	ds_read_b128 v[188:191], v153 offset:17408
	ds_read_b128 v[192:195], v153 offset:18432
	ds_read_b128 v[196:199], v153 offset:19456
	ds_read_b128 v[200:203], v153 offset:20480
	ds_read_b128 v[204:207], v153 offset:21504
	ds_read_b128 v[208:211], v153 offset:22528
	ds_read_b128 v[212:215], v153 offset:23552
	global_load_lds_dwordx4 v[216:217], off
	s_add_i32 m0, s0, 0x2000
	s_add_u32 s0, s30, 0x40000
	v_lshl_add_u64 v[218:219], s[30:31], 0, v[130:131]
	s_addc_u32 s1, s31, 0
	s_add_i32 s2, s44, s3
	global_load_lds_dwordx4 v[218:219], off
	v_lshl_add_u64 v[220:221], s[0:1], 0, v[134:135]
	s_mov_b32 m0, s2
	v_lshl_add_u64 v[222:223], s[34:35], 0, v[132:133]
	global_load_lds_dwordx4 v[220:221], off
	v_lshl_add_u64 v[220:221], s[0:1], 0, v[130:131]
	s_add_i32 m0, s2, 0x2000
	s_nop 0
	global_load_lds_dwordx4 v[220:221], off
	v_lshl_add_u64 v[220:221], s[34:35], 0, v[136:137]
	s_mov_b32 m0, s27
	s_nop 0
	global_load_lds_dwordx4 v[220:221], off
	s_mov_b32 m0, s36
	s_nop 0
	global_load_lds_dwordx4 v[222:223], off
	s_waitcnt vmcnt(8)
	s_waitcnt lgkmcnt(0)
	s_barrier
; #define PG8_STAGE(bufoff, gbase, voff) do { _Pragma("unroll") for (int _i = 0; _i < 2; ++_i) \
;         __builtin_amdgcn_global_load_lds((const unsigned*)((const char*)(gbase) + (voff)[_i]), (PG8_LAS unsigned*)(lds + (bufoff) + ldsw + _i * 8192), 16, 0, 0); } while (0)
; #define PG8_LDA(dst, b, h) do { _Pragma("unroll") for (int m = 0; m < 4; ++m) _Pragma("unroll") for (int k = 0; k < 2; ++k) dst[m][k] = *(const PG8_LAS bf16x8*)(lds + PG8_SA(b, h) + aoff + m * 2048 + k * 1024); } while (0)
; #define PG8_LDB(dst, b, h) do { _Pragma("unroll") for (int n = 0; n < 2; ++n) _Pragma("unroll") for (int k = 0; k < 2; ++k) dst[n][k] = *(const PG8_LAS bf16x8*)(lds + PG8_SB(b, h) + boff + n * 2048 + k * 1024); } while (0)
; #define PG8_MMA(ai, bj, At, Bt) do { __builtin_amdgcn_s_setprio(1); _Pragma("unroll") for (int m = 0; m < 4; ++m) _Pragma("unroll") for (int n = 0; n < 2; ++n) _Pragma("unroll") for (int k = 0; k < 2; ++k) \
;         acc[ai][bj][m][n] = __builtin_amdgcn_mfma_f32_16x16x32_bf16(Bt[n][k], At[m][k], acc[ai][bj][m][n], 0, 0, 0); __builtin_amdgcn_s_setprio(0); } while (0)
; #define PG8_WAIT_V(n) asm volatile("s_waitcnt vmcnt(" #n ")" ::: "memory")
; #define PG8_WAIT_L(n) asm volatile("s_waitcnt lgkmcnt(" #n ")" ::: "memory")
; #define PG8_BAR __builtin_amdgcn_s_barrier()
; #define PG8_SCHED __builtin_amdgcn_sched_barrier(0)
; template <class Epi, class Sched, bool ALIGN_EPI = false, bool SP2 = false>
; __device__ __forceinline__ void gemm_phase(PG8_LAS unsigned char* lds, const Gemm g, const Sched& S, const Epi& E) {
;     ...
;             PG8_WAIT_V(8); PG8_WAIT_L(0); PG8_BAR; PG8_MMA(1, 0, At, B0); PG8_MMA(1, 1, At, B1); PG8_BAR; PG8_SCHED;
;             PG8_LDB(B0, 1, 0); PG8_LDB(B1, 1, 1); PG8_SCHED; PG8_LDA(At, 1, 0); PG8_STAGE(PG8_SA(0, 1), a2 + hstepA, voffA);
;             PG8_WAIT_V(8); PG8_WAIT_L(0); PG8_BAR; PG8_MMA(0, 0, At, B0); PG8_MMA(0, 1, At, B1); PG8_BAR; PG8_SCHED;
	s_setprio 1
	s_waitcnt lgkmcnt(0)
	v_mfma_f32_16x16x32_bf16 v[62:65], v[146:149], v[184:187], 0
	v_mfma_f32_16x16x32_bf16 v[58:61], v[160:163], v[184:187], 0
	v_mfma_f32_16x16x32_bf16 v[54:57], v[146:149], v[192:195], 0
	v_mfma_f32_16x16x32_bf16 v[46:49], v[160:163], v[192:195], 0
	v_mfma_f32_16x16x32_bf16 v[38:41], v[146:149], v[200:203], 0
	v_mfma_f32_16x16x32_bf16 v[30:33], v[160:163], v[200:203], 0
	v_mfma_f32_16x16x32_bf16 v[22:25], v[146:149], v[208:211], 0
	v_mfma_f32_16x16x32_bf16 v[14:17], v[160:163], v[208:211], 0
	v_mfma_f32_16x16x32_bf16 v[62:65], v[156:159], v[188:191], v[62:65]
	v_mfma_f32_16x16x32_bf16 v[58:61], v[164:167], v[188:191], v[58:61]
	v_mfma_f32_16x16x32_bf16 v[54:57], v[156:159], v[196:199], v[54:57]
	v_mfma_f32_16x16x32_bf16 v[46:49], v[164:167], v[196:199], v[46:49]
	v_mfma_f32_16x16x32_bf16 v[38:41], v[156:159], v[204:207], v[38:41]
	v_mfma_f32_16x16x32_bf16 v[30:33], v[164:167], v[204:207], v[30:33]
	v_mfma_f32_16x16x32_bf16 v[22:25], v[156:159], v[212:215], v[22:25]
	v_mfma_f32_16x16x32_bf16 v[14:17], v[164:167], v[212:215], v[14:17]
	s_setprio 0
	s_setprio 1
	v_mfma_f32_16x16x32_bf16 v[50:53], v[168:171], v[184:187], 0
	v_mfma_f32_16x16x32_bf16 v[42:45], v[176:179], v[184:187], 0
	v_mfma_f32_16x16x32_bf16 v[34:37], v[168:171], v[192:195], 0
	v_mfma_f32_16x16x32_bf16 v[26:29], v[176:179], v[192:195], 0
	v_mfma_f32_16x16x32_bf16 v[18:21], v[168:171], v[200:203], 0
	v_mfma_f32_16x16x32_bf16 v[10:13], v[176:179], v[200:203], 0
	v_mfma_f32_16x16x32_bf16 v[6:9], v[168:171], v[208:211], 0
	v_mfma_f32_16x16x32_bf16 v[2:5], v[176:179], v[208:211], 0
	v_mfma_f32_16x16x32_bf16 v[50:53], v[172:175], v[188:191], v[50:53]
	v_mfma_f32_16x16x32_bf16 v[42:45], v[180:183], v[188:191], v[42:45]
	v_mfma_f32_16x16x32_bf16 v[34:37], v[172:175], v[196:199], v[34:37]
	v_mfma_f32_16x16x32_bf16 v[26:29], v[180:183], v[196:199], v[26:29]
	v_mfma_f32_16x16x32_bf16 v[18:21], v[172:175], v[204:207], v[18:21]
	v_mfma_f32_16x16x32_bf16 v[10:13], v[180:183], v[204:207], v[10:13]
	v_mfma_f32_16x16x32_bf16 v[6:9], v[172:175], v[212:215], v[6:9]
	v_mfma_f32_16x16x32_bf16 v[2:5], v[180:183], v[212:215], v[2:5]
	s_setprio 0
	s_barrier
	ds_read_b128 v[146:149], v154
	ds_read_b128 v[156:159], v154 offset:1024
	ds_read_b128 v[160:163], v154 offset:2048
	ds_read_b128 v[164:167], v154 offset:3072
	ds_read_b128 v[168:171], v155
	ds_read_b128 v[172:175], v155 offset:1024
	ds_read_b128 v[176:179], v155 offset:2048
	ds_read_b128 v[180:183], v155 offset:3072
	s_add_u32 s0, s34, 0x40000
	s_addc_u32 s1, s35, 0
	s_mov_b32 m0, s37
	v_lshl_add_u64 v[224:225], s[0:1], 0, v[136:137]
	ds_read_b128 v[184:187], v153 offset:32768
	ds_read_b128 v[188:191], v153 offset:33792
	ds_read_b128 v[192:195], v153 offset:34816
	ds_read_b128 v[196:199], v153 offset:35840
	ds_read_b128 v[200:203], v153 offset:36864
	ds_read_b128 v[204:207], v153 offset:37888
	ds_read_b128 v[208:211], v153 offset:38912
	ds_read_b128 v[212:215], v153 offset:39936
	global_load_lds_dwordx4 v[224:225], off
	v_lshl_add_u64 v[224:225], s[0:1], 0, v[132:133]
	s_mov_b32 m0, s38
	s_nop 0
	global_load_lds_dwordx4 v[224:225], off
	s_waitcnt vmcnt(8)
	s_waitcnt lgkmcnt(0)
	s_barrier
	s_setprio 1
	s_waitcnt lgkmcnt(0)
	v_mfma_f32_16x16x32_bf16 v[126:129], v[146:149], v[184:187], v[126:129]
	v_mfma_f32_16x16x32_bf16 v[122:125], v[160:163], v[184:187], v[122:125]
	v_mfma_f32_16x16x32_bf16 v[118:121], v[146:149], v[192:195], v[118:121]
	v_mfma_f32_16x16x32_bf16 v[110:113], v[160:163], v[192:195], v[110:113]
	v_mfma_f32_16x16x32_bf16 v[102:105], v[146:149], v[200:203], v[102:105]
	v_mfma_f32_16x16x32_bf16 v[94:97], v[160:163], v[200:203], v[94:97]
	v_mfma_f32_16x16x32_bf16 v[86:89], v[146:149], v[208:211], v[86:89]
	v_mfma_f32_16x16x32_bf16 v[78:81], v[160:163], v[208:211], v[78:81]
	v_mfma_f32_16x16x32_bf16 v[126:129], v[156:159], v[188:191], v[126:129]
	v_mfma_f32_16x16x32_bf16 v[122:125], v[164:167], v[188:191], v[122:125]
	v_mfma_f32_16x16x32_bf16 v[118:121], v[156:159], v[196:199], v[118:121]
	v_mfma_f32_16x16x32_bf16 v[110:113], v[164:167], v[196:199], v[110:113]
	v_mfma_f32_16x16x32_bf16 v[102:105], v[156:159], v[204:207], v[102:105]
	v_mfma_f32_16x16x32_bf16 v[94:97], v[164:167], v[204:207], v[94:97]
	v_mfma_f32_16x16x32_bf16 v[86:89], v[156:159], v[212:215], v[86:89]
	v_mfma_f32_16x16x32_bf16 v[78:81], v[164:167], v[212:215], v[78:81]
	s_setprio 0
	s_setprio 1
	v_mfma_f32_16x16x32_bf16 v[114:117], v[168:171], v[184:187], v[114:117]
	v_mfma_f32_16x16x32_bf16 v[106:109], v[176:179], v[184:187], v[106:109]
	v_mfma_f32_16x16x32_bf16 v[98:101], v[168:171], v[192:195], v[98:101]
	v_mfma_f32_16x16x32_bf16 v[90:93], v[176:179], v[192:195], v[90:93]
	v_mfma_f32_16x16x32_bf16 v[82:85], v[168:171], v[200:203], v[82:85]
	v_mfma_f32_16x16x32_bf16 v[74:77], v[176:179], v[200:203], v[74:77]
	v_mfma_f32_16x16x32_bf16 v[70:73], v[168:171], v[208:211], v[70:73]
	v_mfma_f32_16x16x32_bf16 v[66:69], v[176:179], v[208:211], v[66:69]
	v_mfma_f32_16x16x32_bf16 v[114:117], v[172:175], v[188:191], v[114:117]
	v_mfma_f32_16x16x32_bf16 v[106:109], v[180:183], v[188:191], v[106:109]
	v_mfma_f32_16x16x32_bf16 v[98:101], v[172:175], v[196:199], v[98:101]
	v_mfma_f32_16x16x32_bf16 v[90:93], v[180:183], v[196:199], v[90:93]
	v_mfma_f32_16x16x32_bf16 v[82:85], v[172:175], v[204:207], v[82:85]
	v_mfma_f32_16x16x32_bf16 v[74:77], v[180:183], v[204:207], v[74:77]
	v_mfma_f32_16x16x32_bf16 v[70:73], v[172:175], v[212:215], v[70:73]
	v_mfma_f32_16x16x32_bf16 v[66:69], v[180:183], v[212:215], v[66:69]
	s_setprio 0
	s_barrier
; #define PG8_STAGE(bufoff, gbase, voff) do { _Pragma("unroll") for (int _i = 0; _i < 2; ++_i) \
;         __builtin_amdgcn_global_load_lds((const unsigned*)((const char*)(gbase) + (voff)[_i]), (PG8_LAS unsigned*)(lds + (bufoff) + ldsw + _i * 8192), 16, 0, 0); } while (0)
; #define PG8_LDA(dst, b, h) do { _Pragma("unroll") for (int m = 0; m < 4; ++m) _Pragma("unroll") for (int k = 0; k < 2; ++k) dst[m][k] = *(const PG8_LAS bf16x8*)(lds + PG8_SA(b, h) + aoff + m * 2048 + k * 1024); } while (0)
; #define PG8_MMA(ai, bj, At, Bt) do { __builtin_amdgcn_s_setprio(1); _Pragma("unroll") for (int m = 0; m < 4; ++m) _Pragma("unroll") for (int n = 0; n < 2; ++n) _Pragma("unroll") for (int k = 0; k < 2; ++k) \
;         acc[ai][bj][m][n] = __builtin_amdgcn_mfma_f32_16x16x32_bf16(Bt[n][k], At[m][k], acc[ai][bj][m][n], 0, 0, 0); __builtin_amdgcn_s_setprio(0); } while (0)
; #define PG8_WAIT_V(n) asm volatile("s_waitcnt vmcnt(" #n ")" ::: "memory")
; #define PG8_WAIT_L(n) asm volatile("s_waitcnt lgkmcnt(" #n ")" ::: "memory")
; #define PG8_BAR __builtin_amdgcn_s_barrier()
; #define PG8_SCHED __builtin_amdgcn_sched_barrier(0)
; template <class Epi, class Sched, bool ALIGN_EPI = false, bool SP2 = false>
; __device__ __forceinline__ void gemm_phase(PG8_LAS unsigned char* lds, const Gemm g, const Sched& S, const Epi& E) {
;     ...
;         for (int t = 0; t < nt; t += 2) {
;             const bool last = (t == nt - 2);
;     ...
;             PG8_LDA(At, 1, 1); PG8_STAGE(PG8_SB(1, 0), b3, voffB); PG8_STAGE(PG8_SB(1, 1), b3 + hstepB, voffB); PG8_STAGE(PG8_SA(1, 0), a3, voffA);
;             PG8_WAIT_V(8); PG8_WAIT_L(0); PG8_BAR; PG8_MMA(1, 0, At, B0); PG8_MMA(1, 1, At, B1); PG8_BAR; PG8_SCHED;
	s_add_i32 s0, s45, s3
	v_lshl_add_u64 v[216:217], v[216:217], 0, s[10:11]
	s_mov_b32 m0, s0
	ds_read_b128 v[184:187], v153 offset:49152
	ds_read_b128 v[188:191], v153 offset:50176
	ds_read_b128 v[192:195], v153 offset:51200
	ds_read_b128 v[196:199], v153 offset:52224
	ds_read_b128 v[200:203], v153 offset:53248
	ds_read_b128 v[204:207], v153 offset:54272
	ds_read_b128 v[208:211], v153 offset:55296
	ds_read_b128 v[212:215], v153 offset:56320
	global_load_lds_dwordx4 v[216:217], off
	s_add_i32 m0, s0, 0x2000
	s_add_u32 s0, s30, 0x40080
	v_lshl_add_u64 v[216:217], v[218:219], 0, s[10:11]
	s_addc_u32 s1, s31, 0
	s_add_i32 s2, s46, s3
	global_load_lds_dwordx4 v[216:217], off
	v_lshl_add_u64 v[216:217], s[0:1], 0, v[134:135]
	s_mov_b32 m0, s2
	s_nop 0
	global_load_lds_dwordx4 v[216:217], off
	v_lshl_add_u64 v[216:217], s[0:1], 0, v[130:131]
	s_add_i32 m0, s2, 0x2000
	s_nop 0
	global_load_lds_dwordx4 v[216:217], off
	v_lshl_add_u64 v[216:217], v[220:221], 0, s[10:11]
	s_mov_b32 m0, s39
	s_nop 0
	global_load_lds_dwordx4 v[216:217], off
	v_lshl_add_u64 v[216:217], v[222:223], 0, s[10:11]
	s_mov_b32 m0, s40
	s_nop 0
	global_load_lds_dwordx4 v[216:217], off
	s_waitcnt vmcnt(8)
	s_waitcnt lgkmcnt(0)
	s_barrier
	s_setprio 1
	s_waitcnt lgkmcnt(0)
	v_mfma_f32_16x16x32_bf16 v[62:65], v[146:149], v[184:187], v[62:65]
	v_mfma_f32_16x16x32_bf16 v[58:61], v[160:163], v[184:187], v[58:61]
	v_mfma_f32_16x16x32_bf16 v[54:57], v[146:149], v[192:195], v[54:57]
	v_mfma_f32_16x16x32_bf16 v[46:49], v[160:163], v[192:195], v[46:49]
	v_mfma_f32_16x16x32_bf16 v[38:41], v[146:149], v[200:203], v[38:41]
	v_mfma_f32_16x16x32_bf16 v[30:33], v[160:163], v[200:203], v[30:33]
	v_mfma_f32_16x16x32_bf16 v[22:25], v[146:149], v[208:211], v[22:25]
	v_mfma_f32_16x16x32_bf16 v[14:17], v[160:163], v[208:211], v[14:17]
	v_mfma_f32_16x16x32_bf16 v[62:65], v[156:159], v[188:191], v[62:65]
	v_mfma_f32_16x16x32_bf16 v[58:61], v[164:167], v[188:191], v[58:61]
	v_mfma_f32_16x16x32_bf16 v[54:57], v[156:159], v[196:199], v[54:57]
	v_mfma_f32_16x16x32_bf16 v[46:49], v[164:167], v[196:199], v[46:49]
	v_mfma_f32_16x16x32_bf16 v[38:41], v[156:159], v[204:207], v[38:41]
	v_mfma_f32_16x16x32_bf16 v[30:33], v[164:167], v[204:207], v[30:33]
	v_mfma_f32_16x16x32_bf16 v[22:25], v[156:159], v[212:215], v[22:25]
	v_mfma_f32_16x16x32_bf16 v[14:17], v[164:167], v[212:215], v[14:17]
	s_setprio 0
	s_setprio 1
	v_mfma_f32_16x16x32_bf16 v[50:53], v[168:171], v[184:187], v[50:53]
	v_mfma_f32_16x16x32_bf16 v[42:45], v[176:179], v[184:187], v[42:45]
	v_mfma_f32_16x16x32_bf16 v[34:37], v[168:171], v[192:195], v[34:37]
	v_mfma_f32_16x16x32_bf16 v[26:29], v[176:179], v[192:195], v[26:29]
	v_mfma_f32_16x16x32_bf16 v[18:21], v[168:171], v[200:203], v[18:21]
	v_mfma_f32_16x16x32_bf16 v[10:13], v[176:179], v[200:203], v[10:13]
	v_mfma_f32_16x16x32_bf16 v[6:9], v[168:171], v[208:211], v[6:9]
	v_mfma_f32_16x16x32_bf16 v[2:5], v[176:179], v[208:211], v[2:5]
	v_mfma_f32_16x16x32_bf16 v[50:53], v[172:175], v[188:191], v[50:53]
	v_mfma_f32_16x16x32_bf16 v[42:45], v[180:183], v[188:191], v[42:45]
	v_mfma_f32_16x16x32_bf16 v[34:37], v[172:175], v[196:199], v[34:37]
	v_mfma_f32_16x16x32_bf16 v[26:29], v[180:183], v[196:199], v[26:29]
	v_mfma_f32_16x16x32_bf16 v[18:21], v[172:175], v[204:207], v[18:21]
	v_mfma_f32_16x16x32_bf16 v[10:13], v[180:183], v[204:207], v[10:13]
	v_mfma_f32_16x16x32_bf16 v[6:9], v[172:175], v[212:215], v[6:9]
	v_mfma_f32_16x16x32_bf16 v[2:5], v[180:183], v[212:215], v[2:5]
	s_setprio 0
	s_barrier
	s_add_i32 s51, s51, 2
	s_add_u32 s28, s28, 0x100
	s_addc_u32 s29, s29, 0
	s_add_u32 s49, s49, 0x100
	s_addc_u32 s50, s50, 0
	s_cmp_gt_u32 s51, 13

;     __device__ __forceinline__ bool next(int i, Unit& u) const { if (!S.next(i, u)) return false; if (u.pn >= 4) u.pn += 2; return true; }
; #define PG8_STAGE(bufoff, gbase, voff) do { _Pragma("unroll") for (int _i = 0; _i < 2; ++_i) \
;         __builtin_amdgcn_global_load_lds((const unsigned*)((const char*)(gbase) + (voff)[_i]), (PG8_LAS unsigned*)(lds + (bufoff) + ldsw + _i * 8192), 16, 0, 0); } while (0)
; #define PG8_LDA(dst, b, h) do { _Pragma("unroll") for (int m = 0; m < 4; ++m) _Pragma("unroll") for (int k = 0; k < 2; ++k) dst[m][k] = *(const PG8_LAS bf16x8*)(lds + PG8_SA(b, h) + aoff + m * 2048 + k * 1024); } while (0)
; #define PG8_LDB(dst, b, h) do { _Pragma("unroll") for (int n = 0; n < 2; ++n) _Pragma("unroll") for (int k = 0; k < 2; ++k) dst[n][k] = *(const PG8_LAS bf16x8*)(lds + PG8_SB(b, h) + boff + n * 2048 + k * 1024); } while (0)
; template <class Epi, class Sched, bool ALIGN_EPI = false, bool SP2 = false>
; __device__ __forceinline__ void gemm_phase(PG8_LAS unsigned char* lds, const Gemm g, const Sched& S, const Epi& E) {
;     ...
;         const bool has_next = S.next(ui + 1, nxt);
;         if constexpr (Epi::LDS_PF) { if (has_next) E.prefetch(nxt, lds + STAGE_BYTES + ((ui + 1) % 3) * 4096, wid, lane); }
;         const char* nA = has_next ? (const char*)g.A + (size_t)nxt.pm * tstepA : cA; const char* nB = has_next ? (const char*)g.Bt + (size_t)nxt.pn * tstepB : cB;
;         for (int t = 0; t < nt; t += 2) {
;             const bool last = (t == nt - 2);
;             const char* a1 = cA + (size_t)(t + 1) * kstep;
;             const char* a2 = last ? nA : cA + (size_t)(t + 2) * kstep; const char* b2 = last ? nB : cB + (size_t)(t + 2) * kstep;
;             const char* a3 = a2 + kstep; const char* b3 = b2 + kstep;
;             if (last && has_next) S.a_ready(nxt);
;             if constexpr (SP2) {
;             PG8_LDB(B0, 0, 0); PG8_LDB(B1, 0, 1); PG8_SCHED; PG8_LDA(At, 0, 0); PG8_STAGE(PG8_SA(1, 1), a1 + hstepA, voffA);
;             PG8_WAIT_V(8); PG8_WAIT_L(0); PG8_BAR; PG8_MMA(0, 0, At, B0); PG8_MMA(0, 1, At, B1); PG8_BAR; PG8_SCHED;
;             PG8_LDA(At, 0, 1); PG8_STAGE(PG8_SB(0, 0), b2, voffB); PG8_STAGE(PG8_SB(0, 1), b2 + hstepB, voffB); PG8_STAGE(PG8_SA(0, 0), a2, voffA);
;             PG8_WAIT_V(8); PG8_WAIT_L(0); PG8_BAR; PG8_MMA(1, 0, At, B0); PG8_MMA(1, 1, At, B1); PG8_BAR; PG8_SCHED;
.LBB0_610:
	s_ashr_i32 s21, s20, 31
	s_lshl_b64 s[0:1], s[20:21], 19
	v_readlane_b32 s22, v253, 29
	v_readlane_b32 s23, v253, 30
	s_add_u32 s22, s22, s0
	s_addc_u32 s23, s23, s1
	s_and_b64 s[0:1], s[6:7], exec
	s_cselect_b32 s5, s23, s29
	s_cselect_b32 s21, s22, s28
	s_ashr_i32 s19, s18, 31
	s_lshl_b64 s[0:1], s[18:19], 19
	v_readlane_b32 s24, v253, 16
	v_readlane_b32 s25, v253, 17
	s_add_u32 s24, s24, s0
	s_addc_u32 s25, s25, s1
	s_and_b64 s[0:1], s[6:7], exec
	s_cselect_b32 s19, s25, s31
	s_cselect_b32 s49, s24, s30
	s_add_u32 s28, s28, 0x40080
	s_addc_u32 s29, s29, 0
	s_add_u32 s50, s30, 0x100
	s_addc_u32 s51, s31, 0
	s_mov_b32 s67, -2
	s_waitcnt vmcnt(0)
	ds_read_b128 v[130:133], v161
	ds_read_b128 v[134:137], v161 offset:1024
	ds_read_b128 v[154:157], v161 offset:2048
	ds_read_b128 v[166:169], v161 offset:3072
	ds_read_b128 v[170:173], v162
	ds_read_b128 v[174:177], v162 offset:1024
	ds_read_b128 v[178:181], v162 offset:2048
	ds_read_b128 v[182:185], v162 offset:3072
	s_add_u32 s0, s28, 0xfffc0080
	s_addc_u32 s1, s29, -1
	s_cmp_eq_u32 s67, 12
	s_cselect_b32 s35, s5, s1
	s_cselect_b32 s34, s21, s0
	s_cselect_b32 s31, s19, s51
	s_cselect_b32 s30, s49, s50
	v_lshl_add_u64 v[158:159], s[28:29], 0, v[146:147]
	s_add_i32 m0, s27, 0xc000
	ds_read_b128 v[186:189], v163
	ds_read_b128 v[190:193], v163 offset:1024
	ds_read_b128 v[194:197], v163 offset:2048
	ds_read_b128 v[198:201], v163 offset:3072
	ds_read_b128 v[202:205], v163 offset:4096
	ds_read_b128 v[206:209], v163 offset:5120
	ds_read_b128 v[210:213], v163 offset:6144
	ds_read_b128 v[214:217], v163 offset:7168
	global_load_lds_dwordx4 v[158:159], off
	v_lshl_add_u64 v[158:159], s[28:29], 0, v[148:149]
	s_add_i32 m0, s27, 0xe000
	s_nop 0
	global_load_lds_dwordx4 v[158:159], off
	s_waitcnt vmcnt(8)
	s_waitcnt lgkmcnt(0)
	s_barrier
	s_setprio 1
	s_waitcnt lgkmcnt(0)
	v_mfma_f32_16x16x32_bf16 v[126:129], v[130:133], v[186:189], 0
	v_mfma_f32_16x16x32_bf16 v[122:125], v[154:157], v[186:189], 0
	v_mfma_f32_16x16x32_bf16 v[118:121], v[130:133], v[194:197], 0
	v_mfma_f32_16x16x32_bf16 v[114:117], v[154:157], v[194:197], 0
	v_mfma_f32_16x16x32_bf16 v[110:113], v[130:133], v[202:205], 0
	v_mfma_f32_16x16x32_bf16 v[102:105], v[154:157], v[202:205], 0
	v_mfma_f32_16x16x32_bf16 v[82:85], v[130:133], v[210:213], 0
	v_mfma_f32_16x16x32_bf16 v[74:77], v[154:157], v[210:213], 0
	v_mfma_f32_16x16x32_bf16 v[126:129], v[134:137], v[190:193], v[126:129]
	v_mfma_f32_16x16x32_bf16 v[122:125], v[166:169], v[190:193], v[122:125]
	v_mfma_f32_16x16x32_bf16 v[118:121], v[134:137], v[198:201], v[118:121]
	v_mfma_f32_16x16x32_bf16 v[114:117], v[166:169], v[198:201], v[114:117]
	v_mfma_f32_16x16x32_bf16 v[110:113], v[134:137], v[206:209], v[110:113]
	v_mfma_f32_16x16x32_bf16 v[102:105], v[166:169], v[206:209], v[102:105]
	v_mfma_f32_16x16x32_bf16 v[82:85], v[134:137], v[214:217], v[82:85]
	v_mfma_f32_16x16x32_bf16 v[74:77], v[166:169], v[214:217], v[74:77]
	s_setprio 0
	s_setprio 1
	v_mfma_f32_16x16x32_bf16 v[106:109], v[170:173], v[186:189], 0
	v_mfma_f32_16x16x32_bf16 v[98:101], v[178:181], v[186:189], 0
	v_mfma_f32_16x16x32_bf16 v[94:97], v[170:173], v[194:197], 0
	v_mfma_f32_16x16x32_bf16 v[90:93], v[178:181], v[194:197], 0
	v_mfma_f32_16x16x32_bf16 v[86:89], v[170:173], v[202:205], 0
	v_mfma_f32_16x16x32_bf16 v[78:81], v[178:181], v[202:205], 0
	v_mfma_f32_16x16x32_bf16 v[70:73], v[170:173], v[210:213], 0
	v_mfma_f32_16x16x32_bf16 v[66:69], v[178:181], v[210:213], 0
	v_mfma_f32_16x16x32_bf16 v[106:109], v[174:177], v[190:193], v[106:109]
	v_mfma_f32_16x16x32_bf16 v[98:101], v[182:185], v[190:193], v[98:101]
	v_mfma_f32_16x16x32_bf16 v[94:97], v[174:177], v[198:201], v[94:97]
	v_mfma_f32_16x16x32_bf16 v[90:93], v[182:185], v[198:201], v[90:93]
	v_mfma_f32_16x16x32_bf16 v[86:89], v[174:177], v[206:209], v[86:89]
	v_mfma_f32_16x16x32_bf16 v[78:81], v[182:185], v[206:209], v[78:81]
	v_mfma_f32_16x16x32_bf16 v[70:73], v[174:177], v[214:217], v[70:73]
	v_mfma_f32_16x16x32_bf16 v[66:69], v[182:185], v[214:217], v[66:69]
	s_setprio 0
	s_barrier
	s_add_i32 s0, s45, s17
	v_lshl_add_u64 v[158:159], s[30:31], 0, v[140:141]
	s_mov_b32 m0, s0
	ds_read_b128 v[186:189], v163 offset:16384
	ds_read_b128 v[190:193], v163 offset:17408
	ds_read_b128 v[194:197], v163 offset:18432
	ds_read_b128 v[198:201], v163 offset:19456
	ds_read_b128 v[202:205], v163 offset:20480
	ds_read_b128 v[206:209], v163 offset:21504
	ds_read_b128 v[210:213], v163 offset:22528
	ds_read_b128 v[214:217], v163 offset:23552
	global_load_lds_dwordx4 v[158:159], off
	s_add_i32 m0, s0, 0x2000
	s_add_u32 s0, s30, 0x40000
	v_lshl_add_u64 v[218:219], s[30:31], 0, v[144:145]
	s_addc_u32 s1, s31, 0
	s_add_i32 s2, s46, s17
	global_load_lds_dwordx4 v[218:219], off
	v_lshl_add_u64 v[220:221], s[0:1], 0, v[140:141]
	s_mov_b32 m0, s2
	v_lshl_add_u64 v[222:223], s[34:35], 0, v[142:143]
	global_load_lds_dwordx4 v[220:221], off
	v_lshl_add_u64 v[220:221], s[0:1], 0, v[144:145]
	s_add_i32 m0, s2, 0x2000
	s_nop 0
	global_load_lds_dwordx4 v[220:221], off
	v_lshl_add_u64 v[220:221], s[34:35], 0, v[138:139]
	s_mov_b32 m0, s27
	s_nop 0
	global_load_lds_dwordx4 v[220:221], off
	s_mov_b32 m0, s38
	s_nop 0
	global_load_lds_dwordx4 v[222:223], off
	s_waitcnt vmcnt(8)
	s_waitcnt lgkmcnt(0)
	s_barrier
; #define PG8_STAGE(bufoff, gbase, voff) do { _Pragma("unroll") for (int _i = 0; _i < 2; ++_i) \
;         __builtin_amdgcn_global_load_lds((const unsigned*)((const char*)(gbase) + (voff)[_i]), (PG8_LAS unsigned*)(lds + (bufoff) + ldsw + _i * 8192), 16, 0, 0); } while (0)
; #define PG8_LDA(dst, b, h) do { _Pragma("unroll") for (int m = 0; m < 4; ++m) _Pragma("unroll") for (int k = 0; k < 2; ++k) dst[m][k] = *(const PG8_LAS bf16x8*)(lds + PG8_SA(b, h) + aoff + m * 2048 + k * 1024); } while (0)
; #define PG8_LDB(dst, b, h) do { _Pragma("unroll") for (int n = 0; n < 2; ++n) _Pragma("unroll") for (int k = 0; k < 2; ++k) dst[n][k] = *(const PG8_LAS bf16x8*)(lds + PG8_SB(b, h) + boff + n * 2048 + k * 1024); } while (0)
; #define PG8_MMA(ai, bj, At, Bt) do { __builtin_amdgcn_s_setprio(1); _Pragma("unroll") for (int m = 0; m < 4; ++m) _Pragma("unroll") for (int n = 0; n < 2; ++n) _Pragma("unroll") for (int k = 0; k < 2; ++k) \
;         acc[ai][bj][m][n] = __builtin_amdgcn_mfma_f32_16x16x32_bf16(Bt[n][k], At[m][k], acc[ai][bj][m][n], 0, 0, 0); __builtin_amdgcn_s_setprio(0); } while (0)
; #define PG8_WAIT_V(n) asm volatile("s_waitcnt vmcnt(" #n ")" ::: "memory")
; #define PG8_WAIT_L(n) asm volatile("s_waitcnt lgkmcnt(" #n ")" ::: "memory")
; #define PG8_BAR __builtin_amdgcn_s_barrier()
; #define PG8_SCHED __builtin_amdgcn_sched_barrier(0)
; template <class Epi, class Sched, bool ALIGN_EPI = false, bool SP2 = false>
; __device__ __forceinline__ void gemm_phase(PG8_LAS unsigned char* lds, const Gemm g, const Sched& S, const Epi& E) {
;     ...
;             PG8_WAIT_V(8); PG8_WAIT_L(0); PG8_BAR; PG8_MMA(1, 0, At, B0); PG8_MMA(1, 1, At, B1); PG8_BAR; PG8_SCHED;
;             PG8_LDB(B0, 1, 0); PG8_LDB(B1, 1, 1); PG8_SCHED; PG8_LDA(At, 1, 0); PG8_STAGE(PG8_SA(0, 1), a2 + hstepA, voffA);
;             PG8_WAIT_V(8); PG8_WAIT_L(0); PG8_BAR; PG8_MMA(0, 0, At, B0); PG8_MMA(0, 1, At, B1); PG8_BAR; PG8_SCHED;
	s_setprio 1
	s_waitcnt lgkmcnt(0)
	v_mfma_f32_16x16x32_bf16 v[62:65], v[130:133], v[186:189], 0
	v_mfma_f32_16x16x32_bf16 v[58:61], v[154:157], v[186:189], 0
	v_mfma_f32_16x16x32_bf16 v[54:57], v[130:133], v[194:197], 0
	v_mfma_f32_16x16x32_bf16 v[50:53], v[154:157], v[194:197], 0
	v_mfma_f32_16x16x32_bf16 v[34:37], v[130:133], v[202:205], 0
	v_mfma_f32_16x16x32_bf16 v[26:29], v[154:157], v[202:205], 0
	v_mfma_f32_16x16x32_bf16 v[18:21], v[130:133], v[210:213], 0
	v_mfma_f32_16x16x32_bf16 v[10:13], v[154:157], v[210:213], 0
	v_mfma_f32_16x16x32_bf16 v[62:65], v[134:137], v[190:193], v[62:65]
	v_mfma_f32_16x16x32_bf16 v[58:61], v[166:169], v[190:193], v[58:61]
	v_mfma_f32_16x16x32_bf16 v[54:57], v[134:137], v[198:201], v[54:57]
	v_mfma_f32_16x16x32_bf16 v[50:53], v[166:169], v[198:201], v[50:53]
	v_mfma_f32_16x16x32_bf16 v[34:37], v[134:137], v[206:209], v[34:37]
	v_mfma_f32_16x16x32_bf16 v[26:29], v[166:169], v[206:209], v[26:29]
	v_mfma_f32_16x16x32_bf16 v[18:21], v[134:137], v[214:217], v[18:21]
	v_mfma_f32_16x16x32_bf16 v[10:13], v[166:169], v[214:217], v[10:13]
	s_setprio 0
	s_setprio 1
	v_mfma_f32_16x16x32_bf16 v[46:49], v[170:173], v[186:189], 0
	v_mfma_f32_16x16x32_bf16 v[42:45], v[178:181], v[186:189], 0
	v_mfma_f32_16x16x32_bf16 v[38:41], v[170:173], v[194:197], 0
	v_mfma_f32_16x16x32_bf16 v[30:33], v[178:181], v[194:197], 0
	v_mfma_f32_16x16x32_bf16 v[22:25], v[170:173], v[202:205], 0
	v_mfma_f32_16x16x32_bf16 v[14:17], v[178:181], v[202:205], 0
	v_mfma_f32_16x16x32_bf16 v[6:9], v[170:173], v[210:213], 0
	v_mfma_f32_16x16x32_bf16 v[2:5], v[178:181], v[210:213], 0
	v_mfma_f32_16x16x32_bf16 v[46:49], v[174:177], v[190:193], v[46:49]
	v_mfma_f32_16x16x32_bf16 v[42:45], v[182:185], v[190:193], v[42:45]
	v_mfma_f32_16x16x32_bf16 v[38:41], v[174:177], v[198:201], v[38:41]
	v_mfma_f32_16x16x32_bf16 v[30:33], v[182:185], v[198:201], v[30:33]
	v_mfma_f32_16x16x32_bf16 v[22:25], v[174:177], v[206:209], v[22:25]
	v_mfma_f32_16x16x32_bf16 v[14:17], v[182:185], v[206:209], v[14:17]
	v_mfma_f32_16x16x32_bf16 v[6:9], v[174:177], v[214:217], v[6:9]
	v_mfma_f32_16x16x32_bf16 v[2:5], v[182:185], v[214:217], v[2:5]
	s_setprio 0
	s_barrier
	ds_read_b128 v[130:133], v164
	ds_read_b128 v[134:137], v164 offset:1024
	ds_read_b128 v[154:157], v164 offset:2048
	ds_read_b128 v[166:169], v164 offset:3072
	ds_read_b128 v[170:173], v165
	ds_read_b128 v[174:177], v165 offset:1024
	ds_read_b128 v[178:181], v165 offset:2048
	ds_read_b128 v[182:185], v165 offset:3072
	s_add_u32 s0, s34, 0x40000
	s_addc_u32 s1, s35, 0
	s_mov_b32 m0, s39
	v_lshl_add_u64 v[224:225], s[0:1], 0, v[138:139]
	ds_read_b128 v[186:189], v163 offset:32768
	ds_read_b128 v[190:193], v163 offset:33792
	ds_read_b128 v[194:197], v163 offset:34816
	ds_read_b128 v[198:201], v163 offset:35840
	ds_read_b128 v[202:205], v163 offset:36864
	ds_read_b128 v[206:209], v163 offset:37888
	ds_read_b128 v[210:213], v163 offset:38912
	ds_read_b128 v[214:217], v163 offset:39936
	global_load_lds_dwordx4 v[224:225], off
	v_lshl_add_u64 v[224:225], s[0:1], 0, v[142:143]
	s_mov_b32 m0, s40
	s_nop 0
	global_load_lds_dwordx4 v[224:225], off
	s_waitcnt vmcnt(8)
	s_waitcnt lgkmcnt(0)
	s_barrier
	s_setprio 1
	s_waitcnt lgkmcnt(0)
	v_mfma_f32_16x16x32_bf16 v[126:129], v[130:133], v[186:189], v[126:129]
	v_mfma_f32_16x16x32_bf16 v[122:125], v[154:157], v[186:189], v[122:125]
	v_mfma_f32_16x16x32_bf16 v[118:121], v[130:133], v[194:197], v[118:121]
	v_mfma_f32_16x16x32_bf16 v[114:117], v[154:157], v[194:197], v[114:117]
	v_mfma_f32_16x16x32_bf16 v[110:113], v[130:133], v[202:205], v[110:113]
	v_mfma_f32_16x16x32_bf16 v[102:105], v[154:157], v[202:205], v[102:105]
	v_mfma_f32_16x16x32_bf16 v[82:85], v[130:133], v[210:213], v[82:85]
	v_mfma_f32_16x16x32_bf16 v[74:77], v[154:157], v[210:213], v[74:77]
	v_mfma_f32_16x16x32_bf16 v[126:129], v[134:137], v[190:193], v[126:129]
	v_mfma_f32_16x16x32_bf16 v[122:125], v[166:169], v[190:193], v[122:125]
	v_mfma_f32_16x16x32_bf16 v[118:121], v[134:137], v[198:201], v[118:121]
	v_mfma_f32_16x16x32_bf16 v[114:117], v[166:169], v[198:201], v[114:117]
	v_mfma_f32_16x16x32_bf16 v[110:113], v[134:137], v[206:209], v[110:113]
	v_mfma_f32_16x16x32_bf16 v[102:105], v[166:169], v[206:209], v[102:105]
	v_mfma_f32_16x16x32_bf16 v[82:85], v[134:137], v[214:217], v[82:85]
	v_mfma_f32_16x16x32_bf16 v[74:77], v[166:169], v[214:217], v[74:77]
	s_setprio 0
	s_setprio 1
	v_mfma_f32_16x16x32_bf16 v[106:109], v[170:173], v[186:189], v[106:109]
	v_mfma_f32_16x16x32_bf16 v[98:101], v[178:181], v[186:189], v[98:101]
	v_mfma_f32_16x16x32_bf16 v[94:97], v[170:173], v[194:197], v[94:97]
	v_mfma_f32_16x16x32_bf16 v[90:93], v[178:181], v[194:197], v[90:93]
	v_mfma_f32_16x16x32_bf16 v[86:89], v[170:173], v[202:205], v[86:89]
	v_mfma_f32_16x16x32_bf16 v[78:81], v[178:181], v[202:205], v[78:81]
	v_mfma_f32_16x16x32_bf16 v[70:73], v[170:173], v[210:213], v[70:73]
	v_mfma_f32_16x16x32_bf16 v[66:69], v[178:181], v[210:213], v[66:69]
	v_mfma_f32_16x16x32_bf16 v[106:109], v[174:177], v[190:193], v[106:109]
	v_mfma_f32_16x16x32_bf16 v[98:101], v[182:185], v[190:193], v[98:101]
	v_mfma_f32_16x16x32_bf16 v[94:97], v[174:177], v[198:201], v[94:97]
	v_mfma_f32_16x16x32_bf16 v[90:93], v[182:185], v[198:201], v[90:93]
	v_mfma_f32_16x16x32_bf16 v[86:89], v[174:177], v[206:209], v[86:89]
	v_mfma_f32_16x16x32_bf16 v[78:81], v[182:185], v[206:209], v[78:81]
	v_mfma_f32_16x16x32_bf16 v[70:73], v[174:177], v[214:217], v[70:73]
	v_mfma_f32_16x16x32_bf16 v[66:69], v[182:185], v[214:217], v[66:69]
	s_setprio 0
	s_barrier
; #define PG8_STAGE(bufoff, gbase, voff) do { _Pragma("unroll") for (int _i = 0; _i < 2; ++_i) \
;         __builtin_amdgcn_global_load_lds((const unsigned*)((const char*)(gbase) + (voff)[_i]), (PG8_LAS unsigned*)(lds + (bufoff) + ldsw + _i * 8192), 16, 0, 0); } while (0)
; #define PG8_LDA(dst, b, h) do { _Pragma("unroll") for (int m = 0; m < 4; ++m) _Pragma("unroll") for (int k = 0; k < 2; ++k) dst[m][k] = *(const PG8_LAS bf16x8*)(lds + PG8_SA(b, h) + aoff + m * 2048 + k * 1024); } while (0)
; #define PG8_MMA(ai, bj, At, Bt) do { __builtin_amdgcn_s_setprio(1); _Pragma("unroll") for (int m = 0; m < 4; ++m) _Pragma("unroll") for (int n = 0; n < 2; ++n) _Pragma("unroll") for (int k = 0; k < 2; ++k) \
;         acc[ai][bj][m][n] = __builtin_amdgcn_mfma_f32_16x16x32_bf16(Bt[n][k], At[m][k], acc[ai][bj][m][n], 0, 0, 0); __builtin_amdgcn_s_setprio(0); } while (0)
; #define PG8_WAIT_V(n) asm volatile("s_waitcnt vmcnt(" #n ")" ::: "memory")
; #define PG8_WAIT_L(n) asm volatile("s_waitcnt lgkmcnt(" #n ")" ::: "memory")
; #define PG8_BAR __builtin_amdgcn_s_barrier()
; #define PG8_SCHED __builtin_amdgcn_sched_barrier(0)
; template <class Epi, class Sched, bool ALIGN_EPI = false, bool SP2 = false>
; __device__ __forceinline__ void gemm_phase(PG8_LAS unsigned char* lds, const Gemm g, const Sched& S, const Epi& E) {
;     ...
;         for (int t = 0; t < nt; t += 2) {
;             const bool last = (t == nt - 2);
;     ...
;             PG8_LDA(At, 1, 1); PG8_STAGE(PG8_SB(1, 0), b3, voffB); PG8_STAGE(PG8_SB(1, 1), b3 + hstepB, voffB); PG8_STAGE(PG8_SA(1, 0), a3, voffA);
;             PG8_WAIT_V(8); PG8_WAIT_L(0); PG8_BAR; PG8_MMA(1, 0, At, B0); PG8_MMA(1, 1, At, B1); PG8_BAR; PG8_SCHED;
	s_add_i32 s0, s47, s17
	v_lshl_add_u64 v[158:159], v[158:159], 0, s[8:9]
	s_mov_b32 m0, s0
	ds_read_b128 v[186:189], v163 offset:49152
	ds_read_b128 v[190:193], v163 offset:50176
	ds_read_b128 v[194:197], v163 offset:51200
	ds_read_b128 v[198:201], v163 offset:52224
	ds_read_b128 v[202:205], v163 offset:53248
	ds_read_b128 v[206:209], v163 offset:54272
	ds_read_b128 v[210:213], v163 offset:55296
	ds_read_b128 v[214:217], v163 offset:56320
	global_load_lds_dwordx4 v[158:159], off
	s_add_i32 m0, s0, 0x2000
	s_add_u32 s0, s30, 0x40080
	v_lshl_add_u64 v[158:159], v[218:219], 0, s[8:9]
	s_addc_u32 s1, s31, 0
	s_add_i32 s2, s48, s17
	global_load_lds_dwordx4 v[158:159], off
	v_lshl_add_u64 v[158:159], s[0:1], 0, v[140:141]
	s_mov_b32 m0, s2
	s_nop 0
	global_load_lds_dwordx4 v[158:159], off
	v_lshl_add_u64 v[158:159], s[0:1], 0, v[144:145]
	s_add_i32 m0, s2, 0x2000
	s_nop 0
	global_load_lds_dwordx4 v[158:159], off
	v_lshl_add_u64 v[158:159], v[220:221], 0, s[8:9]
	s_mov_b32 m0, s41
	s_nop 0
	global_load_lds_dwordx4 v[158:159], off
	v_lshl_add_u64 v[158:159], v[222:223], 0, s[8:9]
	s_mov_b32 m0, s42
	s_nop 0
	global_load_lds_dwordx4 v[158:159], off
	s_waitcnt vmcnt(8)
	s_waitcnt lgkmcnt(0)
	s_barrier
	s_setprio 1
	s_waitcnt lgkmcnt(0)
	v_mfma_f32_16x16x32_bf16 v[62:65], v[130:133], v[186:189], v[62:65]
	v_mfma_f32_16x16x32_bf16 v[58:61], v[154:157], v[186:189], v[58:61]
	v_mfma_f32_16x16x32_bf16 v[54:57], v[130:133], v[194:197], v[54:57]
	v_mfma_f32_16x16x32_bf16 v[50:53], v[154:157], v[194:197], v[50:53]
	v_mfma_f32_16x16x32_bf16 v[34:37], v[130:133], v[202:205], v[34:37]
	v_mfma_f32_16x16x32_bf16 v[26:29], v[154:157], v[202:205], v[26:29]
	v_mfma_f32_16x16x32_bf16 v[18:21], v[130:133], v[210:213], v[18:21]
	v_mfma_f32_16x16x32_bf16 v[10:13], v[154:157], v[210:213], v[10:13]
	v_mfma_f32_16x16x32_bf16 v[62:65], v[134:137], v[190:193], v[62:65]
	v_mfma_f32_16x16x32_bf16 v[58:61], v[166:169], v[190:193], v[58:61]
	v_mfma_f32_16x16x32_bf16 v[54:57], v[134:137], v[198:201], v[54:57]
	v_mfma_f32_16x16x32_bf16 v[50:53], v[166:169], v[198:201], v[50:53]
	v_mfma_f32_16x16x32_bf16 v[34:37], v[134:137], v[206:209], v[34:37]
	v_mfma_f32_16x16x32_bf16 v[26:29], v[166:169], v[206:209], v[26:29]
	v_mfma_f32_16x16x32_bf16 v[18:21], v[134:137], v[214:217], v[18:21]
	v_mfma_f32_16x16x32_bf16 v[10:13], v[166:169], v[214:217], v[10:13]
	s_setprio 0
	s_setprio 1
	v_mfma_f32_16x16x32_bf16 v[46:49], v[170:173], v[186:189], v[46:49]
	v_mfma_f32_16x16x32_bf16 v[42:45], v[178:181], v[186:189], v[42:45]
	v_mfma_f32_16x16x32_bf16 v[38:41], v[170:173], v[194:197], v[38:41]
	v_mfma_f32_16x16x32_bf16 v[30:33], v[178:181], v[194:197], v[30:33]
	v_mfma_f32_16x16x32_bf16 v[22:25], v[170:173], v[202:205], v[22:25]
	v_mfma_f32_16x16x32_bf16 v[14:17], v[178:181], v[202:205], v[14:17]
	v_mfma_f32_16x16x32_bf16 v[6:9], v[170:173], v[210:213], v[6:9]
	v_mfma_f32_16x16x32_bf16 v[2:5], v[178:181], v[210:213], v[2:5]
	v_mfma_f32_16x16x32_bf16 v[46:49], v[174:177], v[190:193], v[46:49]
	v_mfma_f32_16x16x32_bf16 v[42:45], v[182:185], v[190:193], v[42:45]
	v_mfma_f32_16x16x32_bf16 v[38:41], v[174:177], v[198:201], v[38:41]
	v_mfma_f32_16x16x32_bf16 v[30:33], v[182:185], v[198:201], v[30:33]
	v_mfma_f32_16x16x32_bf16 v[22:25], v[174:177], v[206:209], v[22:25]
	v_mfma_f32_16x16x32_bf16 v[14:17], v[182:185], v[206:209], v[14:17]
	v_mfma_f32_16x16x32_bf16 v[6:9], v[174:177], v[214:217], v[6:9]
	v_mfma_f32_16x16x32_bf16 v[2:5], v[182:185], v[214:217], v[2:5]
	s_setprio 0
	s_barrier
	s_add_i32 s67, s67, 2
	s_add_u32 s28, s28, 0x100
	s_addc_u32 s29, s29, 0
	s_add_u32 s50, s50, 0x100
	s_addc_u32 s51, s51, 0
	s_cmp_gt_u32 s67, 13

;     __device__ __forceinline__ bool next(int i, Unit& u) const { if (!S.next(i, u)) return false; if (u.pn >= 4) u.pn += 2; return true; }
; #define PG8_STAGE(bufoff, gbase, voff) do { _Pragma("unroll") for (int _i = 0; _i < 2; ++_i) \
;         __builtin_amdgcn_global_load_lds((const unsigned*)((const char*)(gbase) + (voff)[_i]), (PG8_LAS unsigned*)(lds + (bufoff) + ldsw + _i * 8192), 16, 0, 0); } while (0)
; #define PG8_LDA(dst, b, h) do { _Pragma("unroll") for (int m = 0; m < 4; ++m) _Pragma("unroll") for (int k = 0; k < 2; ++k) dst[m][k] = *(const PG8_LAS bf16x8*)(lds + PG8_SA(b, h) + aoff + m * 2048 + k * 1024); } while (0)
; #define PG8_LDB(dst, b, h) do { _Pragma("unroll") for (int n = 0; n < 2; ++n) _Pragma("unroll") for (int k = 0; k < 2; ++k) dst[n][k] = *(const PG8_LAS bf16x8*)(lds + PG8_SB(b, h) + boff + n * 2048 + k * 1024); } while (0)
; template <class Epi, class Sched, bool ALIGN_EPI = false, bool SP2 = false>
; __device__ __forceinline__ void gemm_phase(PG8_LAS unsigned char* lds, const Gemm g, const Sched& S, const Epi& E) {
;     ...
;         const bool has_next = S.next(ui + 1, nxt);
;         if constexpr (Epi::LDS_PF) { if (has_next) E.prefetch(nxt, lds + STAGE_BYTES + ((ui + 1) % 3) * 4096, wid, lane); }
;         const char* nA = has_next ? (const char*)g.A + (size_t)nxt.pm * tstepA : cA; const char* nB = has_next ? (const char*)g.Bt + (size_t)nxt.pn * tstepB : cB;
;         for (int t = 0; t < nt; t += 2) {
;             const bool last = (t == nt - 2);
;             const char* a1 = cA + (size_t)(t + 1) * kstep;
;             const char* a2 = last ? nA : cA + (size_t)(t + 2) * kstep; const char* b2 = last ? nB : cB + (size_t)(t + 2) * kstep;
;             const char* a3 = a2 + kstep; const char* b3 = b2 + kstep;
;             if (last && has_next) S.a_ready(nxt);
;             if constexpr (SP2) {
;             PG8_LDB(B0, 0, 0); PG8_LDB(B1, 0, 1); PG8_SCHED; PG8_LDA(At, 0, 0); PG8_STAGE(PG8_SA(1, 1), a1 + hstepA, voffA);
;             PG8_WAIT_V(8); PG8_WAIT_L(0); PG8_BAR; PG8_MMA(0, 0, At, B0); PG8_MMA(0, 1, At, B1); PG8_BAR; PG8_SCHED;
;             PG8_LDA(At, 0, 1); PG8_STAGE(PG8_SB(0, 0), b2, voffB); PG8_STAGE(PG8_SB(0, 1), b2 + hstepB, voffB); PG8_STAGE(PG8_SA(0, 0), a2, voffA);
;             PG8_WAIT_V(8); PG8_WAIT_L(0); PG8_BAR; PG8_MMA(1, 0, At, B0); PG8_MMA(1, 1, At, B1); PG8_BAR; PG8_SCHED;
.LBB0_1106:
	s_ashr_i32 s47, s46, 31
	s_lshl_b64 s[0:1], s[46:47], 19
	v_readlane_b32 s18, v253, 31
	v_readlane_b32 s19, v253, 32
	s_add_u32 s66, s18, s0
	s_addc_u32 s67, s19, s1
	s_and_b64 s[0:1], s[12:13], exec
	s_cselect_b32 s5, s67, s73
	s_cselect_b32 s15, s66, s72
	s_add_u32 s18, s72, 0x100
	s_addc_u32 s19, s73, 0
	s_mov_b32 s20, -2
	ds_read_b128 v[126:129], v205
	ds_read_b128 v[130:133], v205 offset:1024
	ds_read_b128 v[134:137], v205 offset:2048
	ds_read_b128 v[138:141], v205 offset:3072
	ds_read_b128 v[142:145], v206
	ds_read_b128 v[146:149], v206 offset:1024
	ds_read_b128 v[150:153], v206 offset:2048
	ds_read_b128 v[154:157], v206 offset:3072
	s_add_u32 s12, s70, 0x100
	s_addc_u32 s13, s71, 0
	s_cmp_eq_u32 s20, 12
	s_cselect_b32 s79, s51, s13
	s_cselect_b32 s78, s50, s12
	s_cselect_b32 s73, s5, s19
	s_cselect_b32 s72, s15, s18
	v_lshl_add_u64 v[226:227], s[70:71], 0, v[192:193]
	s_add_i32 m0, s80, 0xc000
	ds_read_b128 v[162:165], v207
	ds_read_b128 v[166:169], v207 offset:1024
	ds_read_b128 v[170:173], v207 offset:2048
	ds_read_b128 v[174:177], v207 offset:3072
	ds_read_b128 v[210:213], v207 offset:4096
	ds_read_b128 v[214:217], v207 offset:5120
	ds_read_b128 v[218:221], v207 offset:6144
	ds_read_b128 v[222:225], v207 offset:7168
	global_load_lds_dwordx4 v[226:227], off
	v_lshl_add_u64 v[226:227], s[70:71], 0, v[194:195]
	s_add_i32 m0, s80, 0xe000
	s_nop 0
	global_load_lds_dwordx4 v[226:227], off
	s_waitcnt vmcnt(8)
	s_waitcnt lgkmcnt(0)
	s_barrier
	s_setprio 1
	s_waitcnt lgkmcnt(0)
	v_mfma_f32_16x16x32_bf16 v[114:117], v[126:129], v[162:165], 0
	v_mfma_f32_16x16x32_bf16 v[106:109], v[134:137], v[162:165], 0
	v_mfma_f32_16x16x32_bf16 v[98:101], v[126:129], v[170:173], 0
	v_mfma_f32_16x16x32_bf16 v[82:85], v[134:137], v[170:173], 0
	v_mfma_f32_16x16x32_bf16 v[94:97], v[126:129], v[210:213], 0
	v_mfma_f32_16x16x32_bf16 v[78:81], v[134:137], v[210:213], 0
	v_mfma_f32_16x16x32_bf16 v[90:93], v[126:129], v[218:221], 0
	v_mfma_f32_16x16x32_bf16 v[74:77], v[134:137], v[218:221], 0
	v_mfma_f32_16x16x32_bf16 v[114:117], v[130:133], v[166:169], v[114:117]
	v_mfma_f32_16x16x32_bf16 v[106:109], v[138:141], v[166:169], v[106:109]
	v_mfma_f32_16x16x32_bf16 v[98:101], v[130:133], v[174:177], v[98:101]
	v_mfma_f32_16x16x32_bf16 v[82:85], v[138:141], v[174:177], v[82:85]
	v_mfma_f32_16x16x32_bf16 v[94:97], v[130:133], v[214:217], v[94:97]
	v_mfma_f32_16x16x32_bf16 v[78:81], v[138:141], v[214:217], v[78:81]
	v_mfma_f32_16x16x32_bf16 v[90:93], v[130:133], v[222:225], v[90:93]
	v_mfma_f32_16x16x32_bf16 v[74:77], v[138:141], v[222:225], v[74:77]
	s_setprio 0
	s_setprio 1
	v_mfma_f32_16x16x32_bf16 v[158:161], v[142:145], v[162:165], 0
	v_mfma_f32_16x16x32_bf16 v[122:125], v[150:153], v[162:165], 0
	v_mfma_f32_16x16x32_bf16 v[118:121], v[142:145], v[170:173], 0
	v_mfma_f32_16x16x32_bf16 v[110:113], v[150:153], v[170:173], 0
	v_mfma_f32_16x16x32_bf16 v[102:105], v[142:145], v[210:213], 0
	v_mfma_f32_16x16x32_bf16 v[86:89], v[150:153], v[210:213], 0
	v_mfma_f32_16x16x32_bf16 v[70:73], v[142:145], v[218:221], 0
	v_mfma_f32_16x16x32_bf16 v[66:69], v[150:153], v[218:221], 0
	v_mfma_f32_16x16x32_bf16 v[158:161], v[146:149], v[166:169], v[158:161]
	v_mfma_f32_16x16x32_bf16 v[122:125], v[154:157], v[166:169], v[122:125]
	v_mfma_f32_16x16x32_bf16 v[118:121], v[146:149], v[174:177], v[118:121]
	v_mfma_f32_16x16x32_bf16 v[110:113], v[154:157], v[174:177], v[110:113]
	v_mfma_f32_16x16x32_bf16 v[102:105], v[146:149], v[214:217], v[102:105]
	v_mfma_f32_16x16x32_bf16 v[86:89], v[154:157], v[214:217], v[86:89]
	v_mfma_f32_16x16x32_bf16 v[70:73], v[146:149], v[222:225], v[70:73]
	v_mfma_f32_16x16x32_bf16 v[66:69], v[154:157], v[222:225], v[66:69]
	s_setprio 0
	s_barrier
	s_add_i32 s0, s88, s69
	v_lshl_add_u64 v[226:227], s[72:73], 0, v[180:181]
	s_mov_b32 m0, s0
	ds_read_b128 v[162:165], v207 offset:16384
	ds_read_b128 v[166:169], v207 offset:17408
	ds_read_b128 v[170:173], v207 offset:18432
	ds_read_b128 v[174:177], v207 offset:19456
	ds_read_b128 v[210:213], v207 offset:20480
	ds_read_b128 v[214:217], v207 offset:21504
	ds_read_b128 v[218:221], v207 offset:22528
	ds_read_b128 v[222:225], v207 offset:23552
	global_load_lds_dwordx4 v[226:227], off
	s_add_i32 m0, s0, 0x2000
	s_add_u32 s0, s72, 0x40000
	v_lshl_add_u64 v[228:229], s[72:73], 0, v[184:185]
	s_addc_u32 s1, s73, 0
	s_add_i32 s2, s89, s69
	global_load_lds_dwordx4 v[228:229], off
	v_lshl_add_u64 v[230:231], s[0:1], 0, v[180:181]
	s_mov_b32 m0, s2
	v_lshl_add_u64 v[232:233], s[78:79], 0, v[182:183]
	global_load_lds_dwordx4 v[230:231], off
	v_lshl_add_u64 v[230:231], s[0:1], 0, v[184:185]
	s_add_i32 m0, s2, 0x2000
	s_nop 0
	global_load_lds_dwordx4 v[230:231], off
	v_lshl_add_u64 v[230:231], s[78:79], 0, v[178:179]
	s_mov_b32 m0, s80
	s_nop 0
	global_load_lds_dwordx4 v[230:231], off
	s_mov_b32 m0, s81
	s_nop 0
	global_load_lds_dwordx4 v[232:233], off
	s_waitcnt vmcnt(8)
	s_waitcnt lgkmcnt(0)
	s_barrier
; #define PG8_STAGE(bufoff, gbase, voff) do { _Pragma("unroll") for (int _i = 0; _i < 2; ++_i) \
;         __builtin_amdgcn_global_load_lds((const unsigned*)((const char*)(gbase) + (voff)[_i]), (PG8_LAS unsigned*)(lds + (bufoff) + ldsw + _i * 8192), 16, 0, 0); } while (0)
; #define PG8_LDA(dst, b, h) do { _Pragma("unroll") for (int m = 0; m < 4; ++m) _Pragma("unroll") for (int k = 0; k < 2; ++k) dst[m][k] = *(const PG8_LAS bf16x8*)(lds + PG8_SA(b, h) + aoff + m * 2048 + k * 1024); } while (0)
; #define PG8_LDB(dst, b, h) do { _Pragma("unroll") for (int n = 0; n < 2; ++n) _Pragma("unroll") for (int k = 0; k < 2; ++k) dst[n][k] = *(const PG8_LAS bf16x8*)(lds + PG8_SB(b, h) + boff + n * 2048 + k * 1024); } while (0)
; #define PG8_MMA(ai, bj, At, Bt) do { __builtin_amdgcn_s_setprio(1); _Pragma("unroll") for (int m = 0; m < 4; ++m) _Pragma("unroll") for (int n = 0; n < 2; ++n) _Pragma("unroll") for (int k = 0; k < 2; ++k) \
;         acc[ai][bj][m][n] = __builtin_amdgcn_mfma_f32_16x16x32_bf16(Bt[n][k], At[m][k], acc[ai][bj][m][n], 0, 0, 0); __builtin_amdgcn_s_setprio(0); } while (0)
; #define PG8_WAIT_V(n) asm volatile("s_waitcnt vmcnt(" #n ")" ::: "memory")
; #define PG8_WAIT_L(n) asm volatile("s_waitcnt lgkmcnt(" #n ")" ::: "memory")
; #define PG8_BAR __builtin_amdgcn_s_barrier()
; #define PG8_SCHED __builtin_amdgcn_sched_barrier(0)
; template <class Epi, class Sched, bool ALIGN_EPI = false, bool SP2 = false>
; __device__ __forceinline__ void gemm_phase(PG8_LAS unsigned char* lds, const Gemm g, const Sched& S, const Epi& E) {
;     ...
;             PG8_WAIT_V(8); PG8_WAIT_L(0); PG8_BAR; PG8_MMA(1, 0, At, B0); PG8_MMA(1, 1, At, B1); PG8_BAR; PG8_SCHED;
;             PG8_LDB(B0, 1, 0); PG8_LDB(B1, 1, 1); PG8_SCHED; PG8_LDA(At, 1, 0); PG8_STAGE(PG8_SA(0, 1), a2 + hstepA, voffA);
;             PG8_WAIT_V(8); PG8_WAIT_L(0); PG8_BAR; PG8_MMA(0, 0, At, B0); PG8_MMA(0, 1, At, B1); PG8_BAR; PG8_SCHED;
	s_setprio 1
	s_waitcnt lgkmcnt(0)
	v_mfma_f32_16x16x32_bf16 v[50:53], v[126:129], v[162:165], 0
	v_mfma_f32_16x16x32_bf16 v[42:45], v[134:137], v[162:165], 0
	v_mfma_f32_16x16x32_bf16 v[34:37], v[126:129], v[170:173], 0
	v_mfma_f32_16x16x32_bf16 v[18:21], v[134:137], v[170:173], 0
	v_mfma_f32_16x16x32_bf16 v[30:33], v[126:129], v[210:213], 0
	v_mfma_f32_16x16x32_bf16 v[14:17], v[134:137], v[210:213], 0
	v_mfma_f32_16x16x32_bf16 v[26:29], v[126:129], v[218:221], 0
	v_mfma_f32_16x16x32_bf16 v[10:13], v[134:137], v[218:221], 0
	v_mfma_f32_16x16x32_bf16 v[50:53], v[130:133], v[166:169], v[50:53]
	v_mfma_f32_16x16x32_bf16 v[42:45], v[138:141], v[166:169], v[42:45]
	v_mfma_f32_16x16x32_bf16 v[34:37], v[130:133], v[174:177], v[34:37]
	v_mfma_f32_16x16x32_bf16 v[18:21], v[138:141], v[174:177], v[18:21]
	v_mfma_f32_16x16x32_bf16 v[30:33], v[130:133], v[214:217], v[30:33]
	v_mfma_f32_16x16x32_bf16 v[14:17], v[138:141], v[214:217], v[14:17]
	v_mfma_f32_16x16x32_bf16 v[26:29], v[130:133], v[222:225], v[26:29]
	v_mfma_f32_16x16x32_bf16 v[10:13], v[138:141], v[222:225], v[10:13]
	s_setprio 0
	s_setprio 1
	v_mfma_f32_16x16x32_bf16 v[62:65], v[142:145], v[162:165], 0
	v_mfma_f32_16x16x32_bf16 v[58:61], v[150:153], v[162:165], 0
	v_mfma_f32_16x16x32_bf16 v[54:57], v[142:145], v[170:173], 0
	v_mfma_f32_16x16x32_bf16 v[46:49], v[150:153], v[170:173], 0
	v_mfma_f32_16x16x32_bf16 v[38:41], v[142:145], v[210:213], 0
	v_mfma_f32_16x16x32_bf16 v[22:25], v[150:153], v[210:213], 0
	v_mfma_f32_16x16x32_bf16 v[6:9], v[142:145], v[218:221], 0
	v_mfma_f32_16x16x32_bf16 v[2:5], v[150:153], v[218:221], 0
	v_mfma_f32_16x16x32_bf16 v[62:65], v[146:149], v[166:169], v[62:65]
	v_mfma_f32_16x16x32_bf16 v[58:61], v[154:157], v[166:169], v[58:61]
	v_mfma_f32_16x16x32_bf16 v[54:57], v[146:149], v[174:177], v[54:57]
	v_mfma_f32_16x16x32_bf16 v[46:49], v[154:157], v[174:177], v[46:49]
	v_mfma_f32_16x16x32_bf16 v[38:41], v[146:149], v[214:217], v[38:41]
	v_mfma_f32_16x16x32_bf16 v[22:25], v[154:157], v[214:217], v[22:25]
	v_mfma_f32_16x16x32_bf16 v[6:9], v[146:149], v[222:225], v[6:9]
	v_mfma_f32_16x16x32_bf16 v[2:5], v[154:157], v[222:225], v[2:5]
	s_setprio 0
	s_barrier
	ds_read_b128 v[126:129], v208
	ds_read_b128 v[130:133], v208 offset:1024
	ds_read_b128 v[134:137], v208 offset:2048
	ds_read_b128 v[138:141], v208 offset:3072
	ds_read_b128 v[142:145], v209
	ds_read_b128 v[146:149], v209 offset:1024
	ds_read_b128 v[150:153], v209 offset:2048
	ds_read_b128 v[154:157], v209 offset:3072
	s_add_u32 s0, s78, 0x40000
	s_addc_u32 s1, s79, 0
	s_mov_b32 m0, s82
	v_lshl_add_u64 v[234:235], s[0:1], 0, v[178:179]
	ds_read_b128 v[162:165], v207 offset:32768
	ds_read_b128 v[166:169], v207 offset:33792
	ds_read_b128 v[170:173], v207 offset:34816
	ds_read_b128 v[174:177], v207 offset:35840
	ds_read_b128 v[210:213], v207 offset:36864
	ds_read_b128 v[214:217], v207 offset:37888
	ds_read_b128 v[218:221], v207 offset:38912
	ds_read_b128 v[222:225], v207 offset:39936
	global_load_lds_dwordx4 v[234:235], off
	v_lshl_add_u64 v[234:235], s[0:1], 0, v[182:183]
	s_mov_b32 m0, s83
	s_nop 0
	global_load_lds_dwordx4 v[234:235], off
	s_waitcnt vmcnt(8)
	s_waitcnt lgkmcnt(0)
	s_barrier
	s_setprio 1
	s_waitcnt lgkmcnt(0)
	v_mfma_f32_16x16x32_bf16 v[114:117], v[126:129], v[162:165], v[114:117]
	v_mfma_f32_16x16x32_bf16 v[106:109], v[134:137], v[162:165], v[106:109]
	v_mfma_f32_16x16x32_bf16 v[98:101], v[126:129], v[170:173], v[98:101]
	v_mfma_f32_16x16x32_bf16 v[82:85], v[134:137], v[170:173], v[82:85]
	v_mfma_f32_16x16x32_bf16 v[94:97], v[126:129], v[210:213], v[94:97]
	v_mfma_f32_16x16x32_bf16 v[78:81], v[134:137], v[210:213], v[78:81]
	v_mfma_f32_16x16x32_bf16 v[90:93], v[126:129], v[218:221], v[90:93]
	v_mfma_f32_16x16x32_bf16 v[74:77], v[134:137], v[218:221], v[74:77]
	v_mfma_f32_16x16x32_bf16 v[114:117], v[130:133], v[166:169], v[114:117]
	v_mfma_f32_16x16x32_bf16 v[106:109], v[138:141], v[166:169], v[106:109]
	v_mfma_f32_16x16x32_bf16 v[98:101], v[130:133], v[174:177], v[98:101]
	v_mfma_f32_16x16x32_bf16 v[82:85], v[138:141], v[174:177], v[82:85]
	v_mfma_f32_16x16x32_bf16 v[94:97], v[130:133], v[214:217], v[94:97]
	v_mfma_f32_16x16x32_bf16 v[78:81], v[138:141], v[214:217], v[78:81]
	v_mfma_f32_16x16x32_bf16 v[90:93], v[130:133], v[222:225], v[90:93]
	v_mfma_f32_16x16x32_bf16 v[74:77], v[138:141], v[222:225], v[74:77]
	s_setprio 0
	s_setprio 1
	v_mfma_f32_16x16x32_bf16 v[158:161], v[142:145], v[162:165], v[158:161]
	v_mfma_f32_16x16x32_bf16 v[122:125], v[150:153], v[162:165], v[122:125]
	v_mfma_f32_16x16x32_bf16 v[118:121], v[142:145], v[170:173], v[118:121]
	v_mfma_f32_16x16x32_bf16 v[110:113], v[150:153], v[170:173], v[110:113]
	v_mfma_f32_16x16x32_bf16 v[102:105], v[142:145], v[210:213], v[102:105]
	v_mfma_f32_16x16x32_bf16 v[86:89], v[150:153], v[210:213], v[86:89]
	v_mfma_f32_16x16x32_bf16 v[70:73], v[142:145], v[218:221], v[70:73]
	v_mfma_f32_16x16x32_bf16 v[66:69], v[150:153], v[218:221], v[66:69]
	v_mfma_f32_16x16x32_bf16 v[158:161], v[146:149], v[166:169], v[158:161]
	v_mfma_f32_16x16x32_bf16 v[122:125], v[154:157], v[166:169], v[122:125]
	v_mfma_f32_16x16x32_bf16 v[118:121], v[146:149], v[174:177], v[118:121]
	v_mfma_f32_16x16x32_bf16 v[110:113], v[154:157], v[174:177], v[110:113]
	v_mfma_f32_16x16x32_bf16 v[102:105], v[146:149], v[214:217], v[102:105]
	v_mfma_f32_16x16x32_bf16 v[86:89], v[154:157], v[214:217], v[86:89]
	v_mfma_f32_16x16x32_bf16 v[70:73], v[146:149], v[222:225], v[70:73]
	v_mfma_f32_16x16x32_bf16 v[66:69], v[154:157], v[222:225], v[66:69]
	s_setprio 0
	s_barrier
; #define PG8_STAGE(bufoff, gbase, voff) do { _Pragma("unroll") for (int _i = 0; _i < 2; ++_i) \
;         __builtin_amdgcn_global_load_lds((const unsigned*)((const char*)(gbase) + (voff)[_i]), (PG8_LAS unsigned*)(lds + (bufoff) + ldsw + _i * 8192), 16, 0, 0); } while (0)
; #define PG8_LDA(dst, b, h) do { _Pragma("unroll") for (int m = 0; m < 4; ++m) _Pragma("unroll") for (int k = 0; k < 2; ++k) dst[m][k] = *(const PG8_LAS bf16x8*)(lds + PG8_SA(b, h) + aoff + m * 2048 + k * 1024); } while (0)
; #define PG8_MMA(ai, bj, At, Bt) do { __builtin_amdgcn_s_setprio(1); _Pragma("unroll") for (int m = 0; m < 4; ++m) _Pragma("unroll") for (int n = 0; n < 2; ++n) _Pragma("unroll") for (int k = 0; k < 2; ++k) \
;         acc[ai][bj][m][n] = __builtin_amdgcn_mfma_f32_16x16x32_bf16(Bt[n][k], At[m][k], acc[ai][bj][m][n], 0, 0, 0); __builtin_amdgcn_s_setprio(0); } while (0)
; #define PG8_WAIT_V(n) asm volatile("s_waitcnt vmcnt(" #n ")" ::: "memory")
; #define PG8_WAIT_L(n) asm volatile("s_waitcnt lgkmcnt(" #n ")" ::: "memory")
; #define PG8_BAR __builtin_amdgcn_s_barrier()
; #define PG8_SCHED __builtin_amdgcn_sched_barrier(0)
; template <class Epi, class Sched, bool ALIGN_EPI = false, bool SP2 = false>
; __device__ __forceinline__ void gemm_phase(PG8_LAS unsigned char* lds, const Gemm g, const Sched& S, const Epi& E) {
;     ...
;         for (int t = 0; t < nt; t += 2) {
;             const bool last = (t == nt - 2);
;     ...
;             PG8_LDA(At, 1, 1); PG8_STAGE(PG8_SB(1, 0), b3, voffB); PG8_STAGE(PG8_SB(1, 1), b3 + hstepB, voffB); PG8_STAGE(PG8_SA(1, 0), a3, voffA);
;             PG8_WAIT_V(8); PG8_WAIT_L(0); PG8_BAR; PG8_MMA(1, 0, At, B0); PG8_MMA(1, 1, At, B1); PG8_BAR; PG8_SCHED;
	s_add_i32 s0, s90, s69
	v_lshl_add_u64 v[226:227], v[226:227], 0, s[38:39]
	s_mov_b32 m0, s0
	ds_read_b128 v[162:165], v207 offset:49152
	ds_read_b128 v[166:169], v207 offset:50176
	ds_read_b128 v[170:173], v207 offset:51200
	ds_read_b128 v[174:177], v207 offset:52224
	ds_read_b128 v[210:213], v207 offset:53248
	ds_read_b128 v[214:217], v207 offset:54272
	ds_read_b128 v[218:221], v207 offset:55296
	ds_read_b128 v[222:225], v207 offset:56320
	global_load_lds_dwordx4 v[226:227], off
	s_add_i32 m0, s0, 0x2000
	s_add_u32 s0, s72, 0x40080
	v_lshl_add_u64 v[226:227], v[228:229], 0, s[38:39]
	s_addc_u32 s1, s73, 0
	s_add_i32 s2, s91, s69
	global_load_lds_dwordx4 v[226:227], off
	v_lshl_add_u64 v[226:227], s[0:1], 0, v[180:181]
	s_mov_b32 m0, s2
	s_nop 0
	global_load_lds_dwordx4 v[226:227], off
	v_lshl_add_u64 v[226:227], s[0:1], 0, v[184:185]
	s_add_i32 m0, s2, 0x2000
	s_nop 0
	global_load_lds_dwordx4 v[226:227], off
	v_lshl_add_u64 v[226:227], v[230:231], 0, s[38:39]
	s_mov_b32 m0, s84
	s_nop 0
	global_load_lds_dwordx4 v[226:227], off
	v_lshl_add_u64 v[226:227], v[232:233], 0, s[38:39]
	s_mov_b32 m0, s85
	s_nop 0
	global_load_lds_dwordx4 v[226:227], off
	s_waitcnt vmcnt(8)
	s_waitcnt lgkmcnt(0)
	s_barrier
	s_setprio 1
	s_waitcnt lgkmcnt(0)
	v_mfma_f32_16x16x32_bf16 v[50:53], v[126:129], v[162:165], v[50:53]
	v_mfma_f32_16x16x32_bf16 v[42:45], v[134:137], v[162:165], v[42:45]
	v_mfma_f32_16x16x32_bf16 v[34:37], v[126:129], v[170:173], v[34:37]
	v_mfma_f32_16x16x32_bf16 v[18:21], v[134:137], v[170:173], v[18:21]
	v_mfma_f32_16x16x32_bf16 v[30:33], v[126:129], v[210:213], v[30:33]
	v_mfma_f32_16x16x32_bf16 v[14:17], v[134:137], v[210:213], v[14:17]
	v_mfma_f32_16x16x32_bf16 v[26:29], v[126:129], v[218:221], v[26:29]
	v_mfma_f32_16x16x32_bf16 v[10:13], v[134:137], v[218:221], v[10:13]
	v_mfma_f32_16x16x32_bf16 v[50:53], v[130:133], v[166:169], v[50:53]
	v_mfma_f32_16x16x32_bf16 v[42:45], v[138:141], v[166:169], v[42:45]
	v_mfma_f32_16x16x32_bf16 v[34:37], v[130:133], v[174:177], v[34:37]
	v_mfma_f32_16x16x32_bf16 v[18:21], v[138:141], v[174:177], v[18:21]
	v_mfma_f32_16x16x32_bf16 v[30:33], v[130:133], v[214:217], v[30:33]
	v_mfma_f32_16x16x32_bf16 v[14:17], v[138:141], v[214:217], v[14:17]
	v_mfma_f32_16x16x32_bf16 v[26:29], v[130:133], v[222:225], v[26:29]
	v_mfma_f32_16x16x32_bf16 v[10:13], v[138:141], v[222:225], v[10:13]
	s_setprio 0
	s_setprio 1
	v_mfma_f32_16x16x32_bf16 v[62:65], v[142:145], v[162:165], v[62:65]
	v_mfma_f32_16x16x32_bf16 v[58:61], v[150:153], v[162:165], v[58:61]
	v_mfma_f32_16x16x32_bf16 v[54:57], v[142:145], v[170:173], v[54:57]
	v_mfma_f32_16x16x32_bf16 v[46:49], v[150:153], v[170:173], v[46:49]
	v_mfma_f32_16x16x32_bf16 v[38:41], v[142:145], v[210:213], v[38:41]
	v_mfma_f32_16x16x32_bf16 v[22:25], v[150:153], v[210:213], v[22:25]
	v_mfma_f32_16x16x32_bf16 v[6:9], v[142:145], v[218:221], v[6:9]
	v_mfma_f32_16x16x32_bf16 v[2:5], v[150:153], v[218:221], v[2:5]
	v_mfma_f32_16x16x32_bf16 v[62:65], v[146:149], v[166:169], v[62:65]
	v_mfma_f32_16x16x32_bf16 v[58:61], v[154:157], v[166:169], v[58:61]
	v_mfma_f32_16x16x32_bf16 v[54:57], v[146:149], v[174:177], v[54:57]
	v_mfma_f32_16x16x32_bf16 v[46:49], v[154:157], v[174:177], v[46:49]
	v_mfma_f32_16x16x32_bf16 v[38:41], v[146:149], v[214:217], v[38:41]
	v_mfma_f32_16x16x32_bf16 v[22:25], v[154:157], v[214:217], v[22:25]
	v_mfma_f32_16x16x32_bf16 v[6:9], v[146:149], v[222:225], v[6:9]
	v_mfma_f32_16x16x32_bf16 v[2:5], v[154:157], v[222:225], v[2:5]
	s_setprio 0
	s_barrier
	s_add_i32 s20, s20, 2
	s_add_u32 s18, s18, 0x100
	s_addc_u32 s19, s19, 0
	s_cmp_gt_u32 s20, 13
	s_mov_b64 s[70:71], s[12:13]

;     __device__ __forceinline__ bool next(int i, Unit& u) const { if (!S.next(i, u)) return false; if (u.pn >= 4) u.pn += 2; return true; }
; #define PG8_STAGE(bufoff, gbase, voff) do { _Pragma("unroll") for (int _i = 0; _i < 2; ++_i) \
;         __builtin_amdgcn_global_load_lds((const unsigned*)((const char*)(gbase) + (voff)[_i]), (PG8_LAS unsigned*)(lds + (bufoff) + ldsw + _i * 8192), 16, 0, 0); } while (0)
; #define PG8_LDA(dst, b, h) do { _Pragma("unroll") for (int m = 0; m < 4; ++m) _Pragma("unroll") for (int k = 0; k < 2; ++k) dst[m][k] = *(const PG8_LAS bf16x8*)(lds + PG8_SA(b, h) + aoff + m * 2048 + k * 1024); } while (0)
; #define PG8_LDB(dst, b, h) do { _Pragma("unroll") for (int n = 0; n < 2; ++n) _Pragma("unroll") for (int k = 0; k < 2; ++k) dst[n][k] = *(const PG8_LAS bf16x8*)(lds + PG8_SB(b, h) + boff + n * 2048 + k * 1024); } while (0)
; template <class Epi, class Sched, bool ALIGN_EPI = false, bool SP2 = false>
; __device__ __forceinline__ void gemm_phase(PG8_LAS unsigned char* lds, const Gemm g, const Sched& S, const Epi& E) {
;     ...
;         const bool has_next = S.next(ui + 1, nxt);
;         if constexpr (Epi::LDS_PF) { if (has_next) E.prefetch(nxt, lds + STAGE_BYTES + ((ui + 1) % 3) * 4096, wid, lane); }
;         const char* nA = has_next ? (const char*)g.A + (size_t)nxt.pm * tstepA : cA; const char* nB = has_next ? (const char*)g.Bt + (size_t)nxt.pn * tstepB : cB;
;         for (int t = 0; t < nt; t += 2) {
;             const bool last = (t == nt - 2);
;             const char* a1 = cA + (size_t)(t + 1) * kstep;
;             const char* a2 = last ? nA : cA + (size_t)(t + 2) * kstep; const char* b2 = last ? nB : cB + (size_t)(t + 2) * kstep;
;             const char* a3 = a2 + kstep; const char* b3 = b2 + kstep;
;             if (last && has_next) S.a_ready(nxt);
;             if constexpr (SP2) {
;             PG8_LDB(B0, 0, 0); PG8_LDB(B1, 0, 1); PG8_SCHED; PG8_LDA(At, 0, 0); PG8_STAGE(PG8_SA(1, 1), a1 + hstepA, voffA);
;             PG8_WAIT_V(8); PG8_WAIT_L(0); PG8_BAR; PG8_MMA(0, 0, At, B0); PG8_MMA(0, 1, At, B1); PG8_BAR; PG8_SCHED;
;             PG8_LDA(At, 0, 1); PG8_STAGE(PG8_SB(0, 0), b2, voffB); PG8_STAGE(PG8_SB(0, 1), b2 + hstepB, voffB); PG8_STAGE(PG8_SA(0, 0), a2, voffA);
;             PG8_WAIT_V(8); PG8_WAIT_L(0); PG8_BAR; PG8_MMA(1, 0, At, B0); PG8_MMA(1, 1, At, B1); PG8_BAR; PG8_SCHED;
.LBB0_1197:
	s_add_u32 s4, s70, 0x100
	s_addc_u32 s5, s71, 0
	s_mov_b32 s7, -2
	ds_read_b128 v[130:133], v207
	ds_read_b128 v[134:137], v207 offset:1024
	ds_read_b128 v[138:141], v207 offset:2048
	ds_read_b128 v[142:145], v207 offset:3072
	ds_read_b128 v[146:149], v208
	ds_read_b128 v[150:153], v208 offset:1024
	ds_read_b128 v[154:157], v208 offset:2048
	ds_read_b128 v[158:161], v208 offset:3072
	s_add_u32 s70, s68, 0x100
	s_addc_u32 s71, s69, 0
	s_cmp_eq_u32 s7, 40
	s_cselect_b32 s77, s13, s71
	s_cselect_b32 s76, s12, s70
	s_cselect_b32 s73, s51, s5
	s_cselect_b32 s72, s50, s4
	v_lshl_add_u64 v[188:189], s[68:69], 0, v[176:177]
	s_add_i32 m0, s78, 0xc000
	ds_read_b128 v[184:187], v209
	ds_read_b128 v[212:215], v209 offset:1024
	ds_read_b128 v[216:219], v209 offset:2048
	ds_read_b128 v[220:223], v209 offset:3072
	ds_read_b128 v[224:227], v209 offset:4096
	ds_read_b128 v[228:231], v209 offset:5120
	ds_read_b128 v[232:235], v209 offset:6144
	ds_read_b128 v[236:239], v209 offset:7168
	global_load_lds_dwordx4 v[188:189], off
	v_lshl_add_u64 v[188:189], s[68:69], 0, v[178:179]
	s_add_i32 m0, s78, 0xe000
	s_nop 0
	global_load_lds_dwordx4 v[188:189], off
	s_waitcnt vmcnt(8)
	s_waitcnt lgkmcnt(0)
	s_barrier
	s_setprio 1
	s_waitcnt lgkmcnt(0)
	v_mfma_f32_16x16x32_bf16 v[126:129], v[130:133], v[184:187], 0
	v_mfma_f32_16x16x32_bf16 v[122:125], v[138:141], v[184:187], 0
	v_mfma_f32_16x16x32_bf16 v[110:113], v[130:133], v[216:219], 0
	v_mfma_f32_16x16x32_bf16 v[106:109], v[138:141], v[216:219], 0
	v_mfma_f32_16x16x32_bf16 v[94:97], v[130:133], v[224:227], 0
	v_mfma_f32_16x16x32_bf16 v[90:93], v[138:141], v[224:227], 0
	v_mfma_f32_16x16x32_bf16 v[78:81], v[130:133], v[232:235], 0
	v_mfma_f32_16x16x32_bf16 v[74:77], v[138:141], v[232:235], 0
	v_mfma_f32_16x16x32_bf16 v[126:129], v[134:137], v[212:215], v[126:129]
	v_mfma_f32_16x16x32_bf16 v[122:125], v[142:145], v[212:215], v[122:125]
	v_mfma_f32_16x16x32_bf16 v[110:113], v[134:137], v[220:223], v[110:113]
	v_mfma_f32_16x16x32_bf16 v[106:109], v[142:145], v[220:223], v[106:109]
	v_mfma_f32_16x16x32_bf16 v[94:97], v[134:137], v[228:231], v[94:97]
	v_mfma_f32_16x16x32_bf16 v[90:93], v[142:145], v[228:231], v[90:93]
	v_mfma_f32_16x16x32_bf16 v[78:81], v[134:137], v[236:239], v[78:81]
	v_mfma_f32_16x16x32_bf16 v[74:77], v[142:145], v[236:239], v[74:77]
	s_setprio 0
	s_setprio 1
	v_mfma_f32_16x16x32_bf16 v[118:121], v[146:149], v[184:187], 0
	v_mfma_f32_16x16x32_bf16 v[114:117], v[154:157], v[184:187], 0
	v_mfma_f32_16x16x32_bf16 v[102:105], v[146:149], v[216:219], 0
	v_mfma_f32_16x16x32_bf16 v[98:101], v[154:157], v[216:219], 0
	v_mfma_f32_16x16x32_bf16 v[86:89], v[146:149], v[224:227], 0
	v_mfma_f32_16x16x32_bf16 v[82:85], v[154:157], v[224:227], 0
	v_mfma_f32_16x16x32_bf16 v[70:73], v[146:149], v[232:235], 0
	v_mfma_f32_16x16x32_bf16 v[66:69], v[154:157], v[232:235], 0
	v_mfma_f32_16x16x32_bf16 v[118:121], v[150:153], v[212:215], v[118:121]
	v_mfma_f32_16x16x32_bf16 v[114:117], v[158:161], v[212:215], v[114:117]
	v_mfma_f32_16x16x32_bf16 v[102:105], v[150:153], v[220:223], v[102:105]
	v_mfma_f32_16x16x32_bf16 v[98:101], v[158:161], v[220:223], v[98:101]
	v_mfma_f32_16x16x32_bf16 v[86:89], v[150:153], v[228:231], v[86:89]
	v_mfma_f32_16x16x32_bf16 v[82:85], v[158:161], v[228:231], v[82:85]
	v_mfma_f32_16x16x32_bf16 v[70:73], v[150:153], v[236:239], v[70:73]
	v_mfma_f32_16x16x32_bf16 v[66:69], v[158:161], v[236:239], v[66:69]
	s_setprio 0
	s_barrier
	s_add_i32 s0, s85, s67
	v_lshl_add_u64 v[188:189], s[72:73], 0, v[162:163]
	s_mov_b32 m0, s0
	ds_read_b128 v[184:187], v209 offset:16384
	ds_read_b128 v[212:215], v209 offset:17408
	ds_read_b128 v[216:219], v209 offset:18432
	ds_read_b128 v[220:223], v209 offset:19456
	ds_read_b128 v[224:227], v209 offset:20480
	ds_read_b128 v[228:231], v209 offset:21504
	ds_read_b128 v[232:235], v209 offset:22528
	ds_read_b128 v[236:239], v209 offset:23552
	global_load_lds_dwordx4 v[188:189], off
	s_add_i32 m0, s0, 0x2000
	s_add_u32 s0, s72, 0xb0000
	v_lshl_add_u64 v[240:241], s[72:73], 0, v[168:169]
	s_addc_u32 s1, s73, 0
	s_add_i32 s2, s86, s67
	global_load_lds_dwordx4 v[240:241], off
	v_lshl_add_u64 v[242:243], s[0:1], 0, v[162:163]
	s_mov_b32 m0, s2
	v_lshl_add_u64 v[244:245], s[76:77], 0, v[166:167]
	global_load_lds_dwordx4 v[242:243], off
	v_lshl_add_u64 v[242:243], s[0:1], 0, v[168:169]
	s_add_i32 m0, s2, 0x2000
	s_nop 0
	global_load_lds_dwordx4 v[242:243], off
	v_lshl_add_u64 v[242:243], s[76:77], 0, v[164:165]
	s_mov_b32 m0, s78
	s_nop 0
	global_load_lds_dwordx4 v[242:243], off
	s_mov_b32 m0, s79
	s_nop 0
	global_load_lds_dwordx4 v[244:245], off
	s_waitcnt vmcnt(8)
	s_waitcnt lgkmcnt(0)
	s_barrier
; #define PG8_STAGE(bufoff, gbase, voff) do { _Pragma("unroll") for (int _i = 0; _i < 2; ++_i) \
;         __builtin_amdgcn_global_load_lds((const unsigned*)((const char*)(gbase) + (voff)[_i]), (PG8_LAS unsigned*)(lds + (bufoff) + ldsw + _i * 8192), 16, 0, 0); } while (0)
; #define PG8_LDA(dst, b, h) do { _Pragma("unroll") for (int m = 0; m < 4; ++m) _Pragma("unroll") for (int k = 0; k < 2; ++k) dst[m][k] = *(const PG8_LAS bf16x8*)(lds + PG8_SA(b, h) + aoff + m * 2048 + k * 1024); } while (0)
; #define PG8_LDB(dst, b, h) do { _Pragma("unroll") for (int n = 0; n < 2; ++n) _Pragma("unroll") for (int k = 0; k < 2; ++k) dst[n][k] = *(const PG8_LAS bf16x8*)(lds + PG8_SB(b, h) + boff + n * 2048 + k * 1024); } while (0)
; #define PG8_MMA(ai, bj, At, Bt) do { __builtin_amdgcn_s_setprio(1); _Pragma("unroll") for (int m = 0; m < 4; ++m) _Pragma("unroll") for (int n = 0; n < 2; ++n) _Pragma("unroll") for (int k = 0; k < 2; ++k) \
;         acc[ai][bj][m][n] = __builtin_amdgcn_mfma_f32_16x16x32_bf16(Bt[n][k], At[m][k], acc[ai][bj][m][n], 0, 0, 0); __builtin_amdgcn_s_setprio(0); } while (0)
; #define PG8_WAIT_V(n) asm volatile("s_waitcnt vmcnt(" #n ")" ::: "memory")
; #define PG8_WAIT_L(n) asm volatile("s_waitcnt lgkmcnt(" #n ")" ::: "memory")
; #define PG8_BAR __builtin_amdgcn_s_barrier()
; #define PG8_SCHED __builtin_amdgcn_sched_barrier(0)
; template <class Epi, class Sched, bool ALIGN_EPI = false, bool SP2 = false>
; __device__ __forceinline__ void gemm_phase(PG8_LAS unsigned char* lds, const Gemm g, const Sched& S, const Epi& E) {
;     ...
;             PG8_WAIT_V(8); PG8_WAIT_L(0); PG8_BAR; PG8_MMA(1, 0, At, B0); PG8_MMA(1, 1, At, B1); PG8_BAR; PG8_SCHED;
;             PG8_LDB(B0, 1, 0); PG8_LDB(B1, 1, 1); PG8_SCHED; PG8_LDA(At, 1, 0); PG8_STAGE(PG8_SA(0, 1), a2 + hstepA, voffA);
;             PG8_WAIT_V(8); PG8_WAIT_L(0); PG8_BAR; PG8_MMA(0, 0, At, B0); PG8_MMA(0, 1, At, B1); PG8_BAR; PG8_SCHED;
	s_setprio 1
	s_waitcnt lgkmcnt(0)
	v_mfma_f32_16x16x32_bf16 v[62:65], v[130:133], v[184:187], 0
	v_mfma_f32_16x16x32_bf16 v[58:61], v[138:141], v[184:187], 0
	v_mfma_f32_16x16x32_bf16 v[46:49], v[130:133], v[216:219], 0
	v_mfma_f32_16x16x32_bf16 v[42:45], v[138:141], v[216:219], 0
	v_mfma_f32_16x16x32_bf16 v[30:33], v[130:133], v[224:227], 0
	v_mfma_f32_16x16x32_bf16 v[26:29], v[138:141], v[224:227], 0
	v_mfma_f32_16x16x32_bf16 v[14:17], v[130:133], v[232:235], 0
	v_mfma_f32_16x16x32_bf16 v[10:13], v[138:141], v[232:235], 0
	v_mfma_f32_16x16x32_bf16 v[62:65], v[134:137], v[212:215], v[62:65]
	v_mfma_f32_16x16x32_bf16 v[58:61], v[142:145], v[212:215], v[58:61]
	v_mfma_f32_16x16x32_bf16 v[46:49], v[134:137], v[220:223], v[46:49]
	v_mfma_f32_16x16x32_bf16 v[42:45], v[142:145], v[220:223], v[42:45]
	v_mfma_f32_16x16x32_bf16 v[30:33], v[134:137], v[228:231], v[30:33]
	v_mfma_f32_16x16x32_bf16 v[26:29], v[142:145], v[228:231], v[26:29]
	v_mfma_f32_16x16x32_bf16 v[14:17], v[134:137], v[236:239], v[14:17]
	v_mfma_f32_16x16x32_bf16 v[10:13], v[142:145], v[236:239], v[10:13]
	s_setprio 0
	s_setprio 1
	v_mfma_f32_16x16x32_bf16 v[54:57], v[146:149], v[184:187], 0
	v_mfma_f32_16x16x32_bf16 v[50:53], v[154:157], v[184:187], 0
	v_mfma_f32_16x16x32_bf16 v[38:41], v[146:149], v[216:219], 0
	v_mfma_f32_16x16x32_bf16 v[34:37], v[154:157], v[216:219], 0
	v_mfma_f32_16x16x32_bf16 v[22:25], v[146:149], v[224:227], 0
	v_mfma_f32_16x16x32_bf16 v[18:21], v[154:157], v[224:227], 0
	v_mfma_f32_16x16x32_bf16 v[6:9], v[146:149], v[232:235], 0
	v_mfma_f32_16x16x32_bf16 v[2:5], v[154:157], v[232:235], 0
	v_mfma_f32_16x16x32_bf16 v[54:57], v[150:153], v[212:215], v[54:57]
	v_mfma_f32_16x16x32_bf16 v[50:53], v[158:161], v[212:215], v[50:53]
	v_mfma_f32_16x16x32_bf16 v[38:41], v[150:153], v[220:223], v[38:41]
	v_mfma_f32_16x16x32_bf16 v[34:37], v[158:161], v[220:223], v[34:37]
	v_mfma_f32_16x16x32_bf16 v[22:25], v[150:153], v[228:231], v[22:25]
	v_mfma_f32_16x16x32_bf16 v[18:21], v[158:161], v[228:231], v[18:21]
	v_mfma_f32_16x16x32_bf16 v[6:9], v[150:153], v[236:239], v[6:9]
	v_mfma_f32_16x16x32_bf16 v[2:5], v[158:161], v[236:239], v[2:5]
	s_setprio 0
	s_barrier
	ds_read_b128 v[130:133], v210
	ds_read_b128 v[134:137], v210 offset:1024
	ds_read_b128 v[138:141], v210 offset:2048
	ds_read_b128 v[142:145], v210 offset:3072
	ds_read_b128 v[146:149], v211
	ds_read_b128 v[150:153], v211 offset:1024
	ds_read_b128 v[154:157], v211 offset:2048
	ds_read_b128 v[158:161], v211 offset:3072
	s_add_u32 s0, s76, 0xb0000
	s_addc_u32 s1, s77, 0
	s_mov_b32 m0, s80
	v_lshl_add_u64 v[246:247], s[0:1], 0, v[164:165]
	ds_read_b128 v[184:187], v209 offset:32768
	ds_read_b128 v[212:215], v209 offset:33792
	ds_read_b128 v[216:219], v209 offset:34816
	ds_read_b128 v[220:223], v209 offset:35840
	ds_read_b128 v[224:227], v209 offset:36864
	ds_read_b128 v[228:231], v209 offset:37888
	ds_read_b128 v[232:235], v209 offset:38912
	ds_read_b128 v[236:239], v209 offset:39936
	global_load_lds_dwordx4 v[246:247], off
	v_lshl_add_u64 v[246:247], s[0:1], 0, v[166:167]
	s_mov_b32 m0, s81
	s_nop 0
	global_load_lds_dwordx4 v[246:247], off
	s_waitcnt vmcnt(8)
	s_waitcnt lgkmcnt(0)
	s_barrier
	s_setprio 1
	s_waitcnt lgkmcnt(0)
	v_mfma_f32_16x16x32_bf16 v[126:129], v[130:133], v[184:187], v[126:129]
	v_mfma_f32_16x16x32_bf16 v[122:125], v[138:141], v[184:187], v[122:125]
	v_mfma_f32_16x16x32_bf16 v[110:113], v[130:133], v[216:219], v[110:113]
	v_mfma_f32_16x16x32_bf16 v[106:109], v[138:141], v[216:219], v[106:109]
	v_mfma_f32_16x16x32_bf16 v[94:97], v[130:133], v[224:227], v[94:97]
	v_mfma_f32_16x16x32_bf16 v[90:93], v[138:141], v[224:227], v[90:93]
	v_mfma_f32_16x16x32_bf16 v[78:81], v[130:133], v[232:235], v[78:81]
	v_mfma_f32_16x16x32_bf16 v[74:77], v[138:141], v[232:235], v[74:77]
	v_mfma_f32_16x16x32_bf16 v[126:129], v[134:137], v[212:215], v[126:129]
	v_mfma_f32_16x16x32_bf16 v[122:125], v[142:145], v[212:215], v[122:125]
	v_mfma_f32_16x16x32_bf16 v[110:113], v[134:137], v[220:223], v[110:113]
	v_mfma_f32_16x16x32_bf16 v[106:109], v[142:145], v[220:223], v[106:109]
	v_mfma_f32_16x16x32_bf16 v[94:97], v[134:137], v[228:231], v[94:97]
	v_mfma_f32_16x16x32_bf16 v[90:93], v[142:145], v[228:231], v[90:93]
	v_mfma_f32_16x16x32_bf16 v[78:81], v[134:137], v[236:239], v[78:81]
	v_mfma_f32_16x16x32_bf16 v[74:77], v[142:145], v[236:239], v[74:77]
	s_setprio 0
	s_setprio 1
	v_mfma_f32_16x16x32_bf16 v[118:121], v[146:149], v[184:187], v[118:121]
	v_mfma_f32_16x16x32_bf16 v[114:117], v[154:157], v[184:187], v[114:117]
	v_mfma_f32_16x16x32_bf16 v[102:105], v[146:149], v[216:219], v[102:105]
	v_mfma_f32_16x16x32_bf16 v[98:101], v[154:157], v[216:219], v[98:101]
	v_mfma_f32_16x16x32_bf16 v[86:89], v[146:149], v[224:227], v[86:89]
	v_mfma_f32_16x16x32_bf16 v[82:85], v[154:157], v[224:227], v[82:85]
	v_mfma_f32_16x16x32_bf16 v[70:73], v[146:149], v[232:235], v[70:73]
	v_mfma_f32_16x16x32_bf16 v[66:69], v[154:157], v[232:235], v[66:69]
	v_mfma_f32_16x16x32_bf16 v[118:121], v[150:153], v[212:215], v[118:121]
	v_mfma_f32_16x16x32_bf16 v[114:117], v[158:161], v[212:215], v[114:117]
	v_mfma_f32_16x16x32_bf16 v[102:105], v[150:153], v[220:223], v[102:105]
	v_mfma_f32_16x16x32_bf16 v[98:101], v[158:161], v[220:223], v[98:101]
	v_mfma_f32_16x16x32_bf16 v[86:89], v[150:153], v[228:231], v[86:89]
	v_mfma_f32_16x16x32_bf16 v[82:85], v[158:161], v[228:231], v[82:85]
	v_mfma_f32_16x16x32_bf16 v[70:73], v[150:153], v[236:239], v[70:73]
	v_mfma_f32_16x16x32_bf16 v[66:69], v[158:161], v[236:239], v[66:69]
	s_setprio 0
	s_barrier
; #define PG8_STAGE(bufoff, gbase, voff) do { _Pragma("unroll") for (int _i = 0; _i < 2; ++_i) \
;         __builtin_amdgcn_global_load_lds((const unsigned*)((const char*)(gbase) + (voff)[_i]), (PG8_LAS unsigned*)(lds + (bufoff) + ldsw + _i * 8192), 16, 0, 0); } while (0)
; #define PG8_LDA(dst, b, h) do { _Pragma("unroll") for (int m = 0; m < 4; ++m) _Pragma("unroll") for (int k = 0; k < 2; ++k) dst[m][k] = *(const PG8_LAS bf16x8*)(lds + PG8_SA(b, h) + aoff + m * 2048 + k * 1024); } while (0)
; #define PG8_MMA(ai, bj, At, Bt) do { __builtin_amdgcn_s_setprio(1); _Pragma("unroll") for (int m = 0; m < 4; ++m) _Pragma("unroll") for (int n = 0; n < 2; ++n) _Pragma("unroll") for (int k = 0; k < 2; ++k) \
;         acc[ai][bj][m][n] = __builtin_amdgcn_mfma_f32_16x16x32_bf16(Bt[n][k], At[m][k], acc[ai][bj][m][n], 0, 0, 0); __builtin_amdgcn_s_setprio(0); } while (0)
; #define PG8_WAIT_V(n) asm volatile("s_waitcnt vmcnt(" #n ")" ::: "memory")
; #define PG8_WAIT_L(n) asm volatile("s_waitcnt lgkmcnt(" #n ")" ::: "memory")
; #define PG8_BAR __builtin_amdgcn_s_barrier()
; #define PG8_SCHED __builtin_amdgcn_sched_barrier(0)
; template <class Epi, class Sched, bool ALIGN_EPI = false, bool SP2 = false>
; __device__ __forceinline__ void gemm_phase(PG8_LAS unsigned char* lds, const Gemm g, const Sched& S, const Epi& E) {
;     ...
;         for (int t = 0; t < nt; t += 2) {
;             const bool last = (t == nt - 2);
;     ...
;             PG8_LDA(At, 1, 1); PG8_STAGE(PG8_SB(1, 0), b3, voffB); PG8_STAGE(PG8_SB(1, 1), b3 + hstepB, voffB); PG8_STAGE(PG8_SA(1, 0), a3, voffA);
;             PG8_WAIT_V(8); PG8_WAIT_L(0); PG8_BAR; PG8_MMA(1, 0, At, B0); PG8_MMA(1, 1, At, B1); PG8_BAR; PG8_SCHED;
	s_add_i32 s0, s87, s67
	v_lshl_add_u64 v[188:189], v[188:189], 0, s[36:37]
	s_mov_b32 m0, s0
	ds_read_b128 v[184:187], v209 offset:49152
	ds_read_b128 v[212:215], v209 offset:50176
	ds_read_b128 v[216:219], v209 offset:51200
	ds_read_b128 v[220:223], v209 offset:52224
	ds_read_b128 v[224:227], v209 offset:53248
	ds_read_b128 v[228:231], v209 offset:54272
	ds_read_b128 v[232:235], v209 offset:55296
	ds_read_b128 v[236:239], v209 offset:56320
	global_load_lds_dwordx4 v[188:189], off
	s_add_i32 m0, s0, 0x2000
	s_add_u32 s0, s72, 0xb0080
	v_lshl_add_u64 v[188:189], v[240:241], 0, s[36:37]
	s_addc_u32 s1, s73, 0
	s_add_i32 s2, s88, s67
	global_load_lds_dwordx4 v[188:189], off
	v_lshl_add_u64 v[188:189], s[0:1], 0, v[162:163]
	s_mov_b32 m0, s2
	s_nop 0
	global_load_lds_dwordx4 v[188:189], off
	v_lshl_add_u64 v[188:189], s[0:1], 0, v[168:169]
	s_add_i32 m0, s2, 0x2000
	s_nop 0
	global_load_lds_dwordx4 v[188:189], off
	v_lshl_add_u64 v[188:189], v[242:243], 0, s[36:37]
	s_mov_b32 m0, s82
	s_nop 0
	global_load_lds_dwordx4 v[188:189], off
	v_lshl_add_u64 v[188:189], v[244:245], 0, s[36:37]
	s_mov_b32 m0, s83
	s_nop 0
	global_load_lds_dwordx4 v[188:189], off
	s_waitcnt vmcnt(8)
	s_waitcnt lgkmcnt(0)
	s_barrier
	s_setprio 1
	s_waitcnt lgkmcnt(0)
	v_mfma_f32_16x16x32_bf16 v[62:65], v[130:133], v[184:187], v[62:65]
	v_mfma_f32_16x16x32_bf16 v[58:61], v[138:141], v[184:187], v[58:61]
	v_mfma_f32_16x16x32_bf16 v[46:49], v[130:133], v[216:219], v[46:49]
	v_mfma_f32_16x16x32_bf16 v[42:45], v[138:141], v[216:219], v[42:45]
	v_mfma_f32_16x16x32_bf16 v[30:33], v[130:133], v[224:227], v[30:33]
	v_mfma_f32_16x16x32_bf16 v[26:29], v[138:141], v[224:227], v[26:29]
	v_mfma_f32_16x16x32_bf16 v[14:17], v[130:133], v[232:235], v[14:17]
	v_mfma_f32_16x16x32_bf16 v[10:13], v[138:141], v[232:235], v[10:13]
	v_mfma_f32_16x16x32_bf16 v[62:65], v[134:137], v[212:215], v[62:65]
	v_mfma_f32_16x16x32_bf16 v[58:61], v[142:145], v[212:215], v[58:61]
	v_mfma_f32_16x16x32_bf16 v[46:49], v[134:137], v[220:223], v[46:49]
	v_mfma_f32_16x16x32_bf16 v[42:45], v[142:145], v[220:223], v[42:45]
	v_mfma_f32_16x16x32_bf16 v[30:33], v[134:137], v[228:231], v[30:33]
	v_mfma_f32_16x16x32_bf16 v[26:29], v[142:145], v[228:231], v[26:29]
	v_mfma_f32_16x16x32_bf16 v[14:17], v[134:137], v[236:239], v[14:17]
	v_mfma_f32_16x16x32_bf16 v[10:13], v[142:145], v[236:239], v[10:13]
	s_setprio 0
	s_setprio 1
	v_mfma_f32_16x16x32_bf16 v[54:57], v[146:149], v[184:187], v[54:57]
	v_mfma_f32_16x16x32_bf16 v[50:53], v[154:157], v[184:187], v[50:53]
	v_mfma_f32_16x16x32_bf16 v[38:41], v[146:149], v[216:219], v[38:41]
	v_mfma_f32_16x16x32_bf16 v[34:37], v[154:157], v[216:219], v[34:37]
	v_mfma_f32_16x16x32_bf16 v[22:25], v[146:149], v[224:227], v[22:25]
	v_mfma_f32_16x16x32_bf16 v[18:21], v[154:157], v[224:227], v[18:21]
	v_mfma_f32_16x16x32_bf16 v[6:9], v[146:149], v[232:235], v[6:9]
	v_mfma_f32_16x16x32_bf16 v[2:5], v[154:157], v[232:235], v[2:5]
	v_mfma_f32_16x16x32_bf16 v[54:57], v[150:153], v[212:215], v[54:57]
	v_mfma_f32_16x16x32_bf16 v[50:53], v[158:161], v[212:215], v[50:53]
	v_mfma_f32_16x16x32_bf16 v[38:41], v[150:153], v[220:223], v[38:41]
	v_mfma_f32_16x16x32_bf16 v[34:37], v[158:161], v[220:223], v[34:37]
	v_mfma_f32_16x16x32_bf16 v[22:25], v[150:153], v[228:231], v[22:25]
	v_mfma_f32_16x16x32_bf16 v[18:21], v[158:161], v[228:231], v[18:21]
	v_mfma_f32_16x16x32_bf16 v[6:9], v[150:153], v[236:239], v[6:9]
	v_mfma_f32_16x16x32_bf16 v[2:5], v[158:161], v[236:239], v[2:5]
	s_setprio 0
	s_barrier
	s_add_i32 s7, s7, 2
	s_add_u32 s4, s4, 0x100
	s_addc_u32 s5, s5, 0
	s_cmp_gt_u32 s7, 41
	s_mov_b64 s[68:69], s[70:71]

;     __device__ __forceinline__ bool next(int i, Unit& u) const { if (!S.next(i, u)) return false; if (u.pn >= 4) u.pn += 2; return true; }
; #define PG8_STAGE(bufoff, gbase, voff) do { _Pragma("unroll") for (int _i = 0; _i < 2; ++_i) \
;         __builtin_amdgcn_global_load_lds((const unsigned*)((const char*)(gbase) + (voff)[_i]), (PG8_LAS unsigned*)(lds + (bufoff) + ldsw + _i * 8192), 16, 0, 0); } while (0)
; #define PG8_LDA(dst, b, h) do { _Pragma("unroll") for (int m = 0; m < 4; ++m) _Pragma("unroll") for (int k = 0; k < 2; ++k) dst[m][k] = *(const PG8_LAS bf16x8*)(lds + PG8_SA(b, h) + aoff + m * 2048 + k * 1024); } while (0)
; #define PG8_LDB(dst, b, h) do { _Pragma("unroll") for (int n = 0; n < 2; ++n) _Pragma("unroll") for (int k = 0; k < 2; ++k) dst[n][k] = *(const PG8_LAS bf16x8*)(lds + PG8_SB(b, h) + boff + n * 2048 + k * 1024); } while (0)
; template <class Epi, class Sched, bool ALIGN_EPI = false, bool SP2 = false>
; __device__ __forceinline__ void gemm_phase(PG8_LAS unsigned char* lds, const Gemm g, const Sched& S, const Epi& E) {
;     ...
;         const bool has_next = S.next(ui + 1, nxt);
;         if constexpr (Epi::LDS_PF) { if (has_next) E.prefetch(nxt, lds + STAGE_BYTES + ((ui + 1) % 3) * 4096, wid, lane); }
;         const char* nA = has_next ? (const char*)g.A + (size_t)nxt.pm * tstepA : cA; const char* nB = has_next ? (const char*)g.Bt + (size_t)nxt.pn * tstepB : cB;
;         for (int t = 0; t < nt; t += 2) {
;             const bool last = (t == nt - 2);
;             const char* a1 = cA + (size_t)(t + 1) * kstep;
;             const char* a2 = last ? nA : cA + (size_t)(t + 2) * kstep; const char* b2 = last ? nB : cB + (size_t)(t + 2) * kstep;
;             const char* a3 = a2 + kstep; const char* b3 = b2 + kstep;
;             if (last && has_next) S.a_ready(nxt);
;             if constexpr (SP2) {
;             PG8_LDB(B0, 0, 0); PG8_LDB(B1, 0, 1); PG8_SCHED; PG8_LDA(At, 0, 0); PG8_STAGE(PG8_SA(1, 1), a1 + hstepA, voffA);
;             PG8_WAIT_V(8); PG8_WAIT_L(0); PG8_BAR; PG8_MMA(0, 0, At, B0); PG8_MMA(0, 1, At, B1); PG8_BAR; PG8_SCHED;
;             PG8_LDA(At, 0, 1); PG8_STAGE(PG8_SB(0, 0), b2, voffB); PG8_STAGE(PG8_SB(0, 1), b2 + hstepB, voffB); PG8_STAGE(PG8_SA(0, 0), a2, voffA);
;             PG8_WAIT_V(8); PG8_WAIT_L(0); PG8_BAR; PG8_MMA(1, 0, At, B0); PG8_MMA(1, 1, At, B1); PG8_BAR; PG8_SCHED;
.LBB0_1341:
	s_mov_b32 s36, s0
	s_ashr_i32 s37, s0, 31
	s_mov_b32 s38, s1
	s_lshl_b64 s[0:1], s[36:37], 19
	v_readlane_b32 s4, v253, 23
	v_readlane_b32 s5, v253, 24
	s_add_u32 s42, s4, s0
	s_addc_u32 s43, s5, s1
	s_and_b64 s[0:1], s[40:41], exec
	s_cselect_b32 s4, s43, s51
	s_cselect_b32 s5, s42, s50
	s_ashr_i32 s39, s38, 31
	s_lshl_b64 s[0:1], s[38:39], 19
	s_add_u32 s44, s34, s0
	s_addc_u32 s45, s35, s1
	s_and_b64 s[0:1], s[40:41], exec
	s_cselect_b32 s18, s45, s67
	s_cselect_b32 s19, s44, s66
	s_add_u32 s50, s50, 0x40080
	s_addc_u32 s51, s51, 0
	s_add_u32 s37, s66, 0x100
	s_addc_u32 s39, s67, 0
	s_mov_b32 s79, -2
	ds_read_b128 v[144:147], v150
	ds_read_b128 v[156:159], v150 offset:1024
	ds_read_b128 v[160:163], v150 offset:2048
	ds_read_b128 v[164:167], v150 offset:3072
	ds_read_b128 v[168:171], v151
	ds_read_b128 v[172:175], v151 offset:1024
	ds_read_b128 v[176:179], v151 offset:2048
	ds_read_b128 v[180:183], v151 offset:3072
	s_add_u32 s0, s50, 0xfffc0080
	s_addc_u32 s1, s51, -1
	s_cmp_eq_u32 s79, 12
	s_cselect_b32 s69, s4, s1
	s_cselect_b32 s68, s5, s0
	s_cselect_b32 s67, s18, s39
	s_cselect_b32 s66, s19, s37
	v_lshl_add_u64 v[216:217], s[50:51], 0, v[138:139]
	s_add_i32 m0, s14, 0xc000
	ds_read_b128 v[184:187], v152
	ds_read_b128 v[188:191], v152 offset:1024
	ds_read_b128 v[192:195], v152 offset:2048
	ds_read_b128 v[196:199], v152 offset:3072
	ds_read_b128 v[200:203], v152 offset:4096
	ds_read_b128 v[204:207], v152 offset:5120
	ds_read_b128 v[208:211], v152 offset:6144
	ds_read_b128 v[212:215], v152 offset:7168
	global_load_lds_dwordx4 v[216:217], off
	v_lshl_add_u64 v[216:217], s[50:51], 0, v[140:141]
	s_add_i32 m0, s14, 0xe000
	s_nop 0
	global_load_lds_dwordx4 v[216:217], off
	s_waitcnt vmcnt(8)
	s_waitcnt lgkmcnt(0)
	s_barrier
	s_setprio 1
	s_waitcnt lgkmcnt(0)
	v_mfma_f32_16x16x32_bf16 v[126:129], v[144:147], v[184:187], 0
	v_mfma_f32_16x16x32_bf16 v[122:125], v[160:163], v[184:187], 0
	v_mfma_f32_16x16x32_bf16 v[118:121], v[144:147], v[192:195], 0
	v_mfma_f32_16x16x32_bf16 v[110:113], v[160:163], v[192:195], 0
	v_mfma_f32_16x16x32_bf16 v[102:105], v[144:147], v[200:203], 0
	v_mfma_f32_16x16x32_bf16 v[94:97], v[160:163], v[200:203], 0
	v_mfma_f32_16x16x32_bf16 v[86:89], v[144:147], v[208:211], 0
	v_mfma_f32_16x16x32_bf16 v[78:81], v[160:163], v[208:211], 0
	v_mfma_f32_16x16x32_bf16 v[126:129], v[156:159], v[188:191], v[126:129]
	v_mfma_f32_16x16x32_bf16 v[122:125], v[164:167], v[188:191], v[122:125]
	v_mfma_f32_16x16x32_bf16 v[118:121], v[156:159], v[196:199], v[118:121]
	v_mfma_f32_16x16x32_bf16 v[110:113], v[164:167], v[196:199], v[110:113]
	v_mfma_f32_16x16x32_bf16 v[102:105], v[156:159], v[204:207], v[102:105]
	v_mfma_f32_16x16x32_bf16 v[94:97], v[164:167], v[204:207], v[94:97]
	v_mfma_f32_16x16x32_bf16 v[86:89], v[156:159], v[212:215], v[86:89]
	v_mfma_f32_16x16x32_bf16 v[78:81], v[164:167], v[212:215], v[78:81]
	s_setprio 0
	s_setprio 1
	v_mfma_f32_16x16x32_bf16 v[114:117], v[168:171], v[184:187], 0
	v_mfma_f32_16x16x32_bf16 v[106:109], v[176:179], v[184:187], 0
	v_mfma_f32_16x16x32_bf16 v[98:101], v[168:171], v[192:195], 0
	v_mfma_f32_16x16x32_bf16 v[90:93], v[176:179], v[192:195], 0
	v_mfma_f32_16x16x32_bf16 v[82:85], v[168:171], v[200:203], 0
	v_mfma_f32_16x16x32_bf16 v[74:77], v[176:179], v[200:203], 0
	v_mfma_f32_16x16x32_bf16 v[70:73], v[168:171], v[208:211], 0
	v_mfma_f32_16x16x32_bf16 v[66:69], v[176:179], v[208:211], 0
	v_mfma_f32_16x16x32_bf16 v[114:117], v[172:175], v[188:191], v[114:117]
	v_mfma_f32_16x16x32_bf16 v[106:109], v[180:183], v[188:191], v[106:109]
	v_mfma_f32_16x16x32_bf16 v[98:101], v[172:175], v[196:199], v[98:101]
	v_mfma_f32_16x16x32_bf16 v[90:93], v[180:183], v[196:199], v[90:93]
	v_mfma_f32_16x16x32_bf16 v[82:85], v[172:175], v[204:207], v[82:85]
	v_mfma_f32_16x16x32_bf16 v[74:77], v[180:183], v[204:207], v[74:77]
	v_mfma_f32_16x16x32_bf16 v[70:73], v[172:175], v[212:215], v[70:73]
	v_mfma_f32_16x16x32_bf16 v[66:69], v[180:183], v[212:215], v[66:69]
	s_setprio 0
	s_barrier
	s_add_i32 s0, s75, s3
	v_lshl_add_u64 v[216:217], s[66:67], 0, v[134:135]
	s_mov_b32 m0, s0
	ds_read_b128 v[184:187], v152 offset:16384
	ds_read_b128 v[188:191], v152 offset:17408
	ds_read_b128 v[192:195], v152 offset:18432
	ds_read_b128 v[196:199], v152 offset:19456
	ds_read_b128 v[200:203], v152 offset:20480
	ds_read_b128 v[204:207], v152 offset:21504
	ds_read_b128 v[208:211], v152 offset:22528
	ds_read_b128 v[212:215], v152 offset:23552
	global_load_lds_dwordx4 v[216:217], off
	s_add_i32 m0, s0, 0x2000
	s_add_u32 s0, s66, 0x40000
	v_lshl_add_u64 v[218:219], s[66:67], 0, v[130:131]
	s_addc_u32 s1, s67, 0
	s_add_i32 s2, s76, s3
	global_load_lds_dwordx4 v[218:219], off
	v_lshl_add_u64 v[220:221], s[0:1], 0, v[134:135]
	s_mov_b32 m0, s2
	v_lshl_add_u64 v[222:223], s[68:69], 0, v[132:133]
	global_load_lds_dwordx4 v[220:221], off
	v_lshl_add_u64 v[220:221], s[0:1], 0, v[130:131]
	s_add_i32 m0, s2, 0x2000
	s_nop 0
	global_load_lds_dwordx4 v[220:221], off
	v_lshl_add_u64 v[220:221], s[68:69], 0, v[136:137]
	s_mov_b32 m0, s14
	s_nop 0
	global_load_lds_dwordx4 v[220:221], off
	s_mov_b32 m0, s15
	s_nop 0
	global_load_lds_dwordx4 v[222:223], off
	s_waitcnt vmcnt(8)
	s_waitcnt lgkmcnt(0)
	s_barrier
; #define PG8_STAGE(bufoff, gbase, voff) do { _Pragma("unroll") for (int _i = 0; _i < 2; ++_i) \
;         __builtin_amdgcn_global_load_lds((const unsigned*)((const char*)(gbase) + (voff)[_i]), (PG8_LAS unsigned*)(lds + (bufoff) + ldsw + _i * 8192), 16, 0, 0); } while (0)
; #define PG8_LDA(dst, b, h) do { _Pragma("unroll") for (int m = 0; m < 4; ++m) _Pragma("unroll") for (int k = 0; k < 2; ++k) dst[m][k] = *(const PG8_LAS bf16x8*)(lds + PG8_SA(b, h) + aoff + m * 2048 + k * 1024); } while (0)
; #define PG8_LDB(dst, b, h) do { _Pragma("unroll") for (int n = 0; n < 2; ++n) _Pragma("unroll") for (int k = 0; k < 2; ++k) dst[n][k] = *(const PG8_LAS bf16x8*)(lds + PG8_SB(b, h) + boff + n * 2048 + k * 1024); } while (0)
; #define PG8_MMA(ai, bj, At, Bt) do { __builtin_amdgcn_s_setprio(1); _Pragma("unroll") for (int m = 0; m < 4; ++m) _Pragma("unroll") for (int n = 0; n < 2; ++n) _Pragma("unroll") for (int k = 0; k < 2; ++k) \
;         acc[ai][bj][m][n] = __builtin_amdgcn_mfma_f32_16x16x32_bf16(Bt[n][k], At[m][k], acc[ai][bj][m][n], 0, 0, 0); __builtin_amdgcn_s_setprio(0); } while (0)
; #define PG8_WAIT_V(n) asm volatile("s_waitcnt vmcnt(" #n ")" ::: "memory")
; #define PG8_WAIT_L(n) asm volatile("s_waitcnt lgkmcnt(" #n ")" ::: "memory")
; #define PG8_BAR __builtin_amdgcn_s_barrier()
; #define PG8_SCHED __builtin_amdgcn_sched_barrier(0)
; template <class Epi, class Sched, bool ALIGN_EPI = false, bool SP2 = false>
; __device__ __forceinline__ void gemm_phase(PG8_LAS unsigned char* lds, const Gemm g, const Sched& S, const Epi& E) {
;     ...
;             PG8_WAIT_V(8); PG8_WAIT_L(0); PG8_BAR; PG8_MMA(1, 0, At, B0); PG8_MMA(1, 1, At, B1); PG8_BAR; PG8_SCHED;
;             PG8_LDB(B0, 1, 0); PG8_LDB(B1, 1, 1); PG8_SCHED; PG8_LDA(At, 1, 0); PG8_STAGE(PG8_SA(0, 1), a2 + hstepA, voffA);
;             PG8_WAIT_V(8); PG8_WAIT_L(0); PG8_BAR; PG8_MMA(0, 0, At, B0); PG8_MMA(0, 1, At, B1); PG8_BAR; PG8_SCHED;
	s_setprio 1
	s_waitcnt lgkmcnt(0)
	v_mfma_f32_16x16x32_bf16 v[62:65], v[144:147], v[184:187], 0
	v_mfma_f32_16x16x32_bf16 v[58:61], v[160:163], v[184:187], 0
	v_mfma_f32_16x16x32_bf16 v[54:57], v[144:147], v[192:195], 0
	v_mfma_f32_16x16x32_bf16 v[46:49], v[160:163], v[192:195], 0
	v_mfma_f32_16x16x32_bf16 v[38:41], v[144:147], v[200:203], 0
	v_mfma_f32_16x16x32_bf16 v[30:33], v[160:163], v[200:203], 0
	v_mfma_f32_16x16x32_bf16 v[22:25], v[144:147], v[208:211], 0
	v_mfma_f32_16x16x32_bf16 v[14:17], v[160:163], v[208:211], 0
	v_mfma_f32_16x16x32_bf16 v[62:65], v[156:159], v[188:191], v[62:65]
	v_mfma_f32_16x16x32_bf16 v[58:61], v[164:167], v[188:191], v[58:61]
	v_mfma_f32_16x16x32_bf16 v[54:57], v[156:159], v[196:199], v[54:57]
	v_mfma_f32_16x16x32_bf16 v[46:49], v[164:167], v[196:199], v[46:49]
	v_mfma_f32_16x16x32_bf16 v[38:41], v[156:159], v[204:207], v[38:41]
	v_mfma_f32_16x16x32_bf16 v[30:33], v[164:167], v[204:207], v[30:33]
	v_mfma_f32_16x16x32_bf16 v[22:25], v[156:159], v[212:215], v[22:25]
	v_mfma_f32_16x16x32_bf16 v[14:17], v[164:167], v[212:215], v[14:17]
	s_setprio 0
	s_setprio 1
	v_mfma_f32_16x16x32_bf16 v[50:53], v[168:171], v[184:187], 0
	v_mfma_f32_16x16x32_bf16 v[42:45], v[176:179], v[184:187], 0
	v_mfma_f32_16x16x32_bf16 v[34:37], v[168:171], v[192:195], 0
	v_mfma_f32_16x16x32_bf16 v[26:29], v[176:179], v[192:195], 0
	v_mfma_f32_16x16x32_bf16 v[18:21], v[168:171], v[200:203], 0
	v_mfma_f32_16x16x32_bf16 v[10:13], v[176:179], v[200:203], 0
	v_mfma_f32_16x16x32_bf16 v[6:9], v[168:171], v[208:211], 0
	v_mfma_f32_16x16x32_bf16 v[2:5], v[176:179], v[208:211], 0
	v_mfma_f32_16x16x32_bf16 v[50:53], v[172:175], v[188:191], v[50:53]
	v_mfma_f32_16x16x32_bf16 v[42:45], v[180:183], v[188:191], v[42:45]
	v_mfma_f32_16x16x32_bf16 v[34:37], v[172:175], v[196:199], v[34:37]
	v_mfma_f32_16x16x32_bf16 v[26:29], v[180:183], v[196:199], v[26:29]
	v_mfma_f32_16x16x32_bf16 v[18:21], v[172:175], v[204:207], v[18:21]
	v_mfma_f32_16x16x32_bf16 v[10:13], v[180:183], v[204:207], v[10:13]
	v_mfma_f32_16x16x32_bf16 v[6:9], v[172:175], v[212:215], v[6:9]
	v_mfma_f32_16x16x32_bf16 v[2:5], v[180:183], v[212:215], v[2:5]
	s_setprio 0
	s_barrier
	ds_read_b128 v[144:147], v153
	ds_read_b128 v[156:159], v153 offset:1024
	ds_read_b128 v[160:163], v153 offset:2048
	ds_read_b128 v[164:167], v153 offset:3072
	ds_read_b128 v[168:171], v154
	ds_read_b128 v[172:175], v154 offset:1024
	ds_read_b128 v[176:179], v154 offset:2048
	ds_read_b128 v[180:183], v154 offset:3072
	s_add_u32 s0, s68, 0x40000
	s_addc_u32 s1, s69, 0
	s_mov_b32 m0, s20
	v_lshl_add_u64 v[224:225], s[0:1], 0, v[136:137]
	ds_read_b128 v[184:187], v152 offset:32768
	ds_read_b128 v[188:191], v152 offset:33792
	ds_read_b128 v[192:195], v152 offset:34816
	ds_read_b128 v[196:199], v152 offset:35840
	ds_read_b128 v[200:203], v152 offset:36864
	ds_read_b128 v[204:207], v152 offset:37888
	ds_read_b128 v[208:211], v152 offset:38912
	ds_read_b128 v[212:215], v152 offset:39936
	global_load_lds_dwordx4 v[224:225], off
	v_lshl_add_u64 v[224:225], s[0:1], 0, v[132:133]
	s_mov_b32 m0, s21
	s_nop 0
	global_load_lds_dwordx4 v[224:225], off
	s_waitcnt vmcnt(8)
	s_waitcnt lgkmcnt(0)
	s_barrier
	s_setprio 1
	s_waitcnt lgkmcnt(0)
	v_mfma_f32_16x16x32_bf16 v[126:129], v[144:147], v[184:187], v[126:129]
	v_mfma_f32_16x16x32_bf16 v[122:125], v[160:163], v[184:187], v[122:125]
	v_mfma_f32_16x16x32_bf16 v[118:121], v[144:147], v[192:195], v[118:121]
	v_mfma_f32_16x16x32_bf16 v[110:113], v[160:163], v[192:195], v[110:113]
	v_mfma_f32_16x16x32_bf16 v[102:105], v[144:147], v[200:203], v[102:105]
	v_mfma_f32_16x16x32_bf16 v[94:97], v[160:163], v[200:203], v[94:97]
	v_mfma_f32_16x16x32_bf16 v[86:89], v[144:147], v[208:211], v[86:89]
	v_mfma_f32_16x16x32_bf16 v[78:81], v[160:163], v[208:211], v[78:81]
	v_mfma_f32_16x16x32_bf16 v[126:129], v[156:159], v[188:191], v[126:129]
	v_mfma_f32_16x16x32_bf16 v[122:125], v[164:167], v[188:191], v[122:125]
	v_mfma_f32_16x16x32_bf16 v[118:121], v[156:159], v[196:199], v[118:121]
	v_mfma_f32_16x16x32_bf16 v[110:113], v[164:167], v[196:199], v[110:113]
	v_mfma_f32_16x16x32_bf16 v[102:105], v[156:159], v[204:207], v[102:105]
	v_mfma_f32_16x16x32_bf16 v[94:97], v[164:167], v[204:207], v[94:97]
	v_mfma_f32_16x16x32_bf16 v[86:89], v[156:159], v[212:215], v[86:89]
	v_mfma_f32_16x16x32_bf16 v[78:81], v[164:167], v[212:215], v[78:81]
	s_setprio 0
	s_setprio 1
	v_mfma_f32_16x16x32_bf16 v[114:117], v[168:171], v[184:187], v[114:117]
	v_mfma_f32_16x16x32_bf16 v[106:109], v[176:179], v[184:187], v[106:109]
	v_mfma_f32_16x16x32_bf16 v[98:101], v[168:171], v[192:195], v[98:101]
	v_mfma_f32_16x16x32_bf16 v[90:93], v[176:179], v[192:195], v[90:93]
	v_mfma_f32_16x16x32_bf16 v[82:85], v[168:171], v[200:203], v[82:85]
	v_mfma_f32_16x16x32_bf16 v[74:77], v[176:179], v[200:203], v[74:77]
	v_mfma_f32_16x16x32_bf16 v[70:73], v[168:171], v[208:211], v[70:73]
	v_mfma_f32_16x16x32_bf16 v[66:69], v[176:179], v[208:211], v[66:69]
	v_mfma_f32_16x16x32_bf16 v[114:117], v[172:175], v[188:191], v[114:117]
	v_mfma_f32_16x16x32_bf16 v[106:109], v[180:183], v[188:191], v[106:109]
	v_mfma_f32_16x16x32_bf16 v[98:101], v[172:175], v[196:199], v[98:101]
	v_mfma_f32_16x16x32_bf16 v[90:93], v[180:183], v[196:199], v[90:93]
	v_mfma_f32_16x16x32_bf16 v[82:85], v[172:175], v[204:207], v[82:85]
	v_mfma_f32_16x16x32_bf16 v[74:77], v[180:183], v[204:207], v[74:77]
	v_mfma_f32_16x16x32_bf16 v[70:73], v[172:175], v[212:215], v[70:73]
	v_mfma_f32_16x16x32_bf16 v[66:69], v[180:183], v[212:215], v[66:69]
	s_setprio 0
	s_barrier
; #define PG8_STAGE(bufoff, gbase, voff) do { _Pragma("unroll") for (int _i = 0; _i < 2; ++_i) \
;         __builtin_amdgcn_global_load_lds((const unsigned*)((const char*)(gbase) + (voff)[_i]), (PG8_LAS unsigned*)(lds + (bufoff) + ldsw + _i * 8192), 16, 0, 0); } while (0)
; #define PG8_LDA(dst, b, h) do { _Pragma("unroll") for (int m = 0; m < 4; ++m) _Pragma("unroll") for (int k = 0; k < 2; ++k) dst[m][k] = *(const PG8_LAS bf16x8*)(lds + PG8_SA(b, h) + aoff + m * 2048 + k * 1024); } while (0)
; #define PG8_MMA(ai, bj, At, Bt) do { __builtin_amdgcn_s_setprio(1); _Pragma("unroll") for (int m = 0; m < 4; ++m) _Pragma("unroll") for (int n = 0; n < 2; ++n) _Pragma("unroll") for (int k = 0; k < 2; ++k) \
;         acc[ai][bj][m][n] = __builtin_amdgcn_mfma_f32_16x16x32_bf16(Bt[n][k], At[m][k], acc[ai][bj][m][n], 0, 0, 0); __builtin_amdgcn_s_setprio(0); } while (0)
; #define PG8_WAIT_V(n) asm volatile("s_waitcnt vmcnt(" #n ")" ::: "memory")
; #define PG8_WAIT_L(n) asm volatile("s_waitcnt lgkmcnt(" #n ")" ::: "memory")
; #define PG8_BAR __builtin_amdgcn_s_barrier()
; #define PG8_SCHED __builtin_amdgcn_sched_barrier(0)
; template <class Epi, class Sched, bool ALIGN_EPI = false, bool SP2 = false>
; __device__ __forceinline__ void gemm_phase(PG8_LAS unsigned char* lds, const Gemm g, const Sched& S, const Epi& E) {
;     ...
;         for (int t = 0; t < nt; t += 2) {
;             const bool last = (t == nt - 2);
;     ...
;             PG8_LDA(At, 1, 1); PG8_STAGE(PG8_SB(1, 0), b3, voffB); PG8_STAGE(PG8_SB(1, 1), b3 + hstepB, voffB); PG8_STAGE(PG8_SA(1, 0), a3, voffA);
;             PG8_WAIT_V(8); PG8_WAIT_L(0); PG8_BAR; PG8_MMA(1, 0, At, B0); PG8_MMA(1, 1, At, B1); PG8_BAR; PG8_SCHED;
	s_add_i32 s0, s77, s3
	v_lshl_add_u64 v[216:217], v[216:217], 0, s[8:9]
	s_mov_b32 m0, s0
	ds_read_b128 v[184:187], v152 offset:49152
	ds_read_b128 v[188:191], v152 offset:50176
	ds_read_b128 v[192:195], v152 offset:51200
	ds_read_b128 v[196:199], v152 offset:52224
	ds_read_b128 v[200:203], v152 offset:53248
	ds_read_b128 v[204:207], v152 offset:54272
	ds_read_b128 v[208:211], v152 offset:55296
	ds_read_b128 v[212:215], v152 offset:56320
	global_load_lds_dwordx4 v[216:217], off
	s_add_i32 m0, s0, 0x2000
	s_add_u32 s0, s66, 0x40080
	v_lshl_add_u64 v[216:217], v[218:219], 0, s[8:9]
	s_addc_u32 s1, s67, 0
	s_add_i32 s2, s78, s3
	global_load_lds_dwordx4 v[216:217], off
	v_lshl_add_u64 v[216:217], s[0:1], 0, v[134:135]
	s_mov_b32 m0, s2
	s_nop 0
	global_load_lds_dwordx4 v[216:217], off
	v_lshl_add_u64 v[216:217], s[0:1], 0, v[130:131]
	s_add_i32 m0, s2, 0x2000
	s_nop 0
	global_load_lds_dwordx4 v[216:217], off
	v_lshl_add_u64 v[216:217], v[220:221], 0, s[8:9]
	s_mov_b32 m0, s47
	s_nop 0
	global_load_lds_dwordx4 v[216:217], off
	v_lshl_add_u64 v[216:217], v[222:223], 0, s[8:9]
	s_mov_b32 m0, s49
	s_nop 0
	global_load_lds_dwordx4 v[216:217], off
	s_waitcnt vmcnt(8)
	s_waitcnt lgkmcnt(0)
	s_barrier
	s_setprio 1
	s_waitcnt lgkmcnt(0)
	v_mfma_f32_16x16x32_bf16 v[62:65], v[144:147], v[184:187], v[62:65]
	v_mfma_f32_16x16x32_bf16 v[58:61], v[160:163], v[184:187], v[58:61]
	v_mfma_f32_16x16x32_bf16 v[54:57], v[144:147], v[192:195], v[54:57]
	v_mfma_f32_16x16x32_bf16 v[46:49], v[160:163], v[192:195], v[46:49]
	v_mfma_f32_16x16x32_bf16 v[38:41], v[144:147], v[200:203], v[38:41]
	v_mfma_f32_16x16x32_bf16 v[30:33], v[160:163], v[200:203], v[30:33]
	v_mfma_f32_16x16x32_bf16 v[22:25], v[144:147], v[208:211], v[22:25]
	v_mfma_f32_16x16x32_bf16 v[14:17], v[160:163], v[208:211], v[14:17]
	v_mfma_f32_16x16x32_bf16 v[62:65], v[156:159], v[188:191], v[62:65]
	v_mfma_f32_16x16x32_bf16 v[58:61], v[164:167], v[188:191], v[58:61]
	v_mfma_f32_16x16x32_bf16 v[54:57], v[156:159], v[196:199], v[54:57]
	v_mfma_f32_16x16x32_bf16 v[46:49], v[164:167], v[196:199], v[46:49]
	v_mfma_f32_16x16x32_bf16 v[38:41], v[156:159], v[204:207], v[38:41]
	v_mfma_f32_16x16x32_bf16 v[30:33], v[164:167], v[204:207], v[30:33]
	v_mfma_f32_16x16x32_bf16 v[22:25], v[156:159], v[212:215], v[22:25]
	v_mfma_f32_16x16x32_bf16 v[14:17], v[164:167], v[212:215], v[14:17]
	s_setprio 0
	s_setprio 1
	v_mfma_f32_16x16x32_bf16 v[50:53], v[168:171], v[184:187], v[50:53]
	v_mfma_f32_16x16x32_bf16 v[42:45], v[176:179], v[184:187], v[42:45]
	v_mfma_f32_16x16x32_bf16 v[34:37], v[168:171], v[192:195], v[34:37]
	v_mfma_f32_16x16x32_bf16 v[26:29], v[176:179], v[192:195], v[26:29]
	v_mfma_f32_16x16x32_bf16 v[18:21], v[168:171], v[200:203], v[18:21]
	v_mfma_f32_16x16x32_bf16 v[10:13], v[176:179], v[200:203], v[10:13]
	v_mfma_f32_16x16x32_bf16 v[6:9], v[168:171], v[208:211], v[6:9]
	v_mfma_f32_16x16x32_bf16 v[2:5], v[176:179], v[208:211], v[2:5]
	v_mfma_f32_16x16x32_bf16 v[50:53], v[172:175], v[188:191], v[50:53]
	v_mfma_f32_16x16x32_bf16 v[42:45], v[180:183], v[188:191], v[42:45]
	v_mfma_f32_16x16x32_bf16 v[34:37], v[172:175], v[196:199], v[34:37]
	v_mfma_f32_16x16x32_bf16 v[26:29], v[180:183], v[196:199], v[26:29]
	v_mfma_f32_16x16x32_bf16 v[18:21], v[172:175], v[204:207], v[18:21]
	v_mfma_f32_16x16x32_bf16 v[10:13], v[180:183], v[204:207], v[10:13]
	v_mfma_f32_16x16x32_bf16 v[6:9], v[172:175], v[212:215], v[6:9]
	v_mfma_f32_16x16x32_bf16 v[2:5], v[180:183], v[212:215], v[2:5]
	s_setprio 0
	s_barrier
	s_add_i32 s79, s79, 2
	s_add_u32 s50, s50, 0x100
	s_addc_u32 s51, s51, 0
	s_add_u32 s37, s37, 0x100
	s_addc_u32 s39, s39, 0
	s_cmp_gt_u32 s79, 13

; #define PG8_STAGE(bufoff, gbase, voff) do { _Pragma("unroll") for (int _i = 0; _i < 2; ++_i) \
;         __builtin_amdgcn_global_load_lds((const unsigned*)((const char*)(gbase) + (voff)[_i]), (PG8_LAS unsigned*)(lds + (bufoff) + ldsw + _i * 8192), 16, 0, 0); } while (0)
; #define PG8_LDA(dst, b, h) do { _Pragma("unroll") for (int m = 0; m < 4; ++m) _Pragma("unroll") for (int k = 0; k < 2; ++k) dst[m][k] = *(const PG8_LAS bf16x8*)(lds + PG8_SA(b, h) + aoff + m * 2048 + k * 1024); } while (0)
; #define PG8_LDB(dst, b, h) do { _Pragma("unroll") for (int n = 0; n < 2; ++n) _Pragma("unroll") for (int k = 0; k < 2; ++k) dst[n][k] = *(const PG8_LAS bf16x8*)(lds + PG8_SB(b, h) + boff + n * 2048 + k * 1024); } while (0)
; #define PG8_WAIT_V(n) asm volatile("s_waitcnt vmcnt(" #n ")" ::: "memory")
; #define PG8_WAIT_L(n) asm volatile("s_waitcnt lgkmcnt(" #n ")" ::: "memory")
; #define PG8_BAR __builtin_amdgcn_s_barrier()
; template <class Epi, class Sched, bool ALIGN_EPI = false, bool SP2 = false>
; __device__ __forceinline__ void gemm_phase(PG8_LAS unsigned char* lds, const Gemm g, const Sched& S, const Epi& E) {
;     ...
;             const bool last = (t == nt - 2);
;             const char* a1 = cA + (size_t)(t + 1) * kstep;
;             const char* a2 = last ? nA : cA + (size_t)(t + 2) * kstep; const char* b2 = last ? nB : cB + (size_t)(t + 2) * kstep;
;             const char* a3 = a2 + kstep; const char* b3 = b2 + kstep;
;             if (last && has_next) S.a_ready(nxt);
;             if constexpr (SP2) {
;             PG8_LDB(B0, 0, 0); PG8_LDB(B1, 0, 1); PG8_SCHED; PG8_LDA(At, 0, 0); PG8_STAGE(PG8_SA(1, 1), a1 + hstepA, voffA);
;             PG8_WAIT_V(8); PG8_WAIT_L(0); PG8_BAR; PG8_MMA(0, 0, At, B0); PG8_MMA(0, 1, At, B1); PG8_BAR; PG8_SCHED;
;             PG8_LDA(At, 0, 1); PG8_STAGE(PG8_SB(0, 0), b2, voffB); PG8_STAGE(PG8_SB(0, 1), b2 + hstepB, voffB); PG8_STAGE(PG8_SA(0, 0), a2, voffA);
;             PG8_WAIT_V(8); PG8_WAIT_L(0); PG8_BAR; PG8_MMA(1, 0, At, B0); PG8_MMA(1, 1, At, B1); PG8_BAR; PG8_SCHED;
;     ...
; #pragma unroll
;         for (int a = 0; a < 2; ++a)
; #pragma unroll
;             for (int b = 0; b < 2; ++b)
; #pragma unroll
;                 for (int m = 0; m < 4; ++m)
; #pragma unroll
;                     for (int n = 0; n < 2; ++n) acc[a][b][m][n] = (f32x4){0.f, 0.f, 0.f, 0.f};
;         cur = nxt; cA = nA; cB = nB; ++ui;
.LBB0_1682:
	s_ashr_i32 s49, s48, 31
	s_lshl_b64 s[0:1], s[48:49], 19
	s_add_u32 s66, s26, s0
	s_addc_u32 s67, s27, s1
	s_and_b64 s[0:1], s[12:13], exec
	s_cselect_b32 s4, s67, s73
	s_cselect_b32 s5, s66, s72
	s_add_u32 s12, s70, 0x40080
	s_addc_u32 s13, s71, 0
	s_add_u32 s7, s72, 0x100
	s_addc_u32 s14, s73, 0
	s_mov_b32 s15, -2
	s_waitcnt vmcnt(0)
	ds_read_b128 v[130:133], v189
	ds_read_b128 v[134:137], v189 offset:1024
	ds_read_b128 v[138:141], v189 offset:2048
	ds_read_b128 v[142:145], v189 offset:3072
	ds_read_b128 v[168:171], v190
	ds_read_b128 v[194:197], v190 offset:1024
	ds_read_b128 v[198:201], v190 offset:2048
	ds_read_b128 v[202:205], v190 offset:3072
	s_add_u32 s0, s12, 0xfffc0080
	s_addc_u32 s1, s13, -1
	s_cmp_eq_u32 s15, 12
	s_cselect_b32 s73, s63, s1
	s_cselect_b32 s72, s62, s0
	s_cselect_b32 s71, s4, s14
	s_cselect_b32 s70, s5, s7
	v_lshl_add_u64 v[238:239], s[12:13], 0, v[160:161]
	s_add_i32 m0, s74, 0xc000
	ds_read_b128 v[206:209], v191
	ds_read_b128 v[210:213], v191 offset:1024
	ds_read_b128 v[214:217], v191 offset:2048
	ds_read_b128 v[218:221], v191 offset:3072
	ds_read_b128 v[222:225], v191 offset:4096
	ds_read_b128 v[226:229], v191 offset:5120
	ds_read_b128 v[230:233], v191 offset:6144
	ds_read_b128 v[234:237], v191 offset:7168
	global_load_lds_dwordx4 v[238:239], off
	v_lshl_add_u64 v[238:239], s[12:13], 0, v[162:163]
	s_add_i32 m0, s74, 0xe000
	s_nop 0
	global_load_lds_dwordx4 v[238:239], off
	s_waitcnt vmcnt(8)
	s_waitcnt lgkmcnt(0)
	s_barrier
	s_setprio 1
	s_waitcnt lgkmcnt(0)
	v_mfma_f32_16x16x32_bf16 v[126:129], v[130:133], v[206:209], 0
	v_mfma_f32_16x16x32_bf16 v[122:125], v[138:141], v[206:209], 0
	v_mfma_f32_16x16x32_bf16 v[110:113], v[130:133], v[214:217], 0
	v_mfma_f32_16x16x32_bf16 v[106:109], v[138:141], v[214:217], 0
	v_mfma_f32_16x16x32_bf16 v[94:97], v[130:133], v[222:225], 0
	v_mfma_f32_16x16x32_bf16 v[90:93], v[138:141], v[222:225], 0
	v_mfma_f32_16x16x32_bf16 v[78:81], v[130:133], v[230:233], 0
	v_mfma_f32_16x16x32_bf16 v[74:77], v[138:141], v[230:233], 0
	v_mfma_f32_16x16x32_bf16 v[126:129], v[134:137], v[210:213], v[126:129]
	v_mfma_f32_16x16x32_bf16 v[122:125], v[142:145], v[210:213], v[122:125]
	v_mfma_f32_16x16x32_bf16 v[110:113], v[134:137], v[218:221], v[110:113]
	v_mfma_f32_16x16x32_bf16 v[106:109], v[142:145], v[218:221], v[106:109]
	v_mfma_f32_16x16x32_bf16 v[94:97], v[134:137], v[226:229], v[94:97]
	v_mfma_f32_16x16x32_bf16 v[90:93], v[142:145], v[226:229], v[90:93]
	v_mfma_f32_16x16x32_bf16 v[78:81], v[134:137], v[234:237], v[78:81]
	v_mfma_f32_16x16x32_bf16 v[74:77], v[142:145], v[234:237], v[74:77]
	s_setprio 0
	s_setprio 1
	v_mfma_f32_16x16x32_bf16 v[118:121], v[168:171], v[206:209], 0
	v_mfma_f32_16x16x32_bf16 v[114:117], v[198:201], v[206:209], 0
	v_mfma_f32_16x16x32_bf16 v[102:105], v[168:171], v[214:217], 0
	v_mfma_f32_16x16x32_bf16 v[98:101], v[198:201], v[214:217], 0
	v_mfma_f32_16x16x32_bf16 v[86:89], v[168:171], v[222:225], 0
	v_mfma_f32_16x16x32_bf16 v[82:85], v[198:201], v[222:225], 0
	v_mfma_f32_16x16x32_bf16 v[70:73], v[168:171], v[230:233], 0
	v_mfma_f32_16x16x32_bf16 v[66:69], v[198:201], v[230:233], 0
	v_mfma_f32_16x16x32_bf16 v[118:121], v[194:197], v[210:213], v[118:121]
	v_mfma_f32_16x16x32_bf16 v[114:117], v[202:205], v[210:213], v[114:117]
	v_mfma_f32_16x16x32_bf16 v[102:105], v[194:197], v[218:221], v[102:105]
	v_mfma_f32_16x16x32_bf16 v[98:101], v[202:205], v[218:221], v[98:101]
	v_mfma_f32_16x16x32_bf16 v[86:89], v[194:197], v[226:229], v[86:89]
	v_mfma_f32_16x16x32_bf16 v[82:85], v[202:205], v[226:229], v[82:85]
	v_mfma_f32_16x16x32_bf16 v[70:73], v[194:197], v[234:237], v[70:73]
	v_mfma_f32_16x16x32_bf16 v[66:69], v[202:205], v[234:237], v[66:69]
	s_setprio 0
	s_barrier
	s_add_i32 s0, s80, s69
	v_lshl_add_u64 v[238:239], s[70:71], 0, v[146:147]
	s_mov_b32 m0, s0
	ds_read_b128 v[206:209], v191 offset:16384
	ds_read_b128 v[210:213], v191 offset:17408
	ds_read_b128 v[214:217], v191 offset:18432
	ds_read_b128 v[218:221], v191 offset:19456
	ds_read_b128 v[222:225], v191 offset:20480
	ds_read_b128 v[226:229], v191 offset:21504
	ds_read_b128 v[230:233], v191 offset:22528
	ds_read_b128 v[234:237], v191 offset:23552
	global_load_lds_dwordx4 v[238:239], off
	s_add_i32 m0, s0, 0x2000
	s_add_u32 s0, s70, 0x40000
	v_lshl_add_u64 v[240:241], s[70:71], 0, v[152:153]
	s_addc_u32 s1, s71, 0
	s_add_i32 s2, s81, s69
	global_load_lds_dwordx4 v[240:241], off
	v_lshl_add_u64 v[242:243], s[0:1], 0, v[146:147]
	s_mov_b32 m0, s2
	v_lshl_add_u64 v[244:245], s[72:73], 0, v[150:151]
	global_load_lds_dwordx4 v[242:243], off
	v_lshl_add_u64 v[242:243], s[0:1], 0, v[152:153]
	s_add_i32 m0, s2, 0x2000
	s_nop 0
	global_load_lds_dwordx4 v[242:243], off
	v_lshl_add_u64 v[242:243], s[72:73], 0, v[148:149]
	s_mov_b32 m0, s74
	s_nop 0
	global_load_lds_dwordx4 v[242:243], off
	s_mov_b32 m0, s75
	s_nop 0
	global_load_lds_dwordx4 v[244:245], off
	s_waitcnt vmcnt(8)
	s_waitcnt lgkmcnt(0)
	s_barrier
; #define PG8_STAGE(bufoff, gbase, voff) do { _Pragma("unroll") for (int _i = 0; _i < 2; ++_i) \
;         __builtin_amdgcn_global_load_lds((const unsigned*)((const char*)(gbase) + (voff)[_i]), (PG8_LAS unsigned*)(lds + (bufoff) + ldsw + _i * 8192), 16, 0, 0); } while (0)
; #define PG8_LDA(dst, b, h) do { _Pragma("unroll") for (int m = 0; m < 4; ++m) _Pragma("unroll") for (int k = 0; k < 2; ++k) dst[m][k] = *(const PG8_LAS bf16x8*)(lds + PG8_SA(b, h) + aoff + m * 2048 + k * 1024); } while (0)
; #define PG8_LDB(dst, b, h) do { _Pragma("unroll") for (int n = 0; n < 2; ++n) _Pragma("unroll") for (int k = 0; k < 2; ++k) dst[n][k] = *(const PG8_LAS bf16x8*)(lds + PG8_SB(b, h) + boff + n * 2048 + k * 1024); } while (0)
; #define PG8_MMA(ai, bj, At, Bt) do { __builtin_amdgcn_s_setprio(1); _Pragma("unroll") for (int m = 0; m < 4; ++m) _Pragma("unroll") for (int n = 0; n < 2; ++n) _Pragma("unroll") for (int k = 0; k < 2; ++k) \
;         acc[ai][bj][m][n] = __builtin_amdgcn_mfma_f32_16x16x32_bf16(Bt[n][k], At[m][k], acc[ai][bj][m][n], 0, 0, 0); __builtin_amdgcn_s_setprio(0); } while (0)
; #define PG8_WAIT_V(n) asm volatile("s_waitcnt vmcnt(" #n ")" ::: "memory")
; #define PG8_WAIT_L(n) asm volatile("s_waitcnt lgkmcnt(" #n ")" ::: "memory")
; #define PG8_BAR __builtin_amdgcn_s_barrier()
; template <class Epi, class Sched, bool ALIGN_EPI = false, bool SP2 = false>
; __device__ __forceinline__ void gemm_phase(PG8_LAS unsigned char* lds, const Gemm g, const Sched& S, const Epi& E) {
;     ...
;             PG8_WAIT_V(8); PG8_WAIT_L(0); PG8_BAR; PG8_MMA(0, 0, At, B0); PG8_MMA(0, 1, At, B1); PG8_BAR; PG8_SCHED;
;             PG8_LDA(At, 0, 1); PG8_STAGE(PG8_SB(0, 0), b2, voffB); PG8_STAGE(PG8_SB(0, 1), b2 + hstepB, voffB); PG8_STAGE(PG8_SA(0, 0), a2, voffA);
;             PG8_WAIT_V(8); PG8_WAIT_L(0); PG8_BAR; PG8_MMA(1, 0, At, B0); PG8_MMA(1, 1, At, B1); PG8_BAR; PG8_SCHED;
;             PG8_LDB(B0, 1, 0); PG8_LDB(B1, 1, 1); PG8_SCHED; PG8_LDA(At, 1, 0); PG8_STAGE(PG8_SA(0, 1), a2 + hstepA, voffA);
;             PG8_WAIT_V(8); PG8_WAIT_L(0); PG8_BAR; PG8_MMA(0, 0, At, B0); PG8_MMA(0, 1, At, B1); PG8_BAR; PG8_SCHED;
;             PG8_LDA(At, 1, 1); PG8_STAGE(PG8_SB(1, 0), b3, voffB); PG8_STAGE(PG8_SB(1, 1), b3 + hstepB, voffB); PG8_STAGE(PG8_SA(1, 0), a3, voffA);
;             PG8_WAIT_V(8); PG8_WAIT_L(0); PG8_BAR; PG8_MMA(1, 0, At, B0); PG8_MMA(1, 1, At, B1); PG8_BAR; PG8_SCHED;
	s_setprio 1
	s_waitcnt lgkmcnt(0)
	v_mfma_f32_16x16x32_bf16 v[62:65], v[130:133], v[206:209], 0
	v_mfma_f32_16x16x32_bf16 v[58:61], v[138:141], v[206:209], 0
	v_mfma_f32_16x16x32_bf16 v[46:49], v[130:133], v[214:217], 0
	v_mfma_f32_16x16x32_bf16 v[42:45], v[138:141], v[214:217], 0
	v_mfma_f32_16x16x32_bf16 v[30:33], v[130:133], v[222:225], 0
	v_mfma_f32_16x16x32_bf16 v[26:29], v[138:141], v[222:225], 0
	v_mfma_f32_16x16x32_bf16 v[14:17], v[130:133], v[230:233], 0
	v_mfma_f32_16x16x32_bf16 v[10:13], v[138:141], v[230:233], 0
	v_mfma_f32_16x16x32_bf16 v[62:65], v[134:137], v[210:213], v[62:65]
	v_mfma_f32_16x16x32_bf16 v[58:61], v[142:145], v[210:213], v[58:61]
	v_mfma_f32_16x16x32_bf16 v[46:49], v[134:137], v[218:221], v[46:49]
	v_mfma_f32_16x16x32_bf16 v[42:45], v[142:145], v[218:221], v[42:45]
	v_mfma_f32_16x16x32_bf16 v[30:33], v[134:137], v[226:229], v[30:33]
	v_mfma_f32_16x16x32_bf16 v[26:29], v[142:145], v[226:229], v[26:29]
	v_mfma_f32_16x16x32_bf16 v[14:17], v[134:137], v[234:237], v[14:17]
	v_mfma_f32_16x16x32_bf16 v[10:13], v[142:145], v[234:237], v[10:13]
	s_setprio 0
	s_setprio 1
	v_mfma_f32_16x16x32_bf16 v[54:57], v[168:171], v[206:209], 0
	v_mfma_f32_16x16x32_bf16 v[50:53], v[198:201], v[206:209], 0
	v_mfma_f32_16x16x32_bf16 v[38:41], v[168:171], v[214:217], 0
	v_mfma_f32_16x16x32_bf16 v[34:37], v[198:201], v[214:217], 0
	v_mfma_f32_16x16x32_bf16 v[22:25], v[168:171], v[222:225], 0
	v_mfma_f32_16x16x32_bf16 v[18:21], v[198:201], v[222:225], 0
	v_mfma_f32_16x16x32_bf16 v[6:9], v[168:171], v[230:233], 0
	v_mfma_f32_16x16x32_bf16 v[2:5], v[198:201], v[230:233], 0
	v_mfma_f32_16x16x32_bf16 v[54:57], v[194:197], v[210:213], v[54:57]
	v_mfma_f32_16x16x32_bf16 v[50:53], v[202:205], v[210:213], v[50:53]
	v_mfma_f32_16x16x32_bf16 v[38:41], v[194:197], v[218:221], v[38:41]
	v_mfma_f32_16x16x32_bf16 v[34:37], v[202:205], v[218:221], v[34:37]
	v_mfma_f32_16x16x32_bf16 v[22:25], v[194:197], v[226:229], v[22:25]
	v_mfma_f32_16x16x32_bf16 v[18:21], v[202:205], v[226:229], v[18:21]
	v_mfma_f32_16x16x32_bf16 v[6:9], v[194:197], v[234:237], v[6:9]
	v_mfma_f32_16x16x32_bf16 v[2:5], v[202:205], v[234:237], v[2:5]
	s_setprio 0
	s_barrier
	ds_read_b128 v[130:133], v192
	ds_read_b128 v[134:137], v192 offset:1024
	ds_read_b128 v[138:141], v192 offset:2048
	ds_read_b128 v[142:145], v192 offset:3072
	ds_read_b128 v[168:171], v193
	ds_read_b128 v[194:197], v193 offset:1024
	ds_read_b128 v[198:201], v193 offset:2048
	ds_read_b128 v[202:205], v193 offset:3072
	s_add_u32 s0, s72, 0x40000
	s_addc_u32 s1, s73, 0
	s_mov_b32 m0, s76
	v_lshl_add_u64 v[246:247], s[0:1], 0, v[148:149]
	ds_read_b128 v[206:209], v191 offset:32768
	ds_read_b128 v[210:213], v191 offset:33792
	ds_read_b128 v[214:217], v191 offset:34816
	ds_read_b128 v[218:221], v191 offset:35840
	ds_read_b128 v[222:225], v191 offset:36864
	ds_read_b128 v[226:229], v191 offset:37888
	ds_read_b128 v[230:233], v191 offset:38912
	ds_read_b128 v[234:237], v191 offset:39936
	global_load_lds_dwordx4 v[246:247], off
	v_lshl_add_u64 v[246:247], s[0:1], 0, v[150:151]
	s_mov_b32 m0, s77
	s_nop 0
	global_load_lds_dwordx4 v[246:247], off
	s_waitcnt vmcnt(8)
	s_waitcnt lgkmcnt(0)
	s_barrier
	s_setprio 1
	s_waitcnt lgkmcnt(0)
	v_mfma_f32_16x16x32_bf16 v[126:129], v[130:133], v[206:209], v[126:129]
	v_mfma_f32_16x16x32_bf16 v[122:125], v[138:141], v[206:209], v[122:125]
	v_mfma_f32_16x16x32_bf16 v[110:113], v[130:133], v[214:217], v[110:113]
	v_mfma_f32_16x16x32_bf16 v[106:109], v[138:141], v[214:217], v[106:109]
	v_mfma_f32_16x16x32_bf16 v[94:97], v[130:133], v[222:225], v[94:97]
	v_mfma_f32_16x16x32_bf16 v[90:93], v[138:141], v[222:225], v[90:93]
	v_mfma_f32_16x16x32_bf16 v[78:81], v[130:133], v[230:233], v[78:81]
	v_mfma_f32_16x16x32_bf16 v[74:77], v[138:141], v[230:233], v[74:77]
	v_mfma_f32_16x16x32_bf16 v[126:129], v[134:137], v[210:213], v[126:129]
	v_mfma_f32_16x16x32_bf16 v[122:125], v[142:145], v[210:213], v[122:125]
	v_mfma_f32_16x16x32_bf16 v[110:113], v[134:137], v[218:221], v[110:113]
	v_mfma_f32_16x16x32_bf16 v[106:109], v[142:145], v[218:221], v[106:109]
	v_mfma_f32_16x16x32_bf16 v[94:97], v[134:137], v[226:229], v[94:97]
	v_mfma_f32_16x16x32_bf16 v[90:93], v[142:145], v[226:229], v[90:93]
	v_mfma_f32_16x16x32_bf16 v[78:81], v[134:137], v[234:237], v[78:81]
	v_mfma_f32_16x16x32_bf16 v[74:77], v[142:145], v[234:237], v[74:77]
	s_setprio 0
	s_setprio 1
	v_mfma_f32_16x16x32_bf16 v[118:121], v[168:171], v[206:209], v[118:121]
	v_mfma_f32_16x16x32_bf16 v[114:117], v[198:201], v[206:209], v[114:117]
	v_mfma_f32_16x16x32_bf16 v[102:105], v[168:171], v[214:217], v[102:105]
	v_mfma_f32_16x16x32_bf16 v[98:101], v[198:201], v[214:217], v[98:101]
	v_mfma_f32_16x16x32_bf16 v[86:89], v[168:171], v[222:225], v[86:89]
	v_mfma_f32_16x16x32_bf16 v[82:85], v[198:201], v[222:225], v[82:85]
	v_mfma_f32_16x16x32_bf16 v[70:73], v[168:171], v[230:233], v[70:73]
	v_mfma_f32_16x16x32_bf16 v[66:69], v[198:201], v[230:233], v[66:69]
	v_mfma_f32_16x16x32_bf16 v[118:121], v[194:197], v[210:213], v[118:121]
	v_mfma_f32_16x16x32_bf16 v[114:117], v[202:205], v[210:213], v[114:117]
	v_mfma_f32_16x16x32_bf16 v[102:105], v[194:197], v[218:221], v[102:105]
	v_mfma_f32_16x16x32_bf16 v[98:101], v[202:205], v[218:221], v[98:101]
	v_mfma_f32_16x16x32_bf16 v[86:89], v[194:197], v[226:229], v[86:89]
	v_mfma_f32_16x16x32_bf16 v[82:85], v[202:205], v[226:229], v[82:85]
	v_mfma_f32_16x16x32_bf16 v[70:73], v[194:197], v[234:237], v[70:73]
	v_mfma_f32_16x16x32_bf16 v[66:69], v[202:205], v[234:237], v[66:69]
	s_setprio 0
	s_barrier
; #define PG8_STAGE(bufoff, gbase, voff) do { _Pragma("unroll") for (int _i = 0; _i < 2; ++_i) \
;         __builtin_amdgcn_global_load_lds((const unsigned*)((const char*)(gbase) + (voff)[_i]), (PG8_LAS unsigned*)(lds + (bufoff) + ldsw + _i * 8192), 16, 0, 0); } while (0)
; #define PG8_LDA(dst, b, h) do { _Pragma("unroll") for (int m = 0; m < 4; ++m) _Pragma("unroll") for (int k = 0; k < 2; ++k) dst[m][k] = *(const PG8_LAS bf16x8*)(lds + PG8_SA(b, h) + aoff + m * 2048 + k * 1024); } while (0)
; #define PG8_MMA(ai, bj, At, Bt) do { __builtin_amdgcn_s_setprio(1); _Pragma("unroll") for (int m = 0; m < 4; ++m) _Pragma("unroll") for (int n = 0; n < 2; ++n) _Pragma("unroll") for (int k = 0; k < 2; ++k) \
;         acc[ai][bj][m][n] = __builtin_amdgcn_mfma_f32_16x16x32_bf16(Bt[n][k], At[m][k], acc[ai][bj][m][n], 0, 0, 0); __builtin_amdgcn_s_setprio(0); } while (0)
; #define PG8_WAIT_V(n) asm volatile("s_waitcnt vmcnt(" #n ")" ::: "memory")
; #define PG8_WAIT_L(n) asm volatile("s_waitcnt lgkmcnt(" #n ")" ::: "memory")
; #define PG8_BAR __builtin_amdgcn_s_barrier()
; #define PG8_SCHED __builtin_amdgcn_sched_barrier(0)
; template <class Epi, class Sched, bool ALIGN_EPI = false, bool SP2 = false>
; __device__ __forceinline__ void gemm_phase(PG8_LAS unsigned char* lds, const Gemm g, const Sched& S, const Epi& E) {
;     ...
;         for (int t = 0; t < nt; t += 2) {
;             const bool last = (t == nt - 2);
;             const char* a1 = cA + (size_t)(t + 1) * kstep;
;             const char* a2 = last ? nA : cA + (size_t)(t + 2) * kstep; const char* b2 = last ? nB : cB + (size_t)(t + 2) * kstep;
;             const char* a3 = a2 + kstep; const char* b3 = b2 + kstep;
;     ...
;             PG8_LDA(At, 1, 1); PG8_STAGE(PG8_SB(1, 0), b3, voffB); PG8_STAGE(PG8_SB(1, 1), b3 + hstepB, voffB); PG8_STAGE(PG8_SA(1, 0), a3, voffA);
;             PG8_WAIT_V(8); PG8_WAIT_L(0); PG8_BAR; PG8_MMA(1, 0, At, B0); PG8_MMA(1, 1, At, B1); PG8_BAR; PG8_SCHED;
	s_add_i32 s0, s82, s69
	v_lshl_add_u64 v[238:239], v[238:239], 0, s[28:29]
	s_mov_b32 m0, s0
	ds_read_b128 v[206:209], v191 offset:49152
	ds_read_b128 v[210:213], v191 offset:50176
	ds_read_b128 v[214:217], v191 offset:51200
	ds_read_b128 v[218:221], v191 offset:52224
	ds_read_b128 v[222:225], v191 offset:53248
	ds_read_b128 v[226:229], v191 offset:54272
	ds_read_b128 v[230:233], v191 offset:55296
	ds_read_b128 v[234:237], v191 offset:56320
	global_load_lds_dwordx4 v[238:239], off
	s_add_i32 m0, s0, 0x2000
	s_add_u32 s0, s70, 0x40080
	v_lshl_add_u64 v[238:239], v[240:241], 0, s[28:29]
	s_addc_u32 s1, s71, 0
	s_add_i32 s2, s83, s69
	global_load_lds_dwordx4 v[238:239], off
	v_lshl_add_u64 v[238:239], s[0:1], 0, v[146:147]
	s_mov_b32 m0, s2
	s_nop 0
	global_load_lds_dwordx4 v[238:239], off
	v_lshl_add_u64 v[238:239], s[0:1], 0, v[152:153]
	s_add_i32 m0, s2, 0x2000
	s_nop 0
	global_load_lds_dwordx4 v[238:239], off
	v_lshl_add_u64 v[238:239], v[242:243], 0, s[28:29]
	s_mov_b32 m0, s78
	s_nop 0
	global_load_lds_dwordx4 v[238:239], off
	v_lshl_add_u64 v[238:239], v[244:245], 0, s[28:29]
	s_mov_b32 m0, s79
	s_nop 0
	global_load_lds_dwordx4 v[238:239], off
	s_waitcnt vmcnt(8)
	s_waitcnt lgkmcnt(0)
	s_barrier
	s_setprio 1
	s_waitcnt lgkmcnt(0)
	v_mfma_f32_16x16x32_bf16 v[62:65], v[130:133], v[206:209], v[62:65]
	v_mfma_f32_16x16x32_bf16 v[58:61], v[138:141], v[206:209], v[58:61]
	v_mfma_f32_16x16x32_bf16 v[46:49], v[130:133], v[214:217], v[46:49]
	v_mfma_f32_16x16x32_bf16 v[42:45], v[138:141], v[214:217], v[42:45]
	v_mfma_f32_16x16x32_bf16 v[30:33], v[130:133], v[222:225], v[30:33]
	v_mfma_f32_16x16x32_bf16 v[26:29], v[138:141], v[222:225], v[26:29]
	v_mfma_f32_16x16x32_bf16 v[14:17], v[130:133], v[230:233], v[14:17]
	v_mfma_f32_16x16x32_bf16 v[10:13], v[138:141], v[230:233], v[10:13]
	v_mfma_f32_16x16x32_bf16 v[62:65], v[134:137], v[210:213], v[62:65]
	v_mfma_f32_16x16x32_bf16 v[58:61], v[142:145], v[210:213], v[58:61]
	v_mfma_f32_16x16x32_bf16 v[46:49], v[134:137], v[218:221], v[46:49]
	v_mfma_f32_16x16x32_bf16 v[42:45], v[142:145], v[218:221], v[42:45]
	v_mfma_f32_16x16x32_bf16 v[30:33], v[134:137], v[226:229], v[30:33]
	v_mfma_f32_16x16x32_bf16 v[26:29], v[142:145], v[226:229], v[26:29]
	v_mfma_f32_16x16x32_bf16 v[14:17], v[134:137], v[234:237], v[14:17]
	v_mfma_f32_16x16x32_bf16 v[10:13], v[142:145], v[234:237], v[10:13]
	s_setprio 0
	s_setprio 1
	v_mfma_f32_16x16x32_bf16 v[54:57], v[168:171], v[206:209], v[54:57]
	v_mfma_f32_16x16x32_bf16 v[50:53], v[198:201], v[206:209], v[50:53]
	v_mfma_f32_16x16x32_bf16 v[38:41], v[168:171], v[214:217], v[38:41]
	v_mfma_f32_16x16x32_bf16 v[34:37], v[198:201], v[214:217], v[34:37]
	v_mfma_f32_16x16x32_bf16 v[22:25], v[168:171], v[222:225], v[22:25]
	v_mfma_f32_16x16x32_bf16 v[18:21], v[198:201], v[222:225], v[18:21]
	v_mfma_f32_16x16x32_bf16 v[6:9], v[168:171], v[230:233], v[6:9]
	v_mfma_f32_16x16x32_bf16 v[2:5], v[198:201], v[230:233], v[2:5]
	v_mfma_f32_16x16x32_bf16 v[54:57], v[194:197], v[210:213], v[54:57]
	v_mfma_f32_16x16x32_bf16 v[50:53], v[202:205], v[210:213], v[50:53]
	v_mfma_f32_16x16x32_bf16 v[38:41], v[194:197], v[218:221], v[38:41]
	v_mfma_f32_16x16x32_bf16 v[34:37], v[202:205], v[218:221], v[34:37]
	v_mfma_f32_16x16x32_bf16 v[22:25], v[194:197], v[226:229], v[22:25]
	v_mfma_f32_16x16x32_bf16 v[18:21], v[202:205], v[226:229], v[18:21]
	v_mfma_f32_16x16x32_bf16 v[6:9], v[194:197], v[234:237], v[6:9]
	v_mfma_f32_16x16x32_bf16 v[2:5], v[202:205], v[234:237], v[2:5]
	s_setprio 0
	s_barrier
	s_add_i32 s15, s15, 2
	s_add_u32 s12, s12, 0x100
	s_addc_u32 s13, s13, 0
	s_add_u32 s7, s7, 0x100
	s_addc_u32 s14, s14, 0
	s_cmp_gt_u32 s15, 13

; #define PG8_STAGE(bufoff, gbase, voff) do { _Pragma("unroll") for (int _i = 0; _i < 2; ++_i) \
;         __builtin_amdgcn_global_load_lds((const unsigned*)((const char*)(gbase) + (voff)[_i]), (PG8_LAS unsigned*)(lds + (bufoff) + ldsw + _i * 8192), 16, 0, 0); } while (0)
; #define PG8_LDA(dst, b, h) do { _Pragma("unroll") for (int m = 0; m < 4; ++m) _Pragma("unroll") for (int k = 0; k < 2; ++k) dst[m][k] = *(const PG8_LAS bf16x8*)(lds + PG8_SA(b, h) + aoff + m * 2048 + k * 1024); } while (0)
; #define PG8_LDB(dst, b, h) do { _Pragma("unroll") for (int n = 0; n < 2; ++n) _Pragma("unroll") for (int k = 0; k < 2; ++k) dst[n][k] = *(const PG8_LAS bf16x8*)(lds + PG8_SB(b, h) + boff + n * 2048 + k * 1024); } while (0)
; #define PG8_WAIT_V(n) asm volatile("s_waitcnt vmcnt(" #n ")" ::: "memory")
; #define PG8_WAIT_L(n) asm volatile("s_waitcnt lgkmcnt(" #n ")" ::: "memory")
; #define PG8_BAR __builtin_amdgcn_s_barrier()
; template <class Epi, class Sched, bool ALIGN_EPI = false, bool SP2 = false>
; __device__ __forceinline__ void gemm_phase(PG8_LAS unsigned char* lds, const Gemm g, const Sched& S, const Epi& E) {
;     ...
;             const bool last = (t == nt - 2);
;             const char* a1 = cA + (size_t)(t + 1) * kstep;
;             const char* a2 = last ? nA : cA + (size_t)(t + 2) * kstep; const char* b2 = last ? nB : cB + (size_t)(t + 2) * kstep;
;             const char* a3 = a2 + kstep; const char* b3 = b2 + kstep;
;             if (last && has_next) S.a_ready(nxt);
;             if constexpr (SP2) {
;             PG8_LDB(B0, 0, 0); PG8_LDB(B1, 0, 1); PG8_SCHED; PG8_LDA(At, 0, 0); PG8_STAGE(PG8_SA(1, 1), a1 + hstepA, voffA);
;             PG8_WAIT_V(8); PG8_WAIT_L(0); PG8_BAR; PG8_MMA(0, 0, At, B0); PG8_MMA(0, 1, At, B1); PG8_BAR; PG8_SCHED;
;             PG8_LDA(At, 0, 1); PG8_STAGE(PG8_SB(0, 0), b2, voffB); PG8_STAGE(PG8_SB(0, 1), b2 + hstepB, voffB); PG8_STAGE(PG8_SA(0, 0), a2, voffA);
;             PG8_WAIT_V(8); PG8_WAIT_L(0); PG8_BAR; PG8_MMA(1, 0, At, B0); PG8_MMA(1, 1, At, B1); PG8_BAR; PG8_SCHED;
;     ...
; #pragma unroll
;         for (int a = 0; a < 2; ++a)
; #pragma unroll
;             for (int b = 0; b < 2; ++b)
; #pragma unroll
;                 for (int m = 0; m < 4; ++m)
; #pragma unroll
;                     for (int n = 0; n < 2; ++n) acc[a][b][m][n] = (f32x4){0.f, 0.f, 0.f, 0.f};
;         cur = nxt; cA = nA; cB = nB; ++ui;
.LBB0_1845:
	s_ashr_i32 s35, s34, 31
	s_lshl_b64 s[0:1], s[34:35], 19
	s_add_u32 s40, s24, s0
	s_addc_u32 s41, s25, s1
	s_and_b64 s[0:1], s[14:15], exec
	s_cselect_b32 s5, s41, s47
	s_cselect_b32 s7, s40, s46
	s_add_u32 s18, s46, 0x100
	s_addc_u32 s19, s47, 0
	s_mov_b32 s35, -2
	ds_read_b128 v[126:129], v205
	ds_read_b128 v[130:133], v205 offset:1024
	ds_read_b128 v[134:137], v205 offset:2048
	ds_read_b128 v[138:141], v205 offset:3072
	ds_read_b128 v[142:145], v206
	ds_read_b128 v[146:149], v206 offset:1024
	ds_read_b128 v[150:153], v206 offset:2048
	ds_read_b128 v[154:157], v206 offset:3072
	s_add_u32 s14, s44, 0x100
	s_addc_u32 s15, s45, 0
	s_cmp_eq_u32 s35, 12
	s_cselect_b32 s49, s39, s15
	s_cselect_b32 s48, s38, s14
	s_cselect_b32 s47, s5, s19
	s_cselect_b32 s46, s7, s18
	v_lshl_add_u64 v[226:227], s[44:45], 0, v[192:193]
	s_add_i32 m0, s50, 0xc000
	ds_read_b128 v[162:165], v207
	ds_read_b128 v[166:169], v207 offset:1024
	ds_read_b128 v[170:173], v207 offset:2048
	ds_read_b128 v[174:177], v207 offset:3072
	ds_read_b128 v[210:213], v207 offset:4096
	ds_read_b128 v[214:217], v207 offset:5120
	ds_read_b128 v[218:221], v207 offset:6144
	ds_read_b128 v[222:225], v207 offset:7168
	global_load_lds_dwordx4 v[226:227], off
	v_lshl_add_u64 v[226:227], s[44:45], 0, v[194:195]
	s_add_i32 m0, s50, 0xe000
	s_nop 0
	global_load_lds_dwordx4 v[226:227], off
	s_waitcnt vmcnt(8)
	s_waitcnt lgkmcnt(0)
	s_barrier
	s_setprio 1
	s_waitcnt lgkmcnt(0)
	v_mfma_f32_16x16x32_bf16 v[114:117], v[126:129], v[162:165], 0
	v_mfma_f32_16x16x32_bf16 v[106:109], v[134:137], v[162:165], 0
	v_mfma_f32_16x16x32_bf16 v[98:101], v[126:129], v[170:173], 0
	v_mfma_f32_16x16x32_bf16 v[82:85], v[134:137], v[170:173], 0
	v_mfma_f32_16x16x32_bf16 v[94:97], v[126:129], v[210:213], 0
	v_mfma_f32_16x16x32_bf16 v[78:81], v[134:137], v[210:213], 0
	v_mfma_f32_16x16x32_bf16 v[90:93], v[126:129], v[218:221], 0
	v_mfma_f32_16x16x32_bf16 v[74:77], v[134:137], v[218:221], 0
	v_mfma_f32_16x16x32_bf16 v[114:117], v[130:133], v[166:169], v[114:117]
	v_mfma_f32_16x16x32_bf16 v[106:109], v[138:141], v[166:169], v[106:109]
	v_mfma_f32_16x16x32_bf16 v[98:101], v[130:133], v[174:177], v[98:101]
	v_mfma_f32_16x16x32_bf16 v[82:85], v[138:141], v[174:177], v[82:85]
	v_mfma_f32_16x16x32_bf16 v[94:97], v[130:133], v[214:217], v[94:97]
	v_mfma_f32_16x16x32_bf16 v[78:81], v[138:141], v[214:217], v[78:81]
	v_mfma_f32_16x16x32_bf16 v[90:93], v[130:133], v[222:225], v[90:93]
	v_mfma_f32_16x16x32_bf16 v[74:77], v[138:141], v[222:225], v[74:77]
	s_setprio 0
	s_setprio 1
	v_mfma_f32_16x16x32_bf16 v[158:161], v[142:145], v[162:165], 0
	v_mfma_f32_16x16x32_bf16 v[122:125], v[150:153], v[162:165], 0
	v_mfma_f32_16x16x32_bf16 v[118:121], v[142:145], v[170:173], 0
	v_mfma_f32_16x16x32_bf16 v[110:113], v[150:153], v[170:173], 0
	v_mfma_f32_16x16x32_bf16 v[102:105], v[142:145], v[210:213], 0
	v_mfma_f32_16x16x32_bf16 v[86:89], v[150:153], v[210:213], 0
	v_mfma_f32_16x16x32_bf16 v[70:73], v[142:145], v[218:221], 0
	v_mfma_f32_16x16x32_bf16 v[66:69], v[150:153], v[218:221], 0
	v_mfma_f32_16x16x32_bf16 v[158:161], v[146:149], v[166:169], v[158:161]
	v_mfma_f32_16x16x32_bf16 v[122:125], v[154:157], v[166:169], v[122:125]
	v_mfma_f32_16x16x32_bf16 v[118:121], v[146:149], v[174:177], v[118:121]
	v_mfma_f32_16x16x32_bf16 v[110:113], v[154:157], v[174:177], v[110:113]
	v_mfma_f32_16x16x32_bf16 v[102:105], v[146:149], v[214:217], v[102:105]
	v_mfma_f32_16x16x32_bf16 v[86:89], v[154:157], v[214:217], v[86:89]
	v_mfma_f32_16x16x32_bf16 v[70:73], v[146:149], v[222:225], v[70:73]
	v_mfma_f32_16x16x32_bf16 v[66:69], v[154:157], v[222:225], v[66:69]
	s_setprio 0
	s_barrier
	s_add_i32 s0, s70, s43
	v_lshl_add_u64 v[226:227], s[46:47], 0, v[180:181]
	s_mov_b32 m0, s0
	ds_read_b128 v[162:165], v207 offset:16384
	ds_read_b128 v[166:169], v207 offset:17408
	ds_read_b128 v[170:173], v207 offset:18432
	ds_read_b128 v[174:177], v207 offset:19456
	ds_read_b128 v[210:213], v207 offset:20480
	ds_read_b128 v[214:217], v207 offset:21504
	ds_read_b128 v[218:221], v207 offset:22528
	ds_read_b128 v[222:225], v207 offset:23552
	global_load_lds_dwordx4 v[226:227], off
	s_add_i32 m0, s0, 0x2000
	s_add_u32 s0, s46, 0x40000
	v_lshl_add_u64 v[228:229], s[46:47], 0, v[184:185]
	s_addc_u32 s1, s47, 0
	s_add_i32 s2, s71, s43
	global_load_lds_dwordx4 v[228:229], off
	v_lshl_add_u64 v[230:231], s[0:1], 0, v[180:181]
	s_mov_b32 m0, s2
	v_lshl_add_u64 v[232:233], s[48:49], 0, v[182:183]
	global_load_lds_dwordx4 v[230:231], off
	v_lshl_add_u64 v[230:231], s[0:1], 0, v[184:185]
	s_add_i32 m0, s2, 0x2000
	s_nop 0
	global_load_lds_dwordx4 v[230:231], off
	v_lshl_add_u64 v[230:231], s[48:49], 0, v[178:179]
	s_mov_b32 m0, s50
	s_nop 0
	global_load_lds_dwordx4 v[230:231], off
	s_mov_b32 m0, s51
	s_nop 0
	global_load_lds_dwordx4 v[232:233], off
	s_waitcnt vmcnt(8)
	s_waitcnt lgkmcnt(0)
	s_barrier
; #define PG8_STAGE(bufoff, gbase, voff) do { _Pragma("unroll") for (int _i = 0; _i < 2; ++_i) \
;         __builtin_amdgcn_global_load_lds((const unsigned*)((const char*)(gbase) + (voff)[_i]), (PG8_LAS unsigned*)(lds + (bufoff) + ldsw + _i * 8192), 16, 0, 0); } while (0)
; #define PG8_LDA(dst, b, h) do { _Pragma("unroll") for (int m = 0; m < 4; ++m) _Pragma("unroll") for (int k = 0; k < 2; ++k) dst[m][k] = *(const PG8_LAS bf16x8*)(lds + PG8_SA(b, h) + aoff + m * 2048 + k * 1024); } while (0)
; #define PG8_LDB(dst, b, h) do { _Pragma("unroll") for (int n = 0; n < 2; ++n) _Pragma("unroll") for (int k = 0; k < 2; ++k) dst[n][k] = *(const PG8_LAS bf16x8*)(lds + PG8_SB(b, h) + boff + n * 2048 + k * 1024); } while (0)
; #define PG8_MMA(ai, bj, At, Bt) do { __builtin_amdgcn_s_setprio(1); _Pragma("unroll") for (int m = 0; m < 4; ++m) _Pragma("unroll") for (int n = 0; n < 2; ++n) _Pragma("unroll") for (int k = 0; k < 2; ++k) \
;         acc[ai][bj][m][n] = __builtin_amdgcn_mfma_f32_16x16x32_bf16(Bt[n][k], At[m][k], acc[ai][bj][m][n], 0, 0, 0); __builtin_amdgcn_s_setprio(0); } while (0)
; #define PG8_WAIT_V(n) asm volatile("s_waitcnt vmcnt(" #n ")" ::: "memory")
; #define PG8_WAIT_L(n) asm volatile("s_waitcnt lgkmcnt(" #n ")" ::: "memory")
; #define PG8_BAR __builtin_amdgcn_s_barrier()
; template <class Epi, class Sched, bool ALIGN_EPI = false, bool SP2 = false>
; __device__ __forceinline__ void gemm_phase(PG8_LAS unsigned char* lds, const Gemm g, const Sched& S, const Epi& E) {
;     ...
;             PG8_WAIT_V(8); PG8_WAIT_L(0); PG8_BAR; PG8_MMA(0, 0, At, B0); PG8_MMA(0, 1, At, B1); PG8_BAR; PG8_SCHED;
;             PG8_LDA(At, 0, 1); PG8_STAGE(PG8_SB(0, 0), b2, voffB); PG8_STAGE(PG8_SB(0, 1), b2 + hstepB, voffB); PG8_STAGE(PG8_SA(0, 0), a2, voffA);
;             PG8_WAIT_V(8); PG8_WAIT_L(0); PG8_BAR; PG8_MMA(1, 0, At, B0); PG8_MMA(1, 1, At, B1); PG8_BAR; PG8_SCHED;
;             PG8_LDB(B0, 1, 0); PG8_LDB(B1, 1, 1); PG8_SCHED; PG8_LDA(At, 1, 0); PG8_STAGE(PG8_SA(0, 1), a2 + hstepA, voffA);
;             PG8_WAIT_V(8); PG8_WAIT_L(0); PG8_BAR; PG8_MMA(0, 0, At, B0); PG8_MMA(0, 1, At, B1); PG8_BAR; PG8_SCHED;
;             PG8_LDA(At, 1, 1); PG8_STAGE(PG8_SB(1, 0), b3, voffB); PG8_STAGE(PG8_SB(1, 1), b3 + hstepB, voffB); PG8_STAGE(PG8_SA(1, 0), a3, voffA);
;             PG8_WAIT_V(8); PG8_WAIT_L(0); PG8_BAR; PG8_MMA(1, 0, At, B0); PG8_MMA(1, 1, At, B1); PG8_BAR; PG8_SCHED;
	s_setprio 1
	s_waitcnt lgkmcnt(0)
	v_mfma_f32_16x16x32_bf16 v[50:53], v[126:129], v[162:165], 0
	v_mfma_f32_16x16x32_bf16 v[42:45], v[134:137], v[162:165], 0
	v_mfma_f32_16x16x32_bf16 v[34:37], v[126:129], v[170:173], 0
	v_mfma_f32_16x16x32_bf16 v[18:21], v[134:137], v[170:173], 0
	v_mfma_f32_16x16x32_bf16 v[30:33], v[126:129], v[210:213], 0
	v_mfma_f32_16x16x32_bf16 v[14:17], v[134:137], v[210:213], 0
	v_mfma_f32_16x16x32_bf16 v[26:29], v[126:129], v[218:221], 0
	v_mfma_f32_16x16x32_bf16 v[10:13], v[134:137], v[218:221], 0
	v_mfma_f32_16x16x32_bf16 v[50:53], v[130:133], v[166:169], v[50:53]
	v_mfma_f32_16x16x32_bf16 v[42:45], v[138:141], v[166:169], v[42:45]
	v_mfma_f32_16x16x32_bf16 v[34:37], v[130:133], v[174:177], v[34:37]
	v_mfma_f32_16x16x32_bf16 v[18:21], v[138:141], v[174:177], v[18:21]
	v_mfma_f32_16x16x32_bf16 v[30:33], v[130:133], v[214:217], v[30:33]
	v_mfma_f32_16x16x32_bf16 v[14:17], v[138:141], v[214:217], v[14:17]
	v_mfma_f32_16x16x32_bf16 v[26:29], v[130:133], v[222:225], v[26:29]
	v_mfma_f32_16x16x32_bf16 v[10:13], v[138:141], v[222:225], v[10:13]
	s_setprio 0
	s_setprio 1
	v_mfma_f32_16x16x32_bf16 v[62:65], v[142:145], v[162:165], 0
	v_mfma_f32_16x16x32_bf16 v[58:61], v[150:153], v[162:165], 0
	v_mfma_f32_16x16x32_bf16 v[54:57], v[142:145], v[170:173], 0
	v_mfma_f32_16x16x32_bf16 v[46:49], v[150:153], v[170:173], 0
	v_mfma_f32_16x16x32_bf16 v[38:41], v[142:145], v[210:213], 0
	v_mfma_f32_16x16x32_bf16 v[22:25], v[150:153], v[210:213], 0
	v_mfma_f32_16x16x32_bf16 v[6:9], v[142:145], v[218:221], 0
	v_mfma_f32_16x16x32_bf16 v[2:5], v[150:153], v[218:221], 0
	v_mfma_f32_16x16x32_bf16 v[62:65], v[146:149], v[166:169], v[62:65]
	v_mfma_f32_16x16x32_bf16 v[58:61], v[154:157], v[166:169], v[58:61]
	v_mfma_f32_16x16x32_bf16 v[54:57], v[146:149], v[174:177], v[54:57]
	v_mfma_f32_16x16x32_bf16 v[46:49], v[154:157], v[174:177], v[46:49]
	v_mfma_f32_16x16x32_bf16 v[38:41], v[146:149], v[214:217], v[38:41]
	v_mfma_f32_16x16x32_bf16 v[22:25], v[154:157], v[214:217], v[22:25]
	v_mfma_f32_16x16x32_bf16 v[6:9], v[146:149], v[222:225], v[6:9]
	v_mfma_f32_16x16x32_bf16 v[2:5], v[154:157], v[222:225], v[2:5]
	s_setprio 0
	s_barrier
	ds_read_b128 v[126:129], v208
	ds_read_b128 v[130:133], v208 offset:1024
	ds_read_b128 v[134:137], v208 offset:2048
	ds_read_b128 v[138:141], v208 offset:3072
	ds_read_b128 v[142:145], v209
	ds_read_b128 v[146:149], v209 offset:1024
	ds_read_b128 v[150:153], v209 offset:2048
	ds_read_b128 v[154:157], v209 offset:3072
	s_add_u32 s0, s48, 0x40000
	s_addc_u32 s1, s49, 0
	s_mov_b32 m0, s62
	v_lshl_add_u64 v[234:235], s[0:1], 0, v[178:179]
	ds_read_b128 v[162:165], v207 offset:32768
	ds_read_b128 v[166:169], v207 offset:33792
	ds_read_b128 v[170:173], v207 offset:34816
	ds_read_b128 v[174:177], v207 offset:35840
	ds_read_b128 v[210:213], v207 offset:36864
	ds_read_b128 v[214:217], v207 offset:37888
	ds_read_b128 v[218:221], v207 offset:38912
	ds_read_b128 v[222:225], v207 offset:39936
	global_load_lds_dwordx4 v[234:235], off
	v_lshl_add_u64 v[234:235], s[0:1], 0, v[182:183]
	s_mov_b32 m0, s63
	s_nop 0
	global_load_lds_dwordx4 v[234:235], off
	s_waitcnt vmcnt(8)
	s_waitcnt lgkmcnt(0)
	s_barrier
	s_setprio 1
	s_waitcnt lgkmcnt(0)
	v_mfma_f32_16x16x32_bf16 v[114:117], v[126:129], v[162:165], v[114:117]
	v_mfma_f32_16x16x32_bf16 v[106:109], v[134:137], v[162:165], v[106:109]
	v_mfma_f32_16x16x32_bf16 v[98:101], v[126:129], v[170:173], v[98:101]
	v_mfma_f32_16x16x32_bf16 v[82:85], v[134:137], v[170:173], v[82:85]
	v_mfma_f32_16x16x32_bf16 v[94:97], v[126:129], v[210:213], v[94:97]
	v_mfma_f32_16x16x32_bf16 v[78:81], v[134:137], v[210:213], v[78:81]
	v_mfma_f32_16x16x32_bf16 v[90:93], v[126:129], v[218:221], v[90:93]
	v_mfma_f32_16x16x32_bf16 v[74:77], v[134:137], v[218:221], v[74:77]
	v_mfma_f32_16x16x32_bf16 v[114:117], v[130:133], v[166:169], v[114:117]
	v_mfma_f32_16x16x32_bf16 v[106:109], v[138:141], v[166:169], v[106:109]
	v_mfma_f32_16x16x32_bf16 v[98:101], v[130:133], v[174:177], v[98:101]
	v_mfma_f32_16x16x32_bf16 v[82:85], v[138:141], v[174:177], v[82:85]
	v_mfma_f32_16x16x32_bf16 v[94:97], v[130:133], v[214:217], v[94:97]
	v_mfma_f32_16x16x32_bf16 v[78:81], v[138:141], v[214:217], v[78:81]
	v_mfma_f32_16x16x32_bf16 v[90:93], v[130:133], v[222:225], v[90:93]
	v_mfma_f32_16x16x32_bf16 v[74:77], v[138:141], v[222:225], v[74:77]
	s_setprio 0
	s_setprio 1
	v_mfma_f32_16x16x32_bf16 v[158:161], v[142:145], v[162:165], v[158:161]
	v_mfma_f32_16x16x32_bf16 v[122:125], v[150:153], v[162:165], v[122:125]
	v_mfma_f32_16x16x32_bf16 v[118:121], v[142:145], v[170:173], v[118:121]
	v_mfma_f32_16x16x32_bf16 v[110:113], v[150:153], v[170:173], v[110:113]
	v_mfma_f32_16x16x32_bf16 v[102:105], v[142:145], v[210:213], v[102:105]
	v_mfma_f32_16x16x32_bf16 v[86:89], v[150:153], v[210:213], v[86:89]
	v_mfma_f32_16x16x32_bf16 v[70:73], v[142:145], v[218:221], v[70:73]
	v_mfma_f32_16x16x32_bf16 v[66:69], v[150:153], v[218:221], v[66:69]
	v_mfma_f32_16x16x32_bf16 v[158:161], v[146:149], v[166:169], v[158:161]
	v_mfma_f32_16x16x32_bf16 v[122:125], v[154:157], v[166:169], v[122:125]
	v_mfma_f32_16x16x32_bf16 v[118:121], v[146:149], v[174:177], v[118:121]
	v_mfma_f32_16x16x32_bf16 v[110:113], v[154:157], v[174:177], v[110:113]
	v_mfma_f32_16x16x32_bf16 v[102:105], v[146:149], v[214:217], v[102:105]
	v_mfma_f32_16x16x32_bf16 v[86:89], v[154:157], v[214:217], v[86:89]
	v_mfma_f32_16x16x32_bf16 v[70:73], v[146:149], v[222:225], v[70:73]
	v_mfma_f32_16x16x32_bf16 v[66:69], v[154:157], v[222:225], v[66:69]
	s_setprio 0
	s_barrier
; #define PG8_STAGE(bufoff, gbase, voff) do { _Pragma("unroll") for (int _i = 0; _i < 2; ++_i) \
;         __builtin_amdgcn_global_load_lds((const unsigned*)((const char*)(gbase) + (voff)[_i]), (PG8_LAS unsigned*)(lds + (bufoff) + ldsw + _i * 8192), 16, 0, 0); } while (0)
; #define PG8_LDA(dst, b, h) do { _Pragma("unroll") for (int m = 0; m < 4; ++m) _Pragma("unroll") for (int k = 0; k < 2; ++k) dst[m][k] = *(const PG8_LAS bf16x8*)(lds + PG8_SA(b, h) + aoff + m * 2048 + k * 1024); } while (0)
; #define PG8_MMA(ai, bj, At, Bt) do { __builtin_amdgcn_s_setprio(1); _Pragma("unroll") for (int m = 0; m < 4; ++m) _Pragma("unroll") for (int n = 0; n < 2; ++n) _Pragma("unroll") for (int k = 0; k < 2; ++k) \
;         acc[ai][bj][m][n] = __builtin_amdgcn_mfma_f32_16x16x32_bf16(Bt[n][k], At[m][k], acc[ai][bj][m][n], 0, 0, 0); __builtin_amdgcn_s_setprio(0); } while (0)
; #define PG8_WAIT_V(n) asm volatile("s_waitcnt vmcnt(" #n ")" ::: "memory")
; #define PG8_WAIT_L(n) asm volatile("s_waitcnt lgkmcnt(" #n ")" ::: "memory")
; #define PG8_BAR __builtin_amdgcn_s_barrier()
; #define PG8_SCHED __builtin_amdgcn_sched_barrier(0)
; template <class Epi, class Sched, bool ALIGN_EPI = false, bool SP2 = false>
; __device__ __forceinline__ void gemm_phase(PG8_LAS unsigned char* lds, const Gemm g, const Sched& S, const Epi& E) {
;     ...
;         for (int t = 0; t < nt; t += 2) {
;             const bool last = (t == nt - 2);
;             const char* a1 = cA + (size_t)(t + 1) * kstep;
;             const char* a2 = last ? nA : cA + (size_t)(t + 2) * kstep; const char* b2 = last ? nB : cB + (size_t)(t + 2) * kstep;
;             const char* a3 = a2 + kstep; const char* b3 = b2 + kstep;
;     ...
;             PG8_LDA(At, 1, 1); PG8_STAGE(PG8_SB(1, 0), b3, voffB); PG8_STAGE(PG8_SB(1, 1), b3 + hstepB, voffB); PG8_STAGE(PG8_SA(1, 0), a3, voffA);
;             PG8_WAIT_V(8); PG8_WAIT_L(0); PG8_BAR; PG8_MMA(1, 0, At, B0); PG8_MMA(1, 1, At, B1); PG8_BAR; PG8_SCHED;
	s_add_i32 s0, s72, s43
	v_lshl_add_u64 v[226:227], v[226:227], 0, s[20:21]
	s_mov_b32 m0, s0
	ds_read_b128 v[162:165], v207 offset:49152
	ds_read_b128 v[166:169], v207 offset:50176
	ds_read_b128 v[170:173], v207 offset:51200
	ds_read_b128 v[174:177], v207 offset:52224
	ds_read_b128 v[210:213], v207 offset:53248
	ds_read_b128 v[214:217], v207 offset:54272
	ds_read_b128 v[218:221], v207 offset:55296
	ds_read_b128 v[222:225], v207 offset:56320
	global_load_lds_dwordx4 v[226:227], off
	s_add_i32 m0, s0, 0x2000
	s_add_u32 s0, s46, 0x40080
	v_lshl_add_u64 v[226:227], v[228:229], 0, s[20:21]
	s_addc_u32 s1, s47, 0
	s_add_i32 s2, s73, s43
	global_load_lds_dwordx4 v[226:227], off
	v_lshl_add_u64 v[226:227], s[0:1], 0, v[180:181]
	s_mov_b32 m0, s2
	s_nop 0
	global_load_lds_dwordx4 v[226:227], off
	v_lshl_add_u64 v[226:227], s[0:1], 0, v[184:185]
	s_add_i32 m0, s2, 0x2000
	s_nop 0
	global_load_lds_dwordx4 v[226:227], off
	v_lshl_add_u64 v[226:227], v[230:231], 0, s[20:21]
	s_mov_b32 m0, s66
	s_nop 0
	global_load_lds_dwordx4 v[226:227], off
	v_lshl_add_u64 v[226:227], v[232:233], 0, s[20:21]
	s_mov_b32 m0, s67
	s_nop 0
	global_load_lds_dwordx4 v[226:227], off
	s_waitcnt vmcnt(8)
	s_waitcnt lgkmcnt(0)
	s_barrier
	s_setprio 1
	s_waitcnt lgkmcnt(0)
	v_mfma_f32_16x16x32_bf16 v[50:53], v[126:129], v[162:165], v[50:53]
	v_mfma_f32_16x16x32_bf16 v[42:45], v[134:137], v[162:165], v[42:45]
	v_mfma_f32_16x16x32_bf16 v[34:37], v[126:129], v[170:173], v[34:37]
	v_mfma_f32_16x16x32_bf16 v[18:21], v[134:137], v[170:173], v[18:21]
	v_mfma_f32_16x16x32_bf16 v[30:33], v[126:129], v[210:213], v[30:33]
	v_mfma_f32_16x16x32_bf16 v[14:17], v[134:137], v[210:213], v[14:17]
	v_mfma_f32_16x16x32_bf16 v[26:29], v[126:129], v[218:221], v[26:29]
	v_mfma_f32_16x16x32_bf16 v[10:13], v[134:137], v[218:221], v[10:13]
	v_mfma_f32_16x16x32_bf16 v[50:53], v[130:133], v[166:169], v[50:53]
	v_mfma_f32_16x16x32_bf16 v[42:45], v[138:141], v[166:169], v[42:45]
	v_mfma_f32_16x16x32_bf16 v[34:37], v[130:133], v[174:177], v[34:37]
	v_mfma_f32_16x16x32_bf16 v[18:21], v[138:141], v[174:177], v[18:21]
	v_mfma_f32_16x16x32_bf16 v[30:33], v[130:133], v[214:217], v[30:33]
	v_mfma_f32_16x16x32_bf16 v[14:17], v[138:141], v[214:217], v[14:17]
	v_mfma_f32_16x16x32_bf16 v[26:29], v[130:133], v[222:225], v[26:29]
	v_mfma_f32_16x16x32_bf16 v[10:13], v[138:141], v[222:225], v[10:13]
	s_setprio 0
	s_setprio 1
	v_mfma_f32_16x16x32_bf16 v[62:65], v[142:145], v[162:165], v[62:65]
	v_mfma_f32_16x16x32_bf16 v[58:61], v[150:153], v[162:165], v[58:61]
	v_mfma_f32_16x16x32_bf16 v[54:57], v[142:145], v[170:173], v[54:57]
	v_mfma_f32_16x16x32_bf16 v[46:49], v[150:153], v[170:173], v[46:49]
	v_mfma_f32_16x16x32_bf16 v[38:41], v[142:145], v[210:213], v[38:41]
	v_mfma_f32_16x16x32_bf16 v[22:25], v[150:153], v[210:213], v[22:25]
	v_mfma_f32_16x16x32_bf16 v[6:9], v[142:145], v[218:221], v[6:9]
	v_mfma_f32_16x16x32_bf16 v[2:5], v[150:153], v[218:221], v[2:5]
	v_mfma_f32_16x16x32_bf16 v[62:65], v[146:149], v[166:169], v[62:65]
	v_mfma_f32_16x16x32_bf16 v[58:61], v[154:157], v[166:169], v[58:61]
	v_mfma_f32_16x16x32_bf16 v[54:57], v[146:149], v[174:177], v[54:57]
	v_mfma_f32_16x16x32_bf16 v[46:49], v[154:157], v[174:177], v[46:49]
	v_mfma_f32_16x16x32_bf16 v[38:41], v[146:149], v[214:217], v[38:41]
	v_mfma_f32_16x16x32_bf16 v[22:25], v[154:157], v[214:217], v[22:25]
	v_mfma_f32_16x16x32_bf16 v[6:9], v[146:149], v[222:225], v[6:9]
	v_mfma_f32_16x16x32_bf16 v[2:5], v[154:157], v[222:225], v[2:5]
	s_setprio 0
	s_barrier
	s_add_i32 s35, s35, 2
	s_add_u32 s18, s18, 0x100
	s_addc_u32 s19, s19, 0
	s_cmp_gt_u32 s35, 13
	s_mov_b64 s[44:45], s[14:15]

; #define PG8_STAGE(bufoff, gbase, voff) do { _Pragma("unroll") for (int _i = 0; _i < 2; ++_i) \
;         __builtin_amdgcn_global_load_lds((const unsigned*)((const char*)(gbase) + (voff)[_i]), (PG8_LAS unsigned*)(lds + (bufoff) + ldsw + _i * 8192), 16, 0, 0); } while (0)
; #define PG8_LDA(dst, b, h) do { _Pragma("unroll") for (int m = 0; m < 4; ++m) _Pragma("unroll") for (int k = 0; k < 2; ++k) dst[m][k] = *(const PG8_LAS bf16x8*)(lds + PG8_SA(b, h) + aoff + m * 2048 + k * 1024); } while (0)
; #define PG8_LDB(dst, b, h) do { _Pragma("unroll") for (int n = 0; n < 2; ++n) _Pragma("unroll") for (int k = 0; k < 2; ++k) dst[n][k] = *(const PG8_LAS bf16x8*)(lds + PG8_SB(b, h) + boff + n * 2048 + k * 1024); } while (0)
; #define PG8_WAIT_V(n) asm volatile("s_waitcnt vmcnt(" #n ")" ::: "memory")
; #define PG8_WAIT_L(n) asm volatile("s_waitcnt lgkmcnt(" #n ")" ::: "memory")
; #define PG8_BAR __builtin_amdgcn_s_barrier()
; template <class Epi, class Sched, bool ALIGN_EPI = false, bool SP2 = false>
; __device__ __forceinline__ void gemm_phase(PG8_LAS unsigned char* lds, const Gemm g, const Sched& S, const Epi& E) {
;     ...
;             const bool last = (t == nt - 2);
;             const char* a1 = cA + (size_t)(t + 1) * kstep;
;             const char* a2 = last ? nA : cA + (size_t)(t + 2) * kstep; const char* b2 = last ? nB : cB + (size_t)(t + 2) * kstep;
;             const char* a3 = a2 + kstep; const char* b3 = b2 + kstep;
;             if (last && has_next) S.a_ready(nxt);
;             if constexpr (SP2) {
;             PG8_LDB(B0, 0, 0); PG8_LDB(B1, 0, 1); PG8_SCHED; PG8_LDA(At, 0, 0); PG8_STAGE(PG8_SA(1, 1), a1 + hstepA, voffA);
;             PG8_WAIT_V(8); PG8_WAIT_L(0); PG8_BAR; PG8_MMA(0, 0, At, B0); PG8_MMA(0, 1, At, B1); PG8_BAR; PG8_SCHED;
;             PG8_LDA(At, 0, 1); PG8_STAGE(PG8_SB(0, 0), b2, voffB); PG8_STAGE(PG8_SB(0, 1), b2 + hstepB, voffB); PG8_STAGE(PG8_SA(0, 0), a2, voffA);
;             PG8_WAIT_V(8); PG8_WAIT_L(0); PG8_BAR; PG8_MMA(1, 0, At, B0); PG8_MMA(1, 1, At, B1); PG8_BAR; PG8_SCHED;
;     ...
; #pragma unroll
;         for (int a = 0; a < 2; ++a)
; #pragma unroll
;             for (int b = 0; b < 2; ++b)
; #pragma unroll
;                 for (int m = 0; m < 4; ++m)
; #pragma unroll
;                     for (int n = 0; n < 2; ++n) acc[a][b][m][n] = (f32x4){0.f, 0.f, 0.f, 0.f};
;         cur = nxt; cA = nA; cB = nB; ++ui;
.LBB0_1936:
	s_add_u32 s4, s42, 0x100
	s_addc_u32 s5, s43, 0
	s_mov_b32 s35, -2
	ds_read_b128 v[130:133], v189
	ds_read_b128 v[134:137], v189 offset:1024
	ds_read_b128 v[138:141], v189 offset:2048
	ds_read_b128 v[142:145], v189 offset:3072
	ds_read_b128 v[168:171], v190
	ds_read_b128 v[194:197], v190 offset:1024
	ds_read_b128 v[198:201], v190 offset:2048
	ds_read_b128 v[202:205], v190 offset:3072
	s_add_u32 s42, s40, 0x100
	s_addc_u32 s43, s41, 0
	s_cmp_eq_u32 s35, 40
	s_cselect_b32 s47, s11, s43
	s_cselect_b32 s46, s10, s42
	s_cselect_b32 s45, s37, s5
	s_cselect_b32 s44, s36, s4
	v_lshl_add_u64 v[238:239], s[40:41], 0, v[160:161]
	s_add_i32 m0, s48, 0xc000
	ds_read_b128 v[206:209], v191
	ds_read_b128 v[210:213], v191 offset:1024
	ds_read_b128 v[214:217], v191 offset:2048
	ds_read_b128 v[218:221], v191 offset:3072
	ds_read_b128 v[222:225], v191 offset:4096
	ds_read_b128 v[226:229], v191 offset:5120
	ds_read_b128 v[230:233], v191 offset:6144
	ds_read_b128 v[234:237], v191 offset:7168
	global_load_lds_dwordx4 v[238:239], off
	v_lshl_add_u64 v[238:239], s[40:41], 0, v[162:163]
	s_add_i32 m0, s48, 0xe000
	s_nop 0
	global_load_lds_dwordx4 v[238:239], off
	s_waitcnt vmcnt(8)
	s_waitcnt lgkmcnt(0)
	s_barrier
	s_setprio 1
	s_waitcnt lgkmcnt(0)
	v_mfma_f32_16x16x32_bf16 v[126:129], v[130:133], v[206:209], 0
	v_mfma_f32_16x16x32_bf16 v[122:125], v[138:141], v[206:209], 0
	v_mfma_f32_16x16x32_bf16 v[110:113], v[130:133], v[214:217], 0
	v_mfma_f32_16x16x32_bf16 v[106:109], v[138:141], v[214:217], 0
	v_mfma_f32_16x16x32_bf16 v[94:97], v[130:133], v[222:225], 0
	v_mfma_f32_16x16x32_bf16 v[90:93], v[138:141], v[222:225], 0
	v_mfma_f32_16x16x32_bf16 v[78:81], v[130:133], v[230:233], 0
	v_mfma_f32_16x16x32_bf16 v[74:77], v[138:141], v[230:233], 0
	v_mfma_f32_16x16x32_bf16 v[126:129], v[134:137], v[210:213], v[126:129]
	v_mfma_f32_16x16x32_bf16 v[122:125], v[142:145], v[210:213], v[122:125]
	v_mfma_f32_16x16x32_bf16 v[110:113], v[134:137], v[218:221], v[110:113]
	v_mfma_f32_16x16x32_bf16 v[106:109], v[142:145], v[218:221], v[106:109]
	v_mfma_f32_16x16x32_bf16 v[94:97], v[134:137], v[226:229], v[94:97]
	v_mfma_f32_16x16x32_bf16 v[90:93], v[142:145], v[226:229], v[90:93]
	v_mfma_f32_16x16x32_bf16 v[78:81], v[134:137], v[234:237], v[78:81]
	v_mfma_f32_16x16x32_bf16 v[74:77], v[142:145], v[234:237], v[74:77]
	s_setprio 0
	s_setprio 1
	v_mfma_f32_16x16x32_bf16 v[118:121], v[168:171], v[206:209], 0
	v_mfma_f32_16x16x32_bf16 v[114:117], v[198:201], v[206:209], 0
	v_mfma_f32_16x16x32_bf16 v[102:105], v[168:171], v[214:217], 0
	v_mfma_f32_16x16x32_bf16 v[98:101], v[198:201], v[214:217], 0
	v_mfma_f32_16x16x32_bf16 v[86:89], v[168:171], v[222:225], 0
	v_mfma_f32_16x16x32_bf16 v[82:85], v[198:201], v[222:225], 0
	v_mfma_f32_16x16x32_bf16 v[70:73], v[168:171], v[230:233], 0
	v_mfma_f32_16x16x32_bf16 v[66:69], v[198:201], v[230:233], 0
	v_mfma_f32_16x16x32_bf16 v[118:121], v[194:197], v[210:213], v[118:121]
	v_mfma_f32_16x16x32_bf16 v[114:117], v[202:205], v[210:213], v[114:117]
	v_mfma_f32_16x16x32_bf16 v[102:105], v[194:197], v[218:221], v[102:105]
	v_mfma_f32_16x16x32_bf16 v[98:101], v[202:205], v[218:221], v[98:101]
	v_mfma_f32_16x16x32_bf16 v[86:89], v[194:197], v[226:229], v[86:89]
	v_mfma_f32_16x16x32_bf16 v[82:85], v[202:205], v[226:229], v[82:85]
	v_mfma_f32_16x16x32_bf16 v[70:73], v[194:197], v[234:237], v[70:73]
	v_mfma_f32_16x16x32_bf16 v[66:69], v[202:205], v[234:237], v[66:69]
	s_setprio 0
	s_barrier
	s_add_i32 s0, s66, s39
	v_lshl_add_u64 v[238:239], s[44:45], 0, v[146:147]
	s_mov_b32 m0, s0
	ds_read_b128 v[206:209], v191 offset:16384
	ds_read_b128 v[210:213], v191 offset:17408
	ds_read_b128 v[214:217], v191 offset:18432
	ds_read_b128 v[218:221], v191 offset:19456
	ds_read_b128 v[222:225], v191 offset:20480
	ds_read_b128 v[226:229], v191 offset:21504
	ds_read_b128 v[230:233], v191 offset:22528
	ds_read_b128 v[234:237], v191 offset:23552
	global_load_lds_dwordx4 v[238:239], off
	s_add_i32 m0, s0, 0x2000
	s_add_u32 s0, s44, 0xb0000
	v_lshl_add_u64 v[240:241], s[44:45], 0, v[152:153]
	s_addc_u32 s1, s45, 0
	s_add_i32 s2, s67, s39
	global_load_lds_dwordx4 v[240:241], off
	v_lshl_add_u64 v[242:243], s[0:1], 0, v[146:147]
	s_mov_b32 m0, s2
	v_lshl_add_u64 v[244:245], s[46:47], 0, v[150:151]
	global_load_lds_dwordx4 v[242:243], off
	v_lshl_add_u64 v[242:243], s[0:1], 0, v[152:153]
	s_add_i32 m0, s2, 0x2000
	s_nop 0
	global_load_lds_dwordx4 v[242:243], off
	v_lshl_add_u64 v[242:243], s[46:47], 0, v[148:149]
	s_mov_b32 m0, s48
	s_nop 0
	global_load_lds_dwordx4 v[242:243], off
	s_mov_b32 m0, s49
	s_nop 0
	global_load_lds_dwordx4 v[244:245], off
	s_waitcnt vmcnt(8)
	s_waitcnt lgkmcnt(0)
	s_barrier
; #define PG8_STAGE(bufoff, gbase, voff) do { _Pragma("unroll") for (int _i = 0; _i < 2; ++_i) \
;         __builtin_amdgcn_global_load_lds((const unsigned*)((const char*)(gbase) + (voff)[_i]), (PG8_LAS unsigned*)(lds + (bufoff) + ldsw + _i * 8192), 16, 0, 0); } while (0)
; #define PG8_LDA(dst, b, h) do { _Pragma("unroll") for (int m = 0; m < 4; ++m) _Pragma("unroll") for (int k = 0; k < 2; ++k) dst[m][k] = *(const PG8_LAS bf16x8*)(lds + PG8_SA(b, h) + aoff + m * 2048 + k * 1024); } while (0)
; #define PG8_LDB(dst, b, h) do { _Pragma("unroll") for (int n = 0; n < 2; ++n) _Pragma("unroll") for (int k = 0; k < 2; ++k) dst[n][k] = *(const PG8_LAS bf16x8*)(lds + PG8_SB(b, h) + boff + n * 2048 + k * 1024); } while (0)
; #define PG8_MMA(ai, bj, At, Bt) do { __builtin_amdgcn_s_setprio(1); _Pragma("unroll") for (int m = 0; m < 4; ++m) _Pragma("unroll") for (int n = 0; n < 2; ++n) _Pragma("unroll") for (int k = 0; k < 2; ++k) \
;         acc[ai][bj][m][n] = __builtin_amdgcn_mfma_f32_16x16x32_bf16(Bt[n][k], At[m][k], acc[ai][bj][m][n], 0, 0, 0); __builtin_amdgcn_s_setprio(0); } while (0)
; #define PG8_WAIT_V(n) asm volatile("s_waitcnt vmcnt(" #n ")" ::: "memory")
; #define PG8_WAIT_L(n) asm volatile("s_waitcnt lgkmcnt(" #n ")" ::: "memory")
; #define PG8_BAR __builtin_amdgcn_s_barrier()
; template <class Epi, class Sched, bool ALIGN_EPI = false, bool SP2 = false>
; __device__ __forceinline__ void gemm_phase(PG8_LAS unsigned char* lds, const Gemm g, const Sched& S, const Epi& E) {
;     ...
;             PG8_WAIT_V(8); PG8_WAIT_L(0); PG8_BAR; PG8_MMA(0, 0, At, B0); PG8_MMA(0, 1, At, B1); PG8_BAR; PG8_SCHED;
;             PG8_LDA(At, 0, 1); PG8_STAGE(PG8_SB(0, 0), b2, voffB); PG8_STAGE(PG8_SB(0, 1), b2 + hstepB, voffB); PG8_STAGE(PG8_SA(0, 0), a2, voffA);
;             PG8_WAIT_V(8); PG8_WAIT_L(0); PG8_BAR; PG8_MMA(1, 0, At, B0); PG8_MMA(1, 1, At, B1); PG8_BAR; PG8_SCHED;
;             PG8_LDB(B0, 1, 0); PG8_LDB(B1, 1, 1); PG8_SCHED; PG8_LDA(At, 1, 0); PG8_STAGE(PG8_SA(0, 1), a2 + hstepA, voffA);
;             PG8_WAIT_V(8); PG8_WAIT_L(0); PG8_BAR; PG8_MMA(0, 0, At, B0); PG8_MMA(0, 1, At, B1); PG8_BAR; PG8_SCHED;
;             PG8_LDA(At, 1, 1); PG8_STAGE(PG8_SB(1, 0), b3, voffB); PG8_STAGE(PG8_SB(1, 1), b3 + hstepB, voffB); PG8_STAGE(PG8_SA(1, 0), a3, voffA);
;             PG8_WAIT_V(8); PG8_WAIT_L(0); PG8_BAR; PG8_MMA(1, 0, At, B0); PG8_MMA(1, 1, At, B1); PG8_BAR; PG8_SCHED;
	s_setprio 1
	s_waitcnt lgkmcnt(0)
	v_mfma_f32_16x16x32_bf16 v[62:65], v[130:133], v[206:209], 0
	v_mfma_f32_16x16x32_bf16 v[58:61], v[138:141], v[206:209], 0
	v_mfma_f32_16x16x32_bf16 v[46:49], v[130:133], v[214:217], 0
	v_mfma_f32_16x16x32_bf16 v[42:45], v[138:141], v[214:217], 0
	v_mfma_f32_16x16x32_bf16 v[30:33], v[130:133], v[222:225], 0
	v_mfma_f32_16x16x32_bf16 v[26:29], v[138:141], v[222:225], 0
	v_mfma_f32_16x16x32_bf16 v[14:17], v[130:133], v[230:233], 0
	v_mfma_f32_16x16x32_bf16 v[10:13], v[138:141], v[230:233], 0
	v_mfma_f32_16x16x32_bf16 v[62:65], v[134:137], v[210:213], v[62:65]
	v_mfma_f32_16x16x32_bf16 v[58:61], v[142:145], v[210:213], v[58:61]
	v_mfma_f32_16x16x32_bf16 v[46:49], v[134:137], v[218:221], v[46:49]
	v_mfma_f32_16x16x32_bf16 v[42:45], v[142:145], v[218:221], v[42:45]
	v_mfma_f32_16x16x32_bf16 v[30:33], v[134:137], v[226:229], v[30:33]
	v_mfma_f32_16x16x32_bf16 v[26:29], v[142:145], v[226:229], v[26:29]
	v_mfma_f32_16x16x32_bf16 v[14:17], v[134:137], v[234:237], v[14:17]
	v_mfma_f32_16x16x32_bf16 v[10:13], v[142:145], v[234:237], v[10:13]
	s_setprio 0
	s_setprio 1
	v_mfma_f32_16x16x32_bf16 v[54:57], v[168:171], v[206:209], 0
	v_mfma_f32_16x16x32_bf16 v[50:53], v[198:201], v[206:209], 0
	v_mfma_f32_16x16x32_bf16 v[38:41], v[168:171], v[214:217], 0
	v_mfma_f32_16x16x32_bf16 v[34:37], v[198:201], v[214:217], 0
	v_mfma_f32_16x16x32_bf16 v[22:25], v[168:171], v[222:225], 0
	v_mfma_f32_16x16x32_bf16 v[18:21], v[198:201], v[222:225], 0
	v_mfma_f32_16x16x32_bf16 v[6:9], v[168:171], v[230:233], 0
	v_mfma_f32_16x16x32_bf16 v[2:5], v[198:201], v[230:233], 0
	v_mfma_f32_16x16x32_bf16 v[54:57], v[194:197], v[210:213], v[54:57]
	v_mfma_f32_16x16x32_bf16 v[50:53], v[202:205], v[210:213], v[50:53]
	v_mfma_f32_16x16x32_bf16 v[38:41], v[194:197], v[218:221], v[38:41]
	v_mfma_f32_16x16x32_bf16 v[34:37], v[202:205], v[218:221], v[34:37]
	v_mfma_f32_16x16x32_bf16 v[22:25], v[194:197], v[226:229], v[22:25]
	v_mfma_f32_16x16x32_bf16 v[18:21], v[202:205], v[226:229], v[18:21]
	v_mfma_f32_16x16x32_bf16 v[6:9], v[194:197], v[234:237], v[6:9]
	v_mfma_f32_16x16x32_bf16 v[2:5], v[202:205], v[234:237], v[2:5]
	s_setprio 0
	s_barrier
	ds_read_b128 v[130:133], v192
	ds_read_b128 v[134:137], v192 offset:1024
	ds_read_b128 v[138:141], v192 offset:2048
	ds_read_b128 v[142:145], v192 offset:3072
	ds_read_b128 v[168:171], v193
	ds_read_b128 v[194:197], v193 offset:1024
	ds_read_b128 v[198:201], v193 offset:2048
	ds_read_b128 v[202:205], v193 offset:3072
	s_add_u32 s0, s46, 0xb0000
	s_addc_u32 s1, s47, 0
	s_mov_b32 m0, s50
	v_lshl_add_u64 v[246:247], s[0:1], 0, v[148:149]
	ds_read_b128 v[206:209], v191 offset:32768
	ds_read_b128 v[210:213], v191 offset:33792
	ds_read_b128 v[214:217], v191 offset:34816
	ds_read_b128 v[218:221], v191 offset:35840
	ds_read_b128 v[222:225], v191 offset:36864
	ds_read_b128 v[226:229], v191 offset:37888
	ds_read_b128 v[230:233], v191 offset:38912
	ds_read_b128 v[234:237], v191 offset:39936
	global_load_lds_dwordx4 v[246:247], off
	v_lshl_add_u64 v[246:247], s[0:1], 0, v[150:151]
	s_mov_b32 m0, s51
	s_nop 0
	global_load_lds_dwordx4 v[246:247], off
	s_waitcnt vmcnt(8)
	s_waitcnt lgkmcnt(0)
	s_barrier
	s_setprio 1
	s_waitcnt lgkmcnt(0)
	v_mfma_f32_16x16x32_bf16 v[126:129], v[130:133], v[206:209], v[126:129]
	v_mfma_f32_16x16x32_bf16 v[122:125], v[138:141], v[206:209], v[122:125]
	v_mfma_f32_16x16x32_bf16 v[110:113], v[130:133], v[214:217], v[110:113]
	v_mfma_f32_16x16x32_bf16 v[106:109], v[138:141], v[214:217], v[106:109]
	v_mfma_f32_16x16x32_bf16 v[94:97], v[130:133], v[222:225], v[94:97]
	v_mfma_f32_16x16x32_bf16 v[90:93], v[138:141], v[222:225], v[90:93]
	v_mfma_f32_16x16x32_bf16 v[78:81], v[130:133], v[230:233], v[78:81]
	v_mfma_f32_16x16x32_bf16 v[74:77], v[138:141], v[230:233], v[74:77]
	v_mfma_f32_16x16x32_bf16 v[126:129], v[134:137], v[210:213], v[126:129]
	v_mfma_f32_16x16x32_bf16 v[122:125], v[142:145], v[210:213], v[122:125]
	v_mfma_f32_16x16x32_bf16 v[110:113], v[134:137], v[218:221], v[110:113]
	v_mfma_f32_16x16x32_bf16 v[106:109], v[142:145], v[218:221], v[106:109]
	v_mfma_f32_16x16x32_bf16 v[94:97], v[134:137], v[226:229], v[94:97]
	v_mfma_f32_16x16x32_bf16 v[90:93], v[142:145], v[226:229], v[90:93]
	v_mfma_f32_16x16x32_bf16 v[78:81], v[134:137], v[234:237], v[78:81]
	v_mfma_f32_16x16x32_bf16 v[74:77], v[142:145], v[234:237], v[74:77]
	s_setprio 0
	s_setprio 1
	v_mfma_f32_16x16x32_bf16 v[118:121], v[168:171], v[206:209], v[118:121]
	v_mfma_f32_16x16x32_bf16 v[114:117], v[198:201], v[206:209], v[114:117]
	v_mfma_f32_16x16x32_bf16 v[102:105], v[168:171], v[214:217], v[102:105]
	v_mfma_f32_16x16x32_bf16 v[98:101], v[198:201], v[214:217], v[98:101]
	v_mfma_f32_16x16x32_bf16 v[86:89], v[168:171], v[222:225], v[86:89]
	v_mfma_f32_16x16x32_bf16 v[82:85], v[198:201], v[222:225], v[82:85]
	v_mfma_f32_16x16x32_bf16 v[70:73], v[168:171], v[230:233], v[70:73]
	v_mfma_f32_16x16x32_bf16 v[66:69], v[198:201], v[230:233], v[66:69]
	v_mfma_f32_16x16x32_bf16 v[118:121], v[194:197], v[210:213], v[118:121]
	v_mfma_f32_16x16x32_bf16 v[114:117], v[202:205], v[210:213], v[114:117]
	v_mfma_f32_16x16x32_bf16 v[102:105], v[194:197], v[218:221], v[102:105]
	v_mfma_f32_16x16x32_bf16 v[98:101], v[202:205], v[218:221], v[98:101]
	v_mfma_f32_16x16x32_bf16 v[86:89], v[194:197], v[226:229], v[86:89]
	v_mfma_f32_16x16x32_bf16 v[82:85], v[202:205], v[226:229], v[82:85]
	v_mfma_f32_16x16x32_bf16 v[70:73], v[194:197], v[234:237], v[70:73]
	v_mfma_f32_16x16x32_bf16 v[66:69], v[202:205], v[234:237], v[66:69]
	s_setprio 0
	s_barrier
; #define PG8_STAGE(bufoff, gbase, voff) do { _Pragma("unroll") for (int _i = 0; _i < 2; ++_i) \
;         __builtin_amdgcn_global_load_lds((const unsigned*)((const char*)(gbase) + (voff)[_i]), (PG8_LAS unsigned*)(lds + (bufoff) + ldsw + _i * 8192), 16, 0, 0); } while (0)
; #define PG8_LDA(dst, b, h) do { _Pragma("unroll") for (int m = 0; m < 4; ++m) _Pragma("unroll") for (int k = 0; k < 2; ++k) dst[m][k] = *(const PG8_LAS bf16x8*)(lds + PG8_SA(b, h) + aoff + m * 2048 + k * 1024); } while (0)
; #define PG8_MMA(ai, bj, At, Bt) do { __builtin_amdgcn_s_setprio(1); _Pragma("unroll") for (int m = 0; m < 4; ++m) _Pragma("unroll") for (int n = 0; n < 2; ++n) _Pragma("unroll") for (int k = 0; k < 2; ++k) \
;         acc[ai][bj][m][n] = __builtin_amdgcn_mfma_f32_16x16x32_bf16(Bt[n][k], At[m][k], acc[ai][bj][m][n], 0, 0, 0); __builtin_amdgcn_s_setprio(0); } while (0)
; #define PG8_WAIT_V(n) asm volatile("s_waitcnt vmcnt(" #n ")" ::: "memory")
; #define PG8_WAIT_L(n) asm volatile("s_waitcnt lgkmcnt(" #n ")" ::: "memory")
; #define PG8_BAR __builtin_amdgcn_s_barrier()
; #define PG8_SCHED __builtin_amdgcn_sched_barrier(0)
; template <class Epi, class Sched, bool ALIGN_EPI = false, bool SP2 = false>
; __device__ __forceinline__ void gemm_phase(PG8_LAS unsigned char* lds, const Gemm g, const Sched& S, const Epi& E) {
;     ...
;         for (int t = 0; t < nt; t += 2) {
;             const bool last = (t == nt - 2);
;             const char* a1 = cA + (size_t)(t + 1) * kstep;
;             const char* a2 = last ? nA : cA + (size_t)(t + 2) * kstep; const char* b2 = last ? nB : cB + (size_t)(t + 2) * kstep;
;             const char* a3 = a2 + kstep; const char* b3 = b2 + kstep;
;     ...
;             PG8_LDA(At, 1, 1); PG8_STAGE(PG8_SB(1, 0), b3, voffB); PG8_STAGE(PG8_SB(1, 1), b3 + hstepB, voffB); PG8_STAGE(PG8_SA(1, 0), a3, voffA);
;             PG8_WAIT_V(8); PG8_WAIT_L(0); PG8_BAR; PG8_MMA(1, 0, At, B0); PG8_MMA(1, 1, At, B1); PG8_BAR; PG8_SCHED;
	s_add_i32 s0, s68, s39
	v_lshl_add_u64 v[238:239], v[238:239], 0, s[12:13]
	s_mov_b32 m0, s0
	ds_read_b128 v[206:209], v191 offset:49152
	ds_read_b128 v[210:213], v191 offset:50176
	ds_read_b128 v[214:217], v191 offset:51200
	ds_read_b128 v[218:221], v191 offset:52224
	ds_read_b128 v[222:225], v191 offset:53248
	ds_read_b128 v[226:229], v191 offset:54272
	ds_read_b128 v[230:233], v191 offset:55296
	ds_read_b128 v[234:237], v191 offset:56320
	global_load_lds_dwordx4 v[238:239], off
	s_add_i32 m0, s0, 0x2000
	s_add_u32 s0, s44, 0xb0080
	v_lshl_add_u64 v[238:239], v[240:241], 0, s[12:13]
	s_addc_u32 s1, s45, 0
	s_add_i32 s2, s69, s39
	global_load_lds_dwordx4 v[238:239], off
	v_lshl_add_u64 v[238:239], s[0:1], 0, v[146:147]
	s_mov_b32 m0, s2
	s_nop 0
	global_load_lds_dwordx4 v[238:239], off
	v_lshl_add_u64 v[238:239], s[0:1], 0, v[152:153]
	s_add_i32 m0, s2, 0x2000
	s_nop 0
	global_load_lds_dwordx4 v[238:239], off
	v_lshl_add_u64 v[238:239], v[242:243], 0, s[12:13]
	s_mov_b32 m0, s62
	s_nop 0
	global_load_lds_dwordx4 v[238:239], off
	v_lshl_add_u64 v[238:239], v[244:245], 0, s[12:13]
	s_mov_b32 m0, s63
	s_nop 0
	global_load_lds_dwordx4 v[238:239], off
	s_waitcnt vmcnt(8)
	s_waitcnt lgkmcnt(0)
	s_barrier
	s_setprio 1
	s_waitcnt lgkmcnt(0)
	v_mfma_f32_16x16x32_bf16 v[62:65], v[130:133], v[206:209], v[62:65]
	v_mfma_f32_16x16x32_bf16 v[58:61], v[138:141], v[206:209], v[58:61]
	v_mfma_f32_16x16x32_bf16 v[46:49], v[130:133], v[214:217], v[46:49]
	v_mfma_f32_16x16x32_bf16 v[42:45], v[138:141], v[214:217], v[42:45]
	v_mfma_f32_16x16x32_bf16 v[30:33], v[130:133], v[222:225], v[30:33]
	v_mfma_f32_16x16x32_bf16 v[26:29], v[138:141], v[222:225], v[26:29]
	v_mfma_f32_16x16x32_bf16 v[14:17], v[130:133], v[230:233], v[14:17]
	v_mfma_f32_16x16x32_bf16 v[10:13], v[138:141], v[230:233], v[10:13]
	v_mfma_f32_16x16x32_bf16 v[62:65], v[134:137], v[210:213], v[62:65]
	v_mfma_f32_16x16x32_bf16 v[58:61], v[142:145], v[210:213], v[58:61]
	v_mfma_f32_16x16x32_bf16 v[46:49], v[134:137], v[218:221], v[46:49]
	v_mfma_f32_16x16x32_bf16 v[42:45], v[142:145], v[218:221], v[42:45]
	v_mfma_f32_16x16x32_bf16 v[30:33], v[134:137], v[226:229], v[30:33]
	v_mfma_f32_16x16x32_bf16 v[26:29], v[142:145], v[226:229], v[26:29]
	v_mfma_f32_16x16x32_bf16 v[14:17], v[134:137], v[234:237], v[14:17]
	v_mfma_f32_16x16x32_bf16 v[10:13], v[142:145], v[234:237], v[10:13]
	s_setprio 0
	s_setprio 1
	v_mfma_f32_16x16x32_bf16 v[54:57], v[168:171], v[206:209], v[54:57]
	v_mfma_f32_16x16x32_bf16 v[50:53], v[198:201], v[206:209], v[50:53]
	v_mfma_f32_16x16x32_bf16 v[38:41], v[168:171], v[214:217], v[38:41]
	v_mfma_f32_16x16x32_bf16 v[34:37], v[198:201], v[214:217], v[34:37]
	v_mfma_f32_16x16x32_bf16 v[22:25], v[168:171], v[222:225], v[22:25]
	v_mfma_f32_16x16x32_bf16 v[18:21], v[198:201], v[222:225], v[18:21]
	v_mfma_f32_16x16x32_bf16 v[6:9], v[168:171], v[230:233], v[6:9]
	v_mfma_f32_16x16x32_bf16 v[2:5], v[198:201], v[230:233], v[2:5]
	v_mfma_f32_16x16x32_bf16 v[54:57], v[194:197], v[210:213], v[54:57]
	v_mfma_f32_16x16x32_bf16 v[50:53], v[202:205], v[210:213], v[50:53]
	v_mfma_f32_16x16x32_bf16 v[38:41], v[194:197], v[218:221], v[38:41]
	v_mfma_f32_16x16x32_bf16 v[34:37], v[202:205], v[218:221], v[34:37]
	v_mfma_f32_16x16x32_bf16 v[22:25], v[194:197], v[226:229], v[22:25]
	v_mfma_f32_16x16x32_bf16 v[18:21], v[202:205], v[226:229], v[18:21]
	v_mfma_f32_16x16x32_bf16 v[6:9], v[194:197], v[234:237], v[6:9]
	v_mfma_f32_16x16x32_bf16 v[2:5], v[202:205], v[234:237], v[2:5]
	s_setprio 0
	s_barrier
	s_add_i32 s35, s35, 2
	s_add_u32 s4, s4, 0x100
	s_addc_u32 s5, s5, 0
	s_cmp_gt_u32 s35, 41
	s_mov_b64 s[40:41], s[42:43]
